# stagger + zero64 + inverted setprio: loader segments at prio 1, MFMA blocks at prio 0
# baseline (speedup 1.0000x reference)
; #define PG8_STAGE(bufoff, gbase, voff) do { _Pragma("unroll") for (int _i = 0; _i < 2; ++_i) \
;         __builtin_amdgcn_global_load_lds((const unsigned*)((const char*)(gbase) + (voff)[_i]), (LAS unsigned*)(lds + (bufoff) + ldsw + _i * 8192), 16, 0, 0); } while (0)
; #define PG8_LDA(dst, b, h) do { _Pragma("unroll") for (int m = 0; m < 4; ++m) _Pragma("unroll") for (int k = 0; k < 2; ++k) dst[m][k] = *(const LAS bf16x8*)(lds + PG8_SA(b, h) + aoff + m * 2048 + k * 1024); } while (0)
; #define PG8_LDB(dst, b, h) do { _Pragma("unroll") for (int n = 0; n < 2; ++n) _Pragma("unroll") for (int k = 0; k < 2; ++k) dst[n][k] = *(const LAS bf16x8*)(lds + PG8_SB(b, h) + boff + n * 2048 + k * 1024); } while (0)
; #define PG8_MMA(ai, bj, At, Bt) do { __builtin_amdgcn_s_setprio(1); _Pragma("unroll") for (int m = 0; m < 4; ++m) _Pragma("unroll") for (int n = 0; n < 2; ++n) _Pragma("unroll") for (int k = 0; k < 2; ++k) \
;         acc[ai][bj][m][n] = __builtin_amdgcn_mfma_f32_16x16x32_bf16(Bt[n][k], At[m][k], acc[ai][bj][m][n], 0, 0, 0); __builtin_amdgcn_s_setprio(0); } while (0)
; #define PG8_WAIT_V(n) asm volatile("s_waitcnt vmcnt(" #n ")" ::: "memory")
; #define PG8_WAIT_L(n) asm volatile("s_waitcnt lgkmcnt(" #n ")" ::: "memory")
; #define PG8_BAR __builtin_amdgcn_s_barrier()
; #define PG8_SCHED __builtin_amdgcn_sched_barrier(0)
; template <class Epi, class Sched, bool ALIGN_EPI = true>
; __device__ __forceinline__ void gemm_phase(LAS unsigned char* lds, const Gemm g, const Sched& S, const Epi& E) {
;     ...
;         for (int t = 0; t < nt; t += 2) {
;             const bool last = (t == nt - 2);
;             const char* a1 = cA + (size_t)(t + 1) * kstep;
;             const char* a2 = last ? nA : cA + (size_t)(t + 2) * kstep; const char* b2 = last ? nB : cB + (size_t)(t + 2) * kstep;
;             const char* a3 = a2 + kstep; const char* b3 = b2 + kstep;
;             PG8_LDB(B0, 0, 0); PG8_LDB(B1, 0, 1); PG8_SCHED; PG8_LDA(At, 0, 0); PG8_STAGE(PG8_SA(1, 1), a1 + hstep, voffA);
;             PG8_WAIT_V(8); PG8_WAIT_L(0); PG8_BAR; PG8_MMA(0, 0, At, B0); PG8_MMA(0, 1, At, B1); PG8_BAR; PG8_SCHED;
;             PG8_LDA(At, 0, 1); PG8_STAGE(PG8_SB(0, 0), b2, voffB); PG8_STAGE(PG8_SB(0, 1), b2 + hstep, voffB); PG8_STAGE(PG8_SA(0, 0), a2, voffA);
.LBB0_195:
	v_add_u32_e32 v136, s78, v169
	ds_read_b128 v[172:175], v136
	ds_read_b128 v[180:183], v136 offset:1024
	ds_read_b128 v[184:187], v136 offset:2048
	ds_read_b128 v[188:191], v136 offset:3072
	v_add_u32_e32 v136, s79, v169
	ds_read_b128 v[192:195], v136
	ds_read_b128 v[196:199], v136 offset:1024
	ds_read_b128 v[204:207], v136 offset:2048
	ds_read_b128 v[208:211], v136 offset:3072
	s_add_u32 s36, s34, 0xfff80080
	s_addc_u32 s37, s35, -1
	s_cmp_eq_u32 s89, 28
	s_cselect_b32 s39, s84, s37
	s_cselect_b32 s38, s85, s36
	s_cselect_b32 s37, s9, s88
	s_cselect_b32 s36, s86, s87
	v_lshl_add_u64 v[164:165], s[34:35], 0, v[160:161]
	s_add_i32 m0, s44, 0xc000
	ds_read_b128 v[212:215], v171
	ds_read_b128 v[216:219], v171 offset:1024
	ds_read_b128 v[220:223], v171 offset:2048
	ds_read_b128 v[224:227], v171 offset:3072
	ds_read_b128 v[228:231], v171 offset:4096
	ds_read_b128 v[232:235], v171 offset:5120
	ds_read_b128 v[236:239], v171 offset:6144
	ds_read_b128 v[240:243], v171 offset:7168
	global_load_lds_dwordx4 v[164:165], off
	v_lshl_add_u64 v[164:165], s[34:35], 0, v[162:163]
	s_add_i32 m0, s44, 0xe000
	s_nop 0
	global_load_lds_dwordx4 v[164:165], off
	s_waitcnt vmcnt(8)
	s_waitcnt lgkmcnt(0)
	s_barrier
	s_setprio 0
	s_waitcnt lgkmcnt(0)
	v_mfma_f32_16x16x32_bf16 v[124:127], v[172:175], v[212:215], v[124:127]
	v_mfma_f32_16x16x32_bf16 v[120:123], v[184:187], v[212:215], v[120:123]
	v_mfma_f32_16x16x32_bf16 v[108:111], v[172:175], v[220:223], v[108:111]
	v_mfma_f32_16x16x32_bf16 v[104:107], v[184:187], v[220:223], v[104:107]
	v_mfma_f32_16x16x32_bf16 v[92:95], v[172:175], v[228:231], v[92:95]
	v_mfma_f32_16x16x32_bf16 v[88:91], v[184:187], v[228:231], v[88:91]
	v_mfma_f32_16x16x32_bf16 v[76:79], v[172:175], v[236:239], v[76:79]
	v_mfma_f32_16x16x32_bf16 v[72:75], v[184:187], v[236:239], v[72:75]
	v_mfma_f32_16x16x32_bf16 v[124:127], v[180:183], v[216:219], v[124:127]
	v_mfma_f32_16x16x32_bf16 v[120:123], v[188:191], v[216:219], v[120:123]
	v_mfma_f32_16x16x32_bf16 v[108:111], v[180:183], v[224:227], v[108:111]
	v_mfma_f32_16x16x32_bf16 v[104:107], v[188:191], v[224:227], v[104:107]
	v_mfma_f32_16x16x32_bf16 v[92:95], v[180:183], v[232:235], v[92:95]
	v_mfma_f32_16x16x32_bf16 v[88:91], v[188:191], v[232:235], v[88:91]
	v_mfma_f32_16x16x32_bf16 v[76:79], v[180:183], v[240:243], v[76:79]
	v_mfma_f32_16x16x32_bf16 v[72:75], v[188:191], v[240:243], v[72:75]
	v_mfma_f32_16x16x32_bf16 v[116:119], v[192:195], v[212:215], v[116:119]
	v_mfma_f32_16x16x32_bf16 v[112:115], v[204:207], v[212:215], v[112:115]
	v_mfma_f32_16x16x32_bf16 v[100:103], v[192:195], v[220:223], v[100:103]
	v_mfma_f32_16x16x32_bf16 v[96:99], v[204:207], v[220:223], v[96:99]
	v_mfma_f32_16x16x32_bf16 v[84:87], v[192:195], v[228:231], v[84:87]
	v_mfma_f32_16x16x32_bf16 v[80:83], v[204:207], v[228:231], v[80:83]
	v_mfma_f32_16x16x32_bf16 v[68:71], v[192:195], v[236:239], v[68:71]
	v_mfma_f32_16x16x32_bf16 v[64:67], v[204:207], v[236:239], v[64:67]
	v_mfma_f32_16x16x32_bf16 v[116:119], v[196:199], v[216:219], v[116:119]
	v_mfma_f32_16x16x32_bf16 v[112:115], v[208:211], v[216:219], v[112:115]
	v_mfma_f32_16x16x32_bf16 v[100:103], v[196:199], v[224:227], v[100:103]
	v_mfma_f32_16x16x32_bf16 v[96:99], v[208:211], v[224:227], v[96:99]
	v_mfma_f32_16x16x32_bf16 v[84:87], v[196:199], v[232:235], v[84:87]
	v_mfma_f32_16x16x32_bf16 v[80:83], v[208:211], v[232:235], v[80:83]
	v_mfma_f32_16x16x32_bf16 v[68:71], v[196:199], v[240:243], v[68:71]
	v_mfma_f32_16x16x32_bf16 v[64:67], v[208:211], v[240:243], v[64:67]
	s_setprio 1
	s_barrier
	s_add_i32 s46, s78, s42
	v_lshl_add_u64 v[164:165], s[36:37], 0, v[130:131]
	s_mov_b32 m0, s46
	ds_read_b128 v[212:215], v171 offset:16384
	ds_read_b128 v[216:219], v171 offset:17408
	ds_read_b128 v[220:223], v171 offset:18432
	ds_read_b128 v[224:227], v171 offset:19456
	ds_read_b128 v[228:231], v171 offset:20480
	ds_read_b128 v[232:235], v171 offset:21504
	ds_read_b128 v[236:239], v171 offset:22528
	ds_read_b128 v[240:243], v171 offset:23552
	global_load_lds_dwordx4 v[164:165], off
	s_add_i32 m0, s46, 0x2000
	s_add_u32 s90, s36, 0x80000
	v_lshl_add_u64 v[176:177], s[36:37], 0, v[134:135]
	s_addc_u32 s91, s37, 0
	s_add_i32 s46, s79, s42
	global_load_lds_dwordx4 v[176:177], off
	v_lshl_add_u64 v[200:201], s[90:91], 0, v[130:131]
	s_mov_b32 m0, s46
	v_lshl_add_u64 v[244:245], s[38:39], 0, v[132:133]
	global_load_lds_dwordx4 v[200:201], off
	v_lshl_add_u64 v[200:201], s[90:91], 0, v[134:135]
	s_add_i32 m0, s46, 0x2000
	s_nop 0
	global_load_lds_dwordx4 v[200:201], off
	v_lshl_add_u64 v[200:201], s[38:39], 0, v[128:129]
	s_mov_b32 m0, s44
	s_nop 0
	global_load_lds_dwordx4 v[200:201], off
	s_mov_b32 m0, s50
	s_nop 0
	global_load_lds_dwordx4 v[244:245], off
	s_waitcnt vmcnt(8)
	s_waitcnt lgkmcnt(0)
	s_barrier
; #define PG8_STAGE(bufoff, gbase, voff) do { _Pragma("unroll") for (int _i = 0; _i < 2; ++_i) \
;         __builtin_amdgcn_global_load_lds((const unsigned*)((const char*)(gbase) + (voff)[_i]), (LAS unsigned*)(lds + (bufoff) + ldsw + _i * 8192), 16, 0, 0); } while (0)
; #define PG8_LDA(dst, b, h) do { _Pragma("unroll") for (int m = 0; m < 4; ++m) _Pragma("unroll") for (int k = 0; k < 2; ++k) dst[m][k] = *(const LAS bf16x8*)(lds + PG8_SA(b, h) + aoff + m * 2048 + k * 1024); } while (0)
; #define PG8_LDB(dst, b, h) do { _Pragma("unroll") for (int n = 0; n < 2; ++n) _Pragma("unroll") for (int k = 0; k < 2; ++k) dst[n][k] = *(const LAS bf16x8*)(lds + PG8_SB(b, h) + boff + n * 2048 + k * 1024); } while (0)
; #define PG8_MMA(ai, bj, At, Bt) do { __builtin_amdgcn_s_setprio(1); _Pragma("unroll") for (int m = 0; m < 4; ++m) _Pragma("unroll") for (int n = 0; n < 2; ++n) _Pragma("unroll") for (int k = 0; k < 2; ++k) \
;         acc[ai][bj][m][n] = __builtin_amdgcn_mfma_f32_16x16x32_bf16(Bt[n][k], At[m][k], acc[ai][bj][m][n], 0, 0, 0); __builtin_amdgcn_s_setprio(0); } while (0)
; #define PG8_WAIT_V(n) asm volatile("s_waitcnt vmcnt(" #n ")" ::: "memory")
; #define PG8_WAIT_L(n) asm volatile("s_waitcnt lgkmcnt(" #n ")" ::: "memory")
; #define PG8_BAR __builtin_amdgcn_s_barrier()
; #define PG8_SCHED __builtin_amdgcn_sched_barrier(0)
; template <class Epi, class Sched, bool ALIGN_EPI = true>
; __device__ __forceinline__ void gemm_phase(LAS unsigned char* lds, const Gemm g, const Sched& S, const Epi& E) {
;     ...
;             PG8_WAIT_V(8); PG8_WAIT_L(0); PG8_BAR; PG8_MMA(1, 0, At, B0); PG8_MMA(1, 1, At, B1); PG8_BAR; PG8_SCHED;
;             PG8_LDB(B0, 1, 0); PG8_LDB(B1, 1, 1); PG8_SCHED; PG8_LDA(At, 1, 0); PG8_STAGE(PG8_SA(0, 1), a2 + hstep, voffA);
;             PG8_WAIT_V(8); PG8_WAIT_L(0); PG8_BAR; PG8_MMA(0, 0, At, B0); PG8_MMA(0, 1, At, B1); PG8_BAR; PG8_SCHED;
	s_setprio 0
	s_waitcnt lgkmcnt(0)
	v_mfma_f32_16x16x32_bf16 v[60:63], v[172:175], v[212:215], v[60:63]
	v_mfma_f32_16x16x32_bf16 v[56:59], v[184:187], v[212:215], v[56:59]
	v_mfma_f32_16x16x32_bf16 v[44:47], v[172:175], v[220:223], v[44:47]
	v_mfma_f32_16x16x32_bf16 v[40:43], v[184:187], v[220:223], v[40:43]
	v_mfma_f32_16x16x32_bf16 v[28:31], v[172:175], v[228:231], v[28:31]
	v_mfma_f32_16x16x32_bf16 v[24:27], v[184:187], v[228:231], v[24:27]
	v_mfma_f32_16x16x32_bf16 v[12:15], v[172:175], v[236:239], v[12:15]
	v_mfma_f32_16x16x32_bf16 v[8:11], v[184:187], v[236:239], v[8:11]
	v_mfma_f32_16x16x32_bf16 v[60:63], v[180:183], v[216:219], v[60:63]
	v_mfma_f32_16x16x32_bf16 v[56:59], v[188:191], v[216:219], v[56:59]
	v_mfma_f32_16x16x32_bf16 v[44:47], v[180:183], v[224:227], v[44:47]
	v_mfma_f32_16x16x32_bf16 v[40:43], v[188:191], v[224:227], v[40:43]
	v_mfma_f32_16x16x32_bf16 v[28:31], v[180:183], v[232:235], v[28:31]
	v_mfma_f32_16x16x32_bf16 v[24:27], v[188:191], v[232:235], v[24:27]
	v_mfma_f32_16x16x32_bf16 v[12:15], v[180:183], v[240:243], v[12:15]
	v_mfma_f32_16x16x32_bf16 v[8:11], v[188:191], v[240:243], v[8:11]
	v_mfma_f32_16x16x32_bf16 v[52:55], v[192:195], v[212:215], v[52:55]
	v_mfma_f32_16x16x32_bf16 v[48:51], v[204:207], v[212:215], v[48:51]
	v_mfma_f32_16x16x32_bf16 v[36:39], v[192:195], v[220:223], v[36:39]
	v_mfma_f32_16x16x32_bf16 v[32:35], v[204:207], v[220:223], v[32:35]
	v_mfma_f32_16x16x32_bf16 v[20:23], v[192:195], v[228:231], v[20:23]
	v_mfma_f32_16x16x32_bf16 v[16:19], v[204:207], v[228:231], v[16:19]
	v_mfma_f32_16x16x32_bf16 v[4:7], v[192:195], v[236:239], v[4:7]
	v_mfma_f32_16x16x32_bf16 v[0:3], v[204:207], v[236:239], v[0:3]
	v_mfma_f32_16x16x32_bf16 v[52:55], v[196:199], v[216:219], v[52:55]
	v_mfma_f32_16x16x32_bf16 v[48:51], v[208:211], v[216:219], v[48:51]
	v_mfma_f32_16x16x32_bf16 v[36:39], v[196:199], v[224:227], v[36:39]
	v_mfma_f32_16x16x32_bf16 v[32:35], v[208:211], v[224:227], v[32:35]
	v_mfma_f32_16x16x32_bf16 v[20:23], v[196:199], v[232:235], v[20:23]
	v_mfma_f32_16x16x32_bf16 v[16:19], v[208:211], v[232:235], v[16:19]
	v_mfma_f32_16x16x32_bf16 v[4:7], v[196:199], v[240:243], v[4:7]
	v_mfma_f32_16x16x32_bf16 v[0:3], v[208:211], v[240:243], v[0:3]
	s_setprio 1
	s_barrier
	s_add_i32 s46, 0, 0x18000
	v_add_u32_e32 v136, s46, v169
	s_add_i32 s47, 0, 0x1c000
	ds_read_b128 v[172:175], v136
	ds_read_b128 v[180:183], v136 offset:1024
	ds_read_b128 v[184:187], v136 offset:2048
	ds_read_b128 v[188:191], v136 offset:3072
	v_add_u32_e32 v136, s47, v169
	ds_read_b128 v[192:195], v136
	ds_read_b128 v[196:199], v136 offset:1024
	ds_read_b128 v[204:207], v136 offset:2048
	ds_read_b128 v[208:211], v136 offset:3072
	s_add_u32 s38, s38, 0x80000
	s_addc_u32 s39, s39, 0
	s_mov_b32 m0, s52
	v_lshl_add_u64 v[246:247], s[38:39], 0, v[128:129]
	ds_read_b128 v[212:215], v171 offset:32768
	ds_read_b128 v[216:219], v171 offset:33792
	ds_read_b128 v[220:223], v171 offset:34816
	ds_read_b128 v[224:227], v171 offset:35840
	ds_read_b128 v[228:231], v171 offset:36864
	ds_read_b128 v[232:235], v171 offset:37888
	ds_read_b128 v[236:239], v171 offset:38912
	ds_read_b128 v[240:243], v171 offset:39936
	global_load_lds_dwordx4 v[246:247], off
	v_lshl_add_u64 v[246:247], s[38:39], 0, v[132:133]
	s_mov_b32 m0, s53
	s_nop 0
	global_load_lds_dwordx4 v[246:247], off
	s_waitcnt vmcnt(8)
	s_waitcnt lgkmcnt(0)
	s_barrier
	s_setprio 0
	s_waitcnt lgkmcnt(0)
	v_mfma_f32_16x16x32_bf16 v[124:127], v[172:175], v[212:215], v[124:127]
	v_mfma_f32_16x16x32_bf16 v[120:123], v[184:187], v[212:215], v[120:123]
	v_mfma_f32_16x16x32_bf16 v[108:111], v[172:175], v[220:223], v[108:111]
	v_mfma_f32_16x16x32_bf16 v[104:107], v[184:187], v[220:223], v[104:107]
	v_mfma_f32_16x16x32_bf16 v[92:95], v[172:175], v[228:231], v[92:95]
	v_mfma_f32_16x16x32_bf16 v[88:91], v[184:187], v[228:231], v[88:91]
	v_mfma_f32_16x16x32_bf16 v[76:79], v[172:175], v[236:239], v[76:79]
	v_mfma_f32_16x16x32_bf16 v[72:75], v[184:187], v[236:239], v[72:75]
	v_mfma_f32_16x16x32_bf16 v[124:127], v[180:183], v[216:219], v[124:127]
	v_mfma_f32_16x16x32_bf16 v[120:123], v[188:191], v[216:219], v[120:123]
	v_mfma_f32_16x16x32_bf16 v[108:111], v[180:183], v[224:227], v[108:111]
	v_mfma_f32_16x16x32_bf16 v[104:107], v[188:191], v[224:227], v[104:107]
	v_mfma_f32_16x16x32_bf16 v[92:95], v[180:183], v[232:235], v[92:95]
	v_mfma_f32_16x16x32_bf16 v[88:91], v[188:191], v[232:235], v[88:91]
	v_mfma_f32_16x16x32_bf16 v[76:79], v[180:183], v[240:243], v[76:79]
	v_mfma_f32_16x16x32_bf16 v[72:75], v[188:191], v[240:243], v[72:75]
	v_mfma_f32_16x16x32_bf16 v[116:119], v[192:195], v[212:215], v[116:119]
	v_mfma_f32_16x16x32_bf16 v[112:115], v[204:207], v[212:215], v[112:115]
	v_mfma_f32_16x16x32_bf16 v[100:103], v[192:195], v[220:223], v[100:103]
	v_mfma_f32_16x16x32_bf16 v[96:99], v[204:207], v[220:223], v[96:99]
	v_mfma_f32_16x16x32_bf16 v[84:87], v[192:195], v[228:231], v[84:87]
	v_mfma_f32_16x16x32_bf16 v[80:83], v[204:207], v[228:231], v[80:83]
	v_mfma_f32_16x16x32_bf16 v[68:71], v[192:195], v[236:239], v[68:71]
	v_mfma_f32_16x16x32_bf16 v[64:67], v[204:207], v[236:239], v[64:67]
	v_mfma_f32_16x16x32_bf16 v[116:119], v[196:199], v[216:219], v[116:119]
	v_mfma_f32_16x16x32_bf16 v[112:115], v[208:211], v[216:219], v[112:115]
	v_mfma_f32_16x16x32_bf16 v[100:103], v[196:199], v[224:227], v[100:103]
	v_mfma_f32_16x16x32_bf16 v[96:99], v[208:211], v[224:227], v[96:99]
	v_mfma_f32_16x16x32_bf16 v[84:87], v[196:199], v[232:235], v[84:87]
	v_mfma_f32_16x16x32_bf16 v[80:83], v[208:211], v[232:235], v[80:83]
	v_mfma_f32_16x16x32_bf16 v[68:71], v[196:199], v[240:243], v[68:71]
	v_mfma_f32_16x16x32_bf16 v[64:67], v[208:211], v[240:243], v[64:67]
	s_setprio 1
	s_barrier
; #define PG8_STAGE(bufoff, gbase, voff) do { _Pragma("unroll") for (int _i = 0; _i < 2; ++_i) \
;         __builtin_amdgcn_global_load_lds((const unsigned*)((const char*)(gbase) + (voff)[_i]), (LAS unsigned*)(lds + (bufoff) + ldsw + _i * 8192), 16, 0, 0); } while (0)
; #define PG8_LDA(dst, b, h) do { _Pragma("unroll") for (int m = 0; m < 4; ++m) _Pragma("unroll") for (int k = 0; k < 2; ++k) dst[m][k] = *(const LAS bf16x8*)(lds + PG8_SA(b, h) + aoff + m * 2048 + k * 1024); } while (0)
; #define PG8_MMA(ai, bj, At, Bt) do { __builtin_amdgcn_s_setprio(1); _Pragma("unroll") for (int m = 0; m < 4; ++m) _Pragma("unroll") for (int n = 0; n < 2; ++n) _Pragma("unroll") for (int k = 0; k < 2; ++k) \
;         acc[ai][bj][m][n] = __builtin_amdgcn_mfma_f32_16x16x32_bf16(Bt[n][k], At[m][k], acc[ai][bj][m][n], 0, 0, 0); __builtin_amdgcn_s_setprio(0); } while (0)
; #define PG8_WAIT_V(n) asm volatile("s_waitcnt vmcnt(" #n ")" ::: "memory")
; #define PG8_WAIT_L(n) asm volatile("s_waitcnt lgkmcnt(" #n ")" ::: "memory")
; #define PG8_BAR __builtin_amdgcn_s_barrier()
; #define PG8_SCHED __builtin_amdgcn_sched_barrier(0)
; template <class Epi, class Sched, bool ALIGN_EPI = true>
; __device__ __forceinline__ void gemm_phase(LAS unsigned char* lds, const Gemm g, const Sched& S, const Epi& E) {
;     ...
;             PG8_LDA(At, 1, 1); PG8_STAGE(PG8_SB(1, 0), b3, voffB); PG8_STAGE(PG8_SB(1, 1), b3 + hstep, voffB); PG8_STAGE(PG8_SA(1, 0), a3, voffA);
;             PG8_WAIT_V(8); PG8_WAIT_L(0); PG8_BAR; PG8_MMA(1, 0, At, B0); PG8_MMA(1, 1, At, B1); PG8_BAR; PG8_SCHED;
;         }
;         if constexpr (ALIGN_EPI) { if (wr == 0) PG8_BAR; }
;     __device__ __forceinline__ void operator()(const Acc& acc, const Unit& u, int wr, int wc, int fr, int fq) const {
;         switch (u.pm >> 2) {
;             case 0: body<0>(acc, u, wr, wc, fr, fq); break;
	s_add_i32 s38, s46, s42
	v_lshl_add_u64 v[164:165], v[164:165], 0, s[22:23]
	s_mov_b32 m0, s38
	ds_read_b128 v[212:215], v171 offset:49152
	ds_read_b128 v[216:219], v171 offset:50176
	ds_read_b128 v[220:223], v171 offset:51200
	ds_read_b128 v[224:227], v171 offset:52224
	ds_read_b128 v[228:231], v171 offset:53248
	ds_read_b128 v[232:235], v171 offset:54272
	ds_read_b128 v[236:239], v171 offset:55296
	ds_read_b128 v[240:243], v171 offset:56320
	global_load_lds_dwordx4 v[164:165], off
	s_add_i32 m0, s38, 0x2000
	s_add_u32 s36, s36, 0x80080
	v_lshl_add_u64 v[164:165], v[176:177], 0, s[22:23]
	s_addc_u32 s37, s37, 0
	s_add_i32 s38, s47, s42
	global_load_lds_dwordx4 v[164:165], off
	v_lshl_add_u64 v[164:165], s[36:37], 0, v[130:131]
	s_mov_b32 m0, s38
	s_nop 0
	global_load_lds_dwordx4 v[164:165], off
	v_lshl_add_u64 v[164:165], s[36:37], 0, v[134:135]
	s_add_i32 m0, s38, 0x2000
	s_nop 0
	global_load_lds_dwordx4 v[164:165], off
	v_lshl_add_u64 v[164:165], v[200:201], 0, s[22:23]
	s_mov_b32 m0, s54
	s_nop 0
	global_load_lds_dwordx4 v[164:165], off
	v_lshl_add_u64 v[164:165], v[244:245], 0, s[22:23]
	s_mov_b32 m0, s55
	s_nop 0
	global_load_lds_dwordx4 v[164:165], off
	s_waitcnt vmcnt(8)
	s_waitcnt lgkmcnt(0)
	s_barrier
	s_setprio 0
	s_waitcnt lgkmcnt(0)
	v_mfma_f32_16x16x32_bf16 v[60:63], v[172:175], v[212:215], v[60:63]
	v_mfma_f32_16x16x32_bf16 v[56:59], v[184:187], v[212:215], v[56:59]
	v_mfma_f32_16x16x32_bf16 v[44:47], v[172:175], v[220:223], v[44:47]
	v_mfma_f32_16x16x32_bf16 v[40:43], v[184:187], v[220:223], v[40:43]
	v_mfma_f32_16x16x32_bf16 v[28:31], v[172:175], v[228:231], v[28:31]
	v_mfma_f32_16x16x32_bf16 v[24:27], v[184:187], v[228:231], v[24:27]
	v_mfma_f32_16x16x32_bf16 v[12:15], v[172:175], v[236:239], v[12:15]
	v_mfma_f32_16x16x32_bf16 v[8:11], v[184:187], v[236:239], v[8:11]
	v_mfma_f32_16x16x32_bf16 v[60:63], v[180:183], v[216:219], v[60:63]
	v_mfma_f32_16x16x32_bf16 v[56:59], v[188:191], v[216:219], v[56:59]
	v_mfma_f32_16x16x32_bf16 v[44:47], v[180:183], v[224:227], v[44:47]
	v_mfma_f32_16x16x32_bf16 v[40:43], v[188:191], v[224:227], v[40:43]
	v_mfma_f32_16x16x32_bf16 v[28:31], v[180:183], v[232:235], v[28:31]
	v_mfma_f32_16x16x32_bf16 v[24:27], v[188:191], v[232:235], v[24:27]
	v_mfma_f32_16x16x32_bf16 v[12:15], v[180:183], v[240:243], v[12:15]
	v_mfma_f32_16x16x32_bf16 v[8:11], v[188:191], v[240:243], v[8:11]
	v_mfma_f32_16x16x32_bf16 v[52:55], v[192:195], v[212:215], v[52:55]
	v_mfma_f32_16x16x32_bf16 v[48:51], v[204:207], v[212:215], v[48:51]
	v_mfma_f32_16x16x32_bf16 v[36:39], v[192:195], v[220:223], v[36:39]
	v_mfma_f32_16x16x32_bf16 v[32:35], v[204:207], v[220:223], v[32:35]
	v_mfma_f32_16x16x32_bf16 v[20:23], v[192:195], v[228:231], v[20:23]
	v_mfma_f32_16x16x32_bf16 v[16:19], v[204:207], v[228:231], v[16:19]
	v_mfma_f32_16x16x32_bf16 v[4:7], v[192:195], v[236:239], v[4:7]
	v_mfma_f32_16x16x32_bf16 v[0:3], v[204:207], v[236:239], v[0:3]
	v_mfma_f32_16x16x32_bf16 v[52:55], v[196:199], v[216:219], v[52:55]
	v_mfma_f32_16x16x32_bf16 v[48:51], v[208:211], v[216:219], v[48:51]
	v_mfma_f32_16x16x32_bf16 v[36:39], v[196:199], v[224:227], v[36:39]
	v_mfma_f32_16x16x32_bf16 v[32:35], v[208:211], v[224:227], v[32:35]
	v_mfma_f32_16x16x32_bf16 v[20:23], v[196:199], v[232:235], v[20:23]
	v_mfma_f32_16x16x32_bf16 v[16:19], v[208:211], v[232:235], v[16:19]
	v_mfma_f32_16x16x32_bf16 v[4:7], v[196:199], v[240:243], v[4:7]
	v_mfma_f32_16x16x32_bf16 v[0:3], v[208:211], v[240:243], v[0:3]
	s_setprio 1
	s_barrier
	s_add_i32 s89, s89, 2
	s_add_u32 s34, s34, 0x100
	s_addc_u32 s35, s35, 0
	s_add_u32 s87, s87, 0x100
	s_addc_u32 s88, s88, 0
	s_cmp_gt_u32 s89, 29
	s_cbranch_scc0 .LBB0_195
	s_and_b64 vcc, exec, s[24:25]
	s_cbranch_vccnz .LBB0_202
	s_lshr_b32 s9, s81, 2
	s_cmp_lt_i32 s9, 1
	s_mov_b64 s[34:35], -1
	s_cbranch_scc0 .LBB0_203

; #define PG8_STAGE(bufoff, gbase, voff) do { _Pragma("unroll") for (int _i = 0; _i < 2; ++_i) \
;         __builtin_amdgcn_global_load_lds((const unsigned*)((const char*)(gbase) + (voff)[_i]), (LAS unsigned*)(lds + (bufoff) + ldsw + _i * 8192), 16, 0, 0); } while (0)
; #define PG8_LDA(dst, b, h) do { _Pragma("unroll") for (int m = 0; m < 4; ++m) _Pragma("unroll") for (int k = 0; k < 2; ++k) dst[m][k] = *(const LAS bf16x8*)(lds + PG8_SA(b, h) + aoff + m * 2048 + k * 1024); } while (0)
; #define PG8_LDB(dst, b, h) do { _Pragma("unroll") for (int n = 0; n < 2; ++n) _Pragma("unroll") for (int k = 0; k < 2; ++k) dst[n][k] = *(const LAS bf16x8*)(lds + PG8_SB(b, h) + boff + n * 2048 + k * 1024); } while (0)
; #define PG8_MMA(ai, bj, At, Bt) do { __builtin_amdgcn_s_setprio(1); _Pragma("unroll") for (int m = 0; m < 4; ++m) _Pragma("unroll") for (int n = 0; n < 2; ++n) _Pragma("unroll") for (int k = 0; k < 2; ++k) \
;         acc[ai][bj][m][n] = __builtin_amdgcn_mfma_f32_16x16x32_bf16(Bt[n][k], At[m][k], acc[ai][bj][m][n], 0, 0, 0); __builtin_amdgcn_s_setprio(0); } while (0)
; #define PG8_WAIT_V(n) asm volatile("s_waitcnt vmcnt(" #n ")" ::: "memory")
; #define PG8_WAIT_L(n) asm volatile("s_waitcnt lgkmcnt(" #n ")" ::: "memory")
; #define PG8_BAR __builtin_amdgcn_s_barrier()
; #define PG8_SCHED __builtin_amdgcn_sched_barrier(0)
; template <class Epi, class Sched, bool ALIGN_EPI = true>
; __device__ __forceinline__ void gemm_phase(LAS unsigned char* lds, const Gemm g, const Sched& S, const Epi& E) {
;     ...
;         for (int t = 0; t < nt; t += 2) {
;             const bool last = (t == nt - 2);
;             const char* a1 = cA + (size_t)(t + 1) * kstep;
;             const char* a2 = last ? nA : cA + (size_t)(t + 2) * kstep; const char* b2 = last ? nB : cB + (size_t)(t + 2) * kstep;
;             const char* a3 = a2 + kstep; const char* b3 = b2 + kstep;
;             PG8_LDB(B0, 0, 0); PG8_LDB(B1, 0, 1); PG8_SCHED; PG8_LDA(At, 0, 0); PG8_STAGE(PG8_SA(1, 1), a1 + hstep, voffA);
;             PG8_WAIT_V(8); PG8_WAIT_L(0); PG8_BAR; PG8_MMA(0, 0, At, B0); PG8_MMA(0, 1, At, B1); PG8_BAR; PG8_SCHED;
;             PG8_LDA(At, 0, 1); PG8_STAGE(PG8_SB(0, 0), b2, voffB); PG8_STAGE(PG8_SB(0, 1), b2 + hstep, voffB); PG8_STAGE(PG8_SA(0, 0), a2, voffA);
.LBB0_223:
	ds_read_b128 v[128:131], v203
	s_waitcnt lgkmcnt(0)
	ds_read_b128 v[132:135], v203 offset:1024
	ds_read_b128 v[136:139], v203 offset:2048
	ds_read_b128 v[140:143], v203 offset:3072
	ds_read_b128 v[176:179], v204
	ds_read_b128 v[180:183], v204 offset:1024
	ds_read_b128 v[184:187], v204 offset:2048
	ds_read_b128 v[188:191], v204 offset:3072
	s_add_u32 s46, s76, 0xfff80080
	s_addc_u32 s47, s77, -1
	s_cmp_eq_u32 vcc_hi, 28
	s_cselect_b32 s81, s9, s47
	s_cselect_b32 s80, s30, s46
	s_cselect_b32 s79, s11, vcc_lo
	s_cselect_b32 s78, s96, s97
	v_lshl_add_u64 v[200:201], s[76:77], 0, v[164:165]
	s_add_i32 m0, s55, 0xc000
	ds_read_b128 v[192:195], v205
	ds_read_b128 v[196:199], v205 offset:1024
	ds_read_b128 v[208:211], v205 offset:2048
	ds_read_b128 v[212:215], v205 offset:3072
	ds_read_b128 v[216:219], v205 offset:4096
	ds_read_b128 v[220:223], v205 offset:5120
	ds_read_b128 v[224:227], v205 offset:6144
	ds_read_b128 v[228:231], v205 offset:7168
	global_load_lds_dwordx4 v[200:201], off
	v_lshl_add_u64 v[200:201], s[76:77], 0, v[166:167]
	s_add_i32 m0, s55, 0xe000
	s_nop 0
	global_load_lds_dwordx4 v[200:201], off
	s_waitcnt vmcnt(8)
	s_waitcnt lgkmcnt(0)
	s_barrier
	s_setprio 0
	s_waitcnt lgkmcnt(0)
	v_mfma_f32_16x16x32_bf16 v[124:127], v[128:131], v[192:195], v[124:127]
	v_mfma_f32_16x16x32_bf16 v[120:123], v[136:139], v[192:195], v[120:123]
	v_mfma_f32_16x16x32_bf16 v[108:111], v[128:131], v[208:211], v[108:111]
	v_mfma_f32_16x16x32_bf16 v[104:107], v[136:139], v[208:211], v[104:107]
	v_mfma_f32_16x16x32_bf16 v[92:95], v[128:131], v[216:219], v[92:95]
	v_mfma_f32_16x16x32_bf16 v[88:91], v[136:139], v[216:219], v[88:91]
	v_mfma_f32_16x16x32_bf16 v[76:79], v[128:131], v[224:227], v[76:79]
	v_mfma_f32_16x16x32_bf16 v[72:75], v[136:139], v[224:227], v[72:75]
	v_mfma_f32_16x16x32_bf16 v[124:127], v[132:135], v[196:199], v[124:127]
	v_mfma_f32_16x16x32_bf16 v[120:123], v[140:143], v[196:199], v[120:123]
	v_mfma_f32_16x16x32_bf16 v[108:111], v[132:135], v[212:215], v[108:111]
	v_mfma_f32_16x16x32_bf16 v[104:107], v[140:143], v[212:215], v[104:107]
	v_mfma_f32_16x16x32_bf16 v[92:95], v[132:135], v[220:223], v[92:95]
	v_mfma_f32_16x16x32_bf16 v[88:91], v[140:143], v[220:223], v[88:91]
	v_mfma_f32_16x16x32_bf16 v[76:79], v[132:135], v[228:231], v[76:79]
	v_mfma_f32_16x16x32_bf16 v[72:75], v[140:143], v[228:231], v[72:75]
	v_mfma_f32_16x16x32_bf16 v[116:119], v[176:179], v[192:195], v[116:119]
	v_mfma_f32_16x16x32_bf16 v[112:115], v[184:187], v[192:195], v[112:115]
	v_mfma_f32_16x16x32_bf16 v[100:103], v[176:179], v[208:211], v[100:103]
	v_mfma_f32_16x16x32_bf16 v[96:99], v[184:187], v[208:211], v[96:99]
	v_mfma_f32_16x16x32_bf16 v[84:87], v[176:179], v[216:219], v[84:87]
	v_mfma_f32_16x16x32_bf16 v[80:83], v[184:187], v[216:219], v[80:83]
	v_mfma_f32_16x16x32_bf16 v[68:71], v[176:179], v[224:227], v[68:71]
	v_mfma_f32_16x16x32_bf16 v[64:67], v[184:187], v[224:227], v[64:67]
	v_mfma_f32_16x16x32_bf16 v[116:119], v[180:183], v[196:199], v[116:119]
	v_mfma_f32_16x16x32_bf16 v[112:115], v[188:191], v[196:199], v[112:115]
	v_mfma_f32_16x16x32_bf16 v[100:103], v[180:183], v[212:215], v[100:103]
	v_mfma_f32_16x16x32_bf16 v[96:99], v[188:191], v[212:215], v[96:99]
	v_mfma_f32_16x16x32_bf16 v[84:87], v[180:183], v[220:223], v[84:87]
	v_mfma_f32_16x16x32_bf16 v[80:83], v[188:191], v[220:223], v[80:83]
	v_mfma_f32_16x16x32_bf16 v[68:71], v[180:183], v[228:231], v[68:71]
	v_mfma_f32_16x16x32_bf16 v[64:67], v[188:191], v[228:231], v[64:67]
	s_setprio 1
	s_barrier
	s_add_i32 s46, s90, s53
	v_lshl_add_u64 v[200:201], s[78:79], 0, v[146:147]
	s_mov_b32 m0, s46
	ds_read_b128 v[192:195], v205 offset:16384
	ds_read_b128 v[196:199], v205 offset:17408
	ds_read_b128 v[208:211], v205 offset:18432
	ds_read_b128 v[212:215], v205 offset:19456
	ds_read_b128 v[216:219], v205 offset:20480
	ds_read_b128 v[220:223], v205 offset:21504
	ds_read_b128 v[224:227], v205 offset:22528
	ds_read_b128 v[228:231], v205 offset:23552
	global_load_lds_dwordx4 v[200:201], off
	s_add_i32 m0, s46, 0x2000
	s_add_u32 s46, s78, 0x80000
	v_lshl_add_u64 v[232:233], s[78:79], 0, v[150:151]
	s_addc_u32 s47, s79, 0
	s_add_i32 s82, s91, s53
	global_load_lds_dwordx4 v[232:233], off
	v_lshl_add_u64 v[234:235], s[46:47], 0, v[146:147]
	s_mov_b32 m0, s82
	v_lshl_add_u64 v[236:237], s[80:81], 0, v[148:149]
	global_load_lds_dwordx4 v[234:235], off
	v_lshl_add_u64 v[234:235], s[46:47], 0, v[150:151]
	s_add_i32 m0, s82, 0x2000
	s_nop 0
	global_load_lds_dwordx4 v[234:235], off
	v_lshl_add_u64 v[234:235], s[80:81], 0, v[144:145]
	s_mov_b32 m0, s55
	s_nop 0
	global_load_lds_dwordx4 v[234:235], off
	s_mov_b32 m0, s57
	s_nop 0
	global_load_lds_dwordx4 v[236:237], off
	s_waitcnt vmcnt(8)
	s_waitcnt lgkmcnt(0)
	s_barrier
; #define PG8_STAGE(bufoff, gbase, voff) do { _Pragma("unroll") for (int _i = 0; _i < 2; ++_i) \
;         __builtin_amdgcn_global_load_lds((const unsigned*)((const char*)(gbase) + (voff)[_i]), (LAS unsigned*)(lds + (bufoff) + ldsw + _i * 8192), 16, 0, 0); } while (0)
; #define PG8_LDA(dst, b, h) do { _Pragma("unroll") for (int m = 0; m < 4; ++m) _Pragma("unroll") for (int k = 0; k < 2; ++k) dst[m][k] = *(const LAS bf16x8*)(lds + PG8_SA(b, h) + aoff + m * 2048 + k * 1024); } while (0)
; #define PG8_LDB(dst, b, h) do { _Pragma("unroll") for (int n = 0; n < 2; ++n) _Pragma("unroll") for (int k = 0; k < 2; ++k) dst[n][k] = *(const LAS bf16x8*)(lds + PG8_SB(b, h) + boff + n * 2048 + k * 1024); } while (0)
; #define PG8_MMA(ai, bj, At, Bt) do { __builtin_amdgcn_s_setprio(1); _Pragma("unroll") for (int m = 0; m < 4; ++m) _Pragma("unroll") for (int n = 0; n < 2; ++n) _Pragma("unroll") for (int k = 0; k < 2; ++k) \
;         acc[ai][bj][m][n] = __builtin_amdgcn_mfma_f32_16x16x32_bf16(Bt[n][k], At[m][k], acc[ai][bj][m][n], 0, 0, 0); __builtin_amdgcn_s_setprio(0); } while (0)
; #define PG8_WAIT_V(n) asm volatile("s_waitcnt vmcnt(" #n ")" ::: "memory")
; #define PG8_WAIT_L(n) asm volatile("s_waitcnt lgkmcnt(" #n ")" ::: "memory")
; #define PG8_BAR __builtin_amdgcn_s_barrier()
; #define PG8_SCHED __builtin_amdgcn_sched_barrier(0)
; template <class Epi, class Sched, bool ALIGN_EPI = true>
; __device__ __forceinline__ void gemm_phase(LAS unsigned char* lds, const Gemm g, const Sched& S, const Epi& E) {
;     ...
;             PG8_WAIT_V(8); PG8_WAIT_L(0); PG8_BAR; PG8_MMA(1, 0, At, B0); PG8_MMA(1, 1, At, B1); PG8_BAR; PG8_SCHED;
;             PG8_LDB(B0, 1, 0); PG8_LDB(B1, 1, 1); PG8_SCHED; PG8_LDA(At, 1, 0); PG8_STAGE(PG8_SA(0, 1), a2 + hstep, voffA);
;             PG8_WAIT_V(8); PG8_WAIT_L(0); PG8_BAR; PG8_MMA(0, 0, At, B0); PG8_MMA(0, 1, At, B1); PG8_BAR; PG8_SCHED;
	s_setprio 0
	s_waitcnt lgkmcnt(0)
	v_mfma_f32_16x16x32_bf16 v[60:63], v[128:131], v[192:195], v[60:63]
	v_mfma_f32_16x16x32_bf16 v[56:59], v[136:139], v[192:195], v[56:59]
	v_mfma_f32_16x16x32_bf16 v[44:47], v[128:131], v[208:211], v[44:47]
	v_mfma_f32_16x16x32_bf16 v[40:43], v[136:139], v[208:211], v[40:43]
	v_mfma_f32_16x16x32_bf16 v[28:31], v[128:131], v[216:219], v[28:31]
	v_mfma_f32_16x16x32_bf16 v[24:27], v[136:139], v[216:219], v[24:27]
	v_mfma_f32_16x16x32_bf16 v[12:15], v[128:131], v[224:227], v[12:15]
	v_mfma_f32_16x16x32_bf16 v[8:11], v[136:139], v[224:227], v[8:11]
	v_mfma_f32_16x16x32_bf16 v[60:63], v[132:135], v[196:199], v[60:63]
	v_mfma_f32_16x16x32_bf16 v[56:59], v[140:143], v[196:199], v[56:59]
	v_mfma_f32_16x16x32_bf16 v[44:47], v[132:135], v[212:215], v[44:47]
	v_mfma_f32_16x16x32_bf16 v[40:43], v[140:143], v[212:215], v[40:43]
	v_mfma_f32_16x16x32_bf16 v[28:31], v[132:135], v[220:223], v[28:31]
	v_mfma_f32_16x16x32_bf16 v[24:27], v[140:143], v[220:223], v[24:27]
	v_mfma_f32_16x16x32_bf16 v[12:15], v[132:135], v[228:231], v[12:15]
	v_mfma_f32_16x16x32_bf16 v[8:11], v[140:143], v[228:231], v[8:11]
	v_mfma_f32_16x16x32_bf16 v[52:55], v[176:179], v[192:195], v[52:55]
	v_mfma_f32_16x16x32_bf16 v[48:51], v[184:187], v[192:195], v[48:51]
	v_mfma_f32_16x16x32_bf16 v[36:39], v[176:179], v[208:211], v[36:39]
	v_mfma_f32_16x16x32_bf16 v[32:35], v[184:187], v[208:211], v[32:35]
	v_mfma_f32_16x16x32_bf16 v[20:23], v[176:179], v[216:219], v[20:23]
	v_mfma_f32_16x16x32_bf16 v[16:19], v[184:187], v[216:219], v[16:19]
	v_mfma_f32_16x16x32_bf16 v[4:7], v[176:179], v[224:227], v[4:7]
	v_mfma_f32_16x16x32_bf16 v[0:3], v[184:187], v[224:227], v[0:3]
	v_mfma_f32_16x16x32_bf16 v[52:55], v[180:183], v[196:199], v[52:55]
	v_mfma_f32_16x16x32_bf16 v[48:51], v[188:191], v[196:199], v[48:51]
	v_mfma_f32_16x16x32_bf16 v[36:39], v[180:183], v[212:215], v[36:39]
	v_mfma_f32_16x16x32_bf16 v[32:35], v[188:191], v[212:215], v[32:35]
	v_mfma_f32_16x16x32_bf16 v[20:23], v[180:183], v[220:223], v[20:23]
	v_mfma_f32_16x16x32_bf16 v[16:19], v[188:191], v[220:223], v[16:19]
	v_mfma_f32_16x16x32_bf16 v[4:7], v[180:183], v[228:231], v[4:7]
	v_mfma_f32_16x16x32_bf16 v[0:3], v[188:191], v[228:231], v[0:3]
	s_setprio 1
	s_barrier
	s_add_i32 s82, 0, 0x18000
	s_add_i32 s92, 0, 0x1c000
	v_add_u32_e32 v140, s82, v161
	v_add_u32_e32 v152, s92, v161
	ds_read_b128 v[128:131], v140
	ds_read_b128 v[132:135], v140 offset:1024
	ds_read_b128 v[136:139], v140 offset:2048
	ds_read_b128 v[140:143], v140 offset:3072
	ds_read_b128 v[176:179], v152
	ds_read_b128 v[180:183], v152 offset:1024
	ds_read_b128 v[184:187], v152 offset:2048
	ds_read_b128 v[188:191], v152 offset:3072
	s_add_u32 s46, s80, 0x80000
	s_addc_u32 s47, s81, 0
	s_mov_b32 m0, s83
	v_lshl_add_u64 v[238:239], s[46:47], 0, v[144:145]
	ds_read_b128 v[192:195], v205 offset:32768
	ds_read_b128 v[196:199], v205 offset:33792
	ds_read_b128 v[208:211], v205 offset:34816
	ds_read_b128 v[212:215], v205 offset:35840
	ds_read_b128 v[216:219], v205 offset:36864
	ds_read_b128 v[220:223], v205 offset:37888
	ds_read_b128 v[224:227], v205 offset:38912
	ds_read_b128 v[228:231], v205 offset:39936
	global_load_lds_dwordx4 v[238:239], off
	v_lshl_add_u64 v[238:239], s[46:47], 0, v[148:149]
	s_mov_b32 m0, s84
	s_nop 0
	global_load_lds_dwordx4 v[238:239], off
	s_waitcnt vmcnt(8)
	s_waitcnt lgkmcnt(0)
	s_barrier
	s_setprio 0
	s_waitcnt lgkmcnt(0)
	v_mfma_f32_16x16x32_bf16 v[124:127], v[128:131], v[192:195], v[124:127]
	v_mfma_f32_16x16x32_bf16 v[120:123], v[136:139], v[192:195], v[120:123]
	v_mfma_f32_16x16x32_bf16 v[108:111], v[128:131], v[208:211], v[108:111]
	v_mfma_f32_16x16x32_bf16 v[104:107], v[136:139], v[208:211], v[104:107]
	v_mfma_f32_16x16x32_bf16 v[92:95], v[128:131], v[216:219], v[92:95]
	v_mfma_f32_16x16x32_bf16 v[88:91], v[136:139], v[216:219], v[88:91]
	v_mfma_f32_16x16x32_bf16 v[76:79], v[128:131], v[224:227], v[76:79]
	v_mfma_f32_16x16x32_bf16 v[72:75], v[136:139], v[224:227], v[72:75]
	v_mfma_f32_16x16x32_bf16 v[124:127], v[132:135], v[196:199], v[124:127]
	v_mfma_f32_16x16x32_bf16 v[120:123], v[140:143], v[196:199], v[120:123]
	v_mfma_f32_16x16x32_bf16 v[108:111], v[132:135], v[212:215], v[108:111]
	v_mfma_f32_16x16x32_bf16 v[104:107], v[140:143], v[212:215], v[104:107]
	v_mfma_f32_16x16x32_bf16 v[92:95], v[132:135], v[220:223], v[92:95]
	v_mfma_f32_16x16x32_bf16 v[88:91], v[140:143], v[220:223], v[88:91]
	v_mfma_f32_16x16x32_bf16 v[76:79], v[132:135], v[228:231], v[76:79]
	v_mfma_f32_16x16x32_bf16 v[72:75], v[140:143], v[228:231], v[72:75]
	v_mfma_f32_16x16x32_bf16 v[116:119], v[176:179], v[192:195], v[116:119]
	v_mfma_f32_16x16x32_bf16 v[112:115], v[184:187], v[192:195], v[112:115]
	v_mfma_f32_16x16x32_bf16 v[100:103], v[176:179], v[208:211], v[100:103]
	v_mfma_f32_16x16x32_bf16 v[96:99], v[184:187], v[208:211], v[96:99]
	v_mfma_f32_16x16x32_bf16 v[84:87], v[176:179], v[216:219], v[84:87]
	v_mfma_f32_16x16x32_bf16 v[80:83], v[184:187], v[216:219], v[80:83]
	v_mfma_f32_16x16x32_bf16 v[68:71], v[176:179], v[224:227], v[68:71]
	v_mfma_f32_16x16x32_bf16 v[64:67], v[184:187], v[224:227], v[64:67]
	v_mfma_f32_16x16x32_bf16 v[116:119], v[180:183], v[196:199], v[116:119]
	v_mfma_f32_16x16x32_bf16 v[112:115], v[188:191], v[196:199], v[112:115]
	v_mfma_f32_16x16x32_bf16 v[100:103], v[180:183], v[212:215], v[100:103]
	v_mfma_f32_16x16x32_bf16 v[96:99], v[188:191], v[212:215], v[96:99]
	v_mfma_f32_16x16x32_bf16 v[84:87], v[180:183], v[220:223], v[84:87]
	v_mfma_f32_16x16x32_bf16 v[80:83], v[188:191], v[220:223], v[80:83]
	v_mfma_f32_16x16x32_bf16 v[68:71], v[180:183], v[228:231], v[68:71]
	v_mfma_f32_16x16x32_bf16 v[64:67], v[188:191], v[228:231], v[64:67]
	s_setprio 1
	s_barrier
; #define PG8_STAGE(bufoff, gbase, voff) do { _Pragma("unroll") for (int _i = 0; _i < 2; ++_i) \
;         __builtin_amdgcn_global_load_lds((const unsigned*)((const char*)(gbase) + (voff)[_i]), (LAS unsigned*)(lds + (bufoff) + ldsw + _i * 8192), 16, 0, 0); } while (0)
; #define PG8_LDA(dst, b, h) do { _Pragma("unroll") for (int m = 0; m < 4; ++m) _Pragma("unroll") for (int k = 0; k < 2; ++k) dst[m][k] = *(const LAS bf16x8*)(lds + PG8_SA(b, h) + aoff + m * 2048 + k * 1024); } while (0)
; #define PG8_MMA(ai, bj, At, Bt) do { __builtin_amdgcn_s_setprio(1); _Pragma("unroll") for (int m = 0; m < 4; ++m) _Pragma("unroll") for (int n = 0; n < 2; ++n) _Pragma("unroll") for (int k = 0; k < 2; ++k) \
;         acc[ai][bj][m][n] = __builtin_amdgcn_mfma_f32_16x16x32_bf16(Bt[n][k], At[m][k], acc[ai][bj][m][n], 0, 0, 0); __builtin_amdgcn_s_setprio(0); } while (0)
; #define PG8_WAIT_V(n) asm volatile("s_waitcnt vmcnt(" #n ")" ::: "memory")
; #define PG8_WAIT_L(n) asm volatile("s_waitcnt lgkmcnt(" #n ")" ::: "memory")
; #define PG8_BAR __builtin_amdgcn_s_barrier()
; #define PG8_SCHED __builtin_amdgcn_sched_barrier(0)
; template <class Epi, class Sched, bool ALIGN_EPI = true>
; __device__ __forceinline__ void gemm_phase(LAS unsigned char* lds, const Gemm g, const Sched& S, const Epi& E) {
;     ...
;             PG8_LDA(At, 1, 1); PG8_STAGE(PG8_SB(1, 0), b3, voffB); PG8_STAGE(PG8_SB(1, 1), b3 + hstep, voffB); PG8_STAGE(PG8_SA(1, 0), a3, voffA);
;             PG8_WAIT_V(8); PG8_WAIT_L(0); PG8_BAR; PG8_MMA(1, 0, At, B0); PG8_MMA(1, 1, At, B1); PG8_BAR; PG8_SCHED;
;         }
;         if constexpr (ALIGN_EPI) { if (wr == 0) PG8_BAR; }
	s_add_i32 s46, s82, s53
	v_lshl_add_u64 v[200:201], v[200:201], 0, s[28:29]
	s_mov_b32 m0, s46
	ds_read_b128 v[192:195], v205 offset:49152
	ds_read_b128 v[196:199], v205 offset:50176
	ds_read_b128 v[208:211], v205 offset:51200
	ds_read_b128 v[212:215], v205 offset:52224
	ds_read_b128 v[216:219], v205 offset:53248
	ds_read_b128 v[220:223], v205 offset:54272
	ds_read_b128 v[224:227], v205 offset:55296
	ds_read_b128 v[228:231], v205 offset:56320
	global_load_lds_dwordx4 v[200:201], off
	s_add_i32 m0, s46, 0x2000
	s_add_u32 s46, s78, 0x80080
	v_lshl_add_u64 v[200:201], v[232:233], 0, s[28:29]
	s_addc_u32 s47, s79, 0
	s_add_i32 s78, s92, s53
	global_load_lds_dwordx4 v[200:201], off
	v_lshl_add_u64 v[200:201], s[46:47], 0, v[146:147]
	s_mov_b32 m0, s78
	s_nop 0
	global_load_lds_dwordx4 v[200:201], off
	v_lshl_add_u64 v[200:201], s[46:47], 0, v[150:151]
	s_add_i32 m0, s78, 0x2000
	s_nop 0
	global_load_lds_dwordx4 v[200:201], off
	v_lshl_add_u64 v[200:201], v[234:235], 0, s[28:29]
	s_mov_b32 m0, s87
	s_nop 0
	global_load_lds_dwordx4 v[200:201], off
	v_lshl_add_u64 v[200:201], v[236:237], 0, s[28:29]
	s_mov_b32 m0, s88
	s_nop 0
	global_load_lds_dwordx4 v[200:201], off
	s_waitcnt vmcnt(8)
	s_waitcnt lgkmcnt(0)
	s_barrier
	s_setprio 0
	s_waitcnt lgkmcnt(0)
	v_mfma_f32_16x16x32_bf16 v[60:63], v[128:131], v[192:195], v[60:63]
	v_mfma_f32_16x16x32_bf16 v[56:59], v[136:139], v[192:195], v[56:59]
	v_mfma_f32_16x16x32_bf16 v[44:47], v[128:131], v[208:211], v[44:47]
	v_mfma_f32_16x16x32_bf16 v[40:43], v[136:139], v[208:211], v[40:43]
	v_mfma_f32_16x16x32_bf16 v[28:31], v[128:131], v[216:219], v[28:31]
	v_mfma_f32_16x16x32_bf16 v[24:27], v[136:139], v[216:219], v[24:27]
	v_mfma_f32_16x16x32_bf16 v[12:15], v[128:131], v[224:227], v[12:15]
	v_mfma_f32_16x16x32_bf16 v[8:11], v[136:139], v[224:227], v[8:11]
	v_mfma_f32_16x16x32_bf16 v[60:63], v[132:135], v[196:199], v[60:63]
	v_mfma_f32_16x16x32_bf16 v[56:59], v[140:143], v[196:199], v[56:59]
	v_mfma_f32_16x16x32_bf16 v[44:47], v[132:135], v[212:215], v[44:47]
	v_mfma_f32_16x16x32_bf16 v[40:43], v[140:143], v[212:215], v[40:43]
	v_mfma_f32_16x16x32_bf16 v[28:31], v[132:135], v[220:223], v[28:31]
	v_mfma_f32_16x16x32_bf16 v[24:27], v[140:143], v[220:223], v[24:27]
	v_mfma_f32_16x16x32_bf16 v[12:15], v[132:135], v[228:231], v[12:15]
	v_mfma_f32_16x16x32_bf16 v[8:11], v[140:143], v[228:231], v[8:11]
	v_mfma_f32_16x16x32_bf16 v[52:55], v[176:179], v[192:195], v[52:55]
	v_mfma_f32_16x16x32_bf16 v[48:51], v[184:187], v[192:195], v[48:51]
	v_mfma_f32_16x16x32_bf16 v[36:39], v[176:179], v[208:211], v[36:39]
	v_mfma_f32_16x16x32_bf16 v[32:35], v[184:187], v[208:211], v[32:35]
	v_mfma_f32_16x16x32_bf16 v[20:23], v[176:179], v[216:219], v[20:23]
	v_mfma_f32_16x16x32_bf16 v[16:19], v[184:187], v[216:219], v[16:19]
	v_mfma_f32_16x16x32_bf16 v[4:7], v[176:179], v[224:227], v[4:7]
	v_mfma_f32_16x16x32_bf16 v[0:3], v[184:187], v[224:227], v[0:3]
	v_mfma_f32_16x16x32_bf16 v[52:55], v[180:183], v[196:199], v[52:55]
	v_mfma_f32_16x16x32_bf16 v[48:51], v[188:191], v[196:199], v[48:51]
	v_mfma_f32_16x16x32_bf16 v[36:39], v[180:183], v[212:215], v[36:39]
	v_mfma_f32_16x16x32_bf16 v[32:35], v[188:191], v[212:215], v[32:35]
	v_mfma_f32_16x16x32_bf16 v[20:23], v[180:183], v[220:223], v[20:23]
	v_mfma_f32_16x16x32_bf16 v[16:19], v[188:191], v[220:223], v[16:19]
	v_mfma_f32_16x16x32_bf16 v[4:7], v[180:183], v[228:231], v[4:7]
	v_mfma_f32_16x16x32_bf16 v[0:3], v[188:191], v[228:231], v[0:3]
	s_setprio 1
	s_barrier
	s_add_i32 vcc_hi, vcc_hi, 2
	s_add_u32 s76, s76, 0x100
	s_addc_u32 s77, s77, 0
	s_add_u32 s97, s97, 0x100
	s_addc_u32 vcc_lo, vcc_lo, 0
	s_cmp_gt_u32 vcc_hi, 29
	s_cbranch_scc0 .LBB0_223
	s_and_b64 vcc, exec, s[34:35]
	s_cbranch_vccz .LBB0_226
	s_barrier

; #define PG8_STAGE(bufoff, gbase, voff) do { _Pragma("unroll") for (int _i = 0; _i < 2; ++_i) \
;         __builtin_amdgcn_global_load_lds((const unsigned*)((const char*)(gbase) + (voff)[_i]), (LAS unsigned*)(lds + (bufoff) + ldsw + _i * 8192), 16, 0, 0); } while (0)
; #define PG8_LDA(dst, b, h) do { _Pragma("unroll") for (int m = 0; m < 4; ++m) _Pragma("unroll") for (int k = 0; k < 2; ++k) dst[m][k] = *(const LAS bf16x8*)(lds + PG8_SA(b, h) + aoff + m * 2048 + k * 1024); } while (0)
; #define PG8_LDB(dst, b, h) do { _Pragma("unroll") for (int n = 0; n < 2; ++n) _Pragma("unroll") for (int k = 0; k < 2; ++k) dst[n][k] = *(const LAS bf16x8*)(lds + PG8_SB(b, h) + boff + n * 2048 + k * 1024); } while (0)
; #define PG8_MMA(ai, bj, At, Bt) do { __builtin_amdgcn_s_setprio(1); _Pragma("unroll") for (int m = 0; m < 4; ++m) _Pragma("unroll") for (int n = 0; n < 2; ++n) _Pragma("unroll") for (int k = 0; k < 2; ++k) \
;         acc[ai][bj][m][n] = __builtin_amdgcn_mfma_f32_16x16x32_bf16(Bt[n][k], At[m][k], acc[ai][bj][m][n], 0, 0, 0); __builtin_amdgcn_s_setprio(0); } while (0)
; #define PG8_WAIT_V(n) asm volatile("s_waitcnt vmcnt(" #n ")" ::: "memory")
; #define PG8_WAIT_L(n) asm volatile("s_waitcnt lgkmcnt(" #n ")" ::: "memory")
; #define PG8_BAR __builtin_amdgcn_s_barrier()
; #define PG8_SCHED __builtin_amdgcn_sched_barrier(0)
; template <class Epi, class Sched, bool ALIGN_EPI = true>
; __device__ __forceinline__ void gemm_phase(LAS unsigned char* lds, const Gemm g, const Sched& S, const Epi& E) {
;     ...
;         for (int t = 0; t < nt; t += 2) {
;             const bool last = (t == nt - 2);
;             const char* a1 = cA + (size_t)(t + 1) * kstep;
;             const char* a2 = last ? nA : cA + (size_t)(t + 2) * kstep; const char* b2 = last ? nB : cB + (size_t)(t + 2) * kstep;
;             const char* a3 = a2 + kstep; const char* b3 = b2 + kstep;
;             PG8_LDB(B0, 0, 0); PG8_LDB(B1, 0, 1); PG8_SCHED; PG8_LDA(At, 0, 0); PG8_STAGE(PG8_SA(1, 1), a1 + hstep, voffA);
;             PG8_WAIT_V(8); PG8_WAIT_L(0); PG8_BAR; PG8_MMA(0, 0, At, B0); PG8_MMA(0, 1, At, B1); PG8_BAR; PG8_SCHED;
;             PG8_LDA(At, 0, 1); PG8_STAGE(PG8_SB(0, 0), b2, voffB); PG8_STAGE(PG8_SB(0, 1), b2 + hstep, voffB); PG8_STAGE(PG8_SA(0, 0), a2, voffA);
.LBB0_560:
	ds_read_b128 v[128:131], v206
	ds_read_b128 v[132:135], v206 offset:1024
	ds_read_b128 v[136:139], v206 offset:2048
	ds_read_b128 v[140:143], v206 offset:3072
	ds_read_b128 v[144:147], v207
	ds_read_b128 v[148:151], v207 offset:1024
	ds_read_b128 v[152:155], v207 offset:2048
	ds_read_b128 v[156:159], v207 offset:3072
	s_add_u32 s28, s26, 0xfff80080
	s_addc_u32 s29, s27, -1
	s_cmp_eq_u32 s58, 28
	s_cselect_b32 s31, s53, s29
	s_cselect_b32 s30, s54, s28
	s_cselect_b32 s29, s9, s57
	s_cselect_b32 s28, s55, s56
	v_lshl_add_u64 v[214:215], s[26:27], 0, v[184:185]
	s_add_i32 m0, s38, 0xc000
	ds_read_b128 v[160:163], v208
	ds_read_b128 v[164:167], v208 offset:1024
	ds_read_b128 v[168:171], v208 offset:2048
	ds_read_b128 v[172:175], v208 offset:3072
	ds_read_b128 v[188:191], v208 offset:4096
	ds_read_b128 v[192:195], v208 offset:5120
	ds_read_b128 v[196:199], v208 offset:6144
	ds_read_b128 v[210:213], v208 offset:7168
	global_load_lds_dwordx4 v[214:215], off
	v_lshl_add_u64 v[214:215], s[26:27], 0, v[186:187]
	s_add_i32 m0, s38, 0xe000
	s_nop 0
	global_load_lds_dwordx4 v[214:215], off
	s_waitcnt vmcnt(8)
	s_waitcnt lgkmcnt(0)
	s_barrier
	s_setprio 0
	s_waitcnt lgkmcnt(0)
	v_mfma_f32_16x16x32_bf16 v[124:127], v[128:131], v[160:163], v[124:127]
	v_mfma_f32_16x16x32_bf16 v[120:123], v[136:139], v[160:163], v[120:123]
	v_mfma_f32_16x16x32_bf16 v[108:111], v[128:131], v[168:171], v[108:111]
	v_mfma_f32_16x16x32_bf16 v[104:107], v[136:139], v[168:171], v[104:107]
	v_mfma_f32_16x16x32_bf16 v[92:95], v[128:131], v[188:191], v[92:95]
	v_mfma_f32_16x16x32_bf16 v[88:91], v[136:139], v[188:191], v[88:91]
	v_mfma_f32_16x16x32_bf16 v[76:79], v[128:131], v[196:199], v[76:79]
	v_mfma_f32_16x16x32_bf16 v[72:75], v[136:139], v[196:199], v[72:75]
	v_mfma_f32_16x16x32_bf16 v[124:127], v[132:135], v[164:167], v[124:127]
	v_mfma_f32_16x16x32_bf16 v[120:123], v[140:143], v[164:167], v[120:123]
	v_mfma_f32_16x16x32_bf16 v[108:111], v[132:135], v[172:175], v[108:111]
	v_mfma_f32_16x16x32_bf16 v[104:107], v[140:143], v[172:175], v[104:107]
	v_mfma_f32_16x16x32_bf16 v[92:95], v[132:135], v[192:195], v[92:95]
	v_mfma_f32_16x16x32_bf16 v[88:91], v[140:143], v[192:195], v[88:91]
	v_mfma_f32_16x16x32_bf16 v[76:79], v[132:135], v[210:213], v[76:79]
	v_mfma_f32_16x16x32_bf16 v[72:75], v[140:143], v[210:213], v[72:75]
	v_mfma_f32_16x16x32_bf16 v[116:119], v[144:147], v[160:163], v[116:119]
	v_mfma_f32_16x16x32_bf16 v[112:115], v[152:155], v[160:163], v[112:115]
	v_mfma_f32_16x16x32_bf16 v[100:103], v[144:147], v[168:171], v[100:103]
	v_mfma_f32_16x16x32_bf16 v[96:99], v[152:155], v[168:171], v[96:99]
	v_mfma_f32_16x16x32_bf16 v[84:87], v[144:147], v[188:191], v[84:87]
	v_mfma_f32_16x16x32_bf16 v[80:83], v[152:155], v[188:191], v[80:83]
	v_mfma_f32_16x16x32_bf16 v[68:71], v[144:147], v[196:199], v[68:71]
	v_mfma_f32_16x16x32_bf16 v[64:67], v[152:155], v[196:199], v[64:67]
	v_mfma_f32_16x16x32_bf16 v[116:119], v[148:151], v[164:167], v[116:119]
	v_mfma_f32_16x16x32_bf16 v[112:115], v[156:159], v[164:167], v[112:115]
	v_mfma_f32_16x16x32_bf16 v[100:103], v[148:151], v[172:175], v[100:103]
	v_mfma_f32_16x16x32_bf16 v[96:99], v[156:159], v[172:175], v[96:99]
	v_mfma_f32_16x16x32_bf16 v[84:87], v[148:151], v[192:195], v[84:87]
	v_mfma_f32_16x16x32_bf16 v[80:83], v[156:159], v[192:195], v[80:83]
	v_mfma_f32_16x16x32_bf16 v[68:71], v[148:151], v[210:213], v[68:71]
	v_mfma_f32_16x16x32_bf16 v[64:67], v[156:159], v[210:213], v[64:67]
	s_setprio 1
	s_barrier
	s_add_i32 s46, s44, s37
	v_lshl_add_u64 v[214:215], s[28:29], 0, v[178:179]
	s_mov_b32 m0, s46
	ds_read_b128 v[160:163], v208 offset:16384
	ds_read_b128 v[164:167], v208 offset:17408
	ds_read_b128 v[168:171], v208 offset:18432
	ds_read_b128 v[172:175], v208 offset:19456
	ds_read_b128 v[188:191], v208 offset:20480
	ds_read_b128 v[192:195], v208 offset:21504
	ds_read_b128 v[196:199], v208 offset:22528
	ds_read_b128 v[210:213], v208 offset:23552
	global_load_lds_dwordx4 v[214:215], off
	s_add_i32 m0, s46, 0x2000
	s_add_u32 s46, s28, 0x80000
	v_lshl_add_u64 v[216:217], s[28:29], 0, v[182:183]
	s_addc_u32 s47, s29, 0
	s_add_i32 s59, s45, s37
	global_load_lds_dwordx4 v[216:217], off
	v_lshl_add_u64 v[218:219], s[46:47], 0, v[178:179]
	s_mov_b32 m0, s59
	v_lshl_add_u64 v[220:221], s[30:31], 0, v[180:181]
	global_load_lds_dwordx4 v[218:219], off
	v_lshl_add_u64 v[218:219], s[46:47], 0, v[182:183]
	s_add_i32 m0, s59, 0x2000
	s_nop 0
	global_load_lds_dwordx4 v[218:219], off
	v_lshl_add_u64 v[218:219], s[30:31], 0, v[176:177]
	s_mov_b32 m0, s38
	s_nop 0
	global_load_lds_dwordx4 v[218:219], off
	s_mov_b32 m0, s39
	s_nop 0
	global_load_lds_dwordx4 v[220:221], off
	s_waitcnt vmcnt(8)
	s_waitcnt lgkmcnt(0)
	s_barrier
; #define PG8_STAGE(bufoff, gbase, voff) do { _Pragma("unroll") for (int _i = 0; _i < 2; ++_i) \
;         __builtin_amdgcn_global_load_lds((const unsigned*)((const char*)(gbase) + (voff)[_i]), (LAS unsigned*)(lds + (bufoff) + ldsw + _i * 8192), 16, 0, 0); } while (0)
; #define PG8_LDA(dst, b, h) do { _Pragma("unroll") for (int m = 0; m < 4; ++m) _Pragma("unroll") for (int k = 0; k < 2; ++k) dst[m][k] = *(const LAS bf16x8*)(lds + PG8_SA(b, h) + aoff + m * 2048 + k * 1024); } while (0)
; #define PG8_LDB(dst, b, h) do { _Pragma("unroll") for (int n = 0; n < 2; ++n) _Pragma("unroll") for (int k = 0; k < 2; ++k) dst[n][k] = *(const LAS bf16x8*)(lds + PG8_SB(b, h) + boff + n * 2048 + k * 1024); } while (0)
; #define PG8_MMA(ai, bj, At, Bt) do { __builtin_amdgcn_s_setprio(1); _Pragma("unroll") for (int m = 0; m < 4; ++m) _Pragma("unroll") for (int n = 0; n < 2; ++n) _Pragma("unroll") for (int k = 0; k < 2; ++k) \
;         acc[ai][bj][m][n] = __builtin_amdgcn_mfma_f32_16x16x32_bf16(Bt[n][k], At[m][k], acc[ai][bj][m][n], 0, 0, 0); __builtin_amdgcn_s_setprio(0); } while (0)
; #define PG8_WAIT_V(n) asm volatile("s_waitcnt vmcnt(" #n ")" ::: "memory")
; #define PG8_WAIT_L(n) asm volatile("s_waitcnt lgkmcnt(" #n ")" ::: "memory")
; #define PG8_BAR __builtin_amdgcn_s_barrier()
; #define PG8_SCHED __builtin_amdgcn_sched_barrier(0)
; template <class Epi, class Sched, bool ALIGN_EPI = true>
; __device__ __forceinline__ void gemm_phase(LAS unsigned char* lds, const Gemm g, const Sched& S, const Epi& E) {
;     ...
;             PG8_WAIT_V(8); PG8_WAIT_L(0); PG8_BAR; PG8_MMA(1, 0, At, B0); PG8_MMA(1, 1, At, B1); PG8_BAR; PG8_SCHED;
;             PG8_LDB(B0, 1, 0); PG8_LDB(B1, 1, 1); PG8_SCHED; PG8_LDA(At, 1, 0); PG8_STAGE(PG8_SA(0, 1), a2 + hstep, voffA);
;             PG8_WAIT_V(8); PG8_WAIT_L(0); PG8_BAR; PG8_MMA(0, 0, At, B0); PG8_MMA(0, 1, At, B1); PG8_BAR; PG8_SCHED;
	s_setprio 0
	s_waitcnt lgkmcnt(0)
	v_mfma_f32_16x16x32_bf16 v[60:63], v[128:131], v[160:163], v[60:63]
	v_mfma_f32_16x16x32_bf16 v[56:59], v[136:139], v[160:163], v[56:59]
	v_mfma_f32_16x16x32_bf16 v[44:47], v[128:131], v[168:171], v[44:47]
	v_mfma_f32_16x16x32_bf16 v[40:43], v[136:139], v[168:171], v[40:43]
	v_mfma_f32_16x16x32_bf16 v[28:31], v[128:131], v[188:191], v[28:31]
	v_mfma_f32_16x16x32_bf16 v[24:27], v[136:139], v[188:191], v[24:27]
	v_mfma_f32_16x16x32_bf16 v[12:15], v[128:131], v[196:199], v[12:15]
	v_mfma_f32_16x16x32_bf16 v[8:11], v[136:139], v[196:199], v[8:11]
	v_mfma_f32_16x16x32_bf16 v[60:63], v[132:135], v[164:167], v[60:63]
	v_mfma_f32_16x16x32_bf16 v[56:59], v[140:143], v[164:167], v[56:59]
	v_mfma_f32_16x16x32_bf16 v[44:47], v[132:135], v[172:175], v[44:47]
	v_mfma_f32_16x16x32_bf16 v[40:43], v[140:143], v[172:175], v[40:43]
	v_mfma_f32_16x16x32_bf16 v[28:31], v[132:135], v[192:195], v[28:31]
	v_mfma_f32_16x16x32_bf16 v[24:27], v[140:143], v[192:195], v[24:27]
	v_mfma_f32_16x16x32_bf16 v[12:15], v[132:135], v[210:213], v[12:15]
	v_mfma_f32_16x16x32_bf16 v[8:11], v[140:143], v[210:213], v[8:11]
	v_mfma_f32_16x16x32_bf16 v[52:55], v[144:147], v[160:163], v[52:55]
	v_mfma_f32_16x16x32_bf16 v[48:51], v[152:155], v[160:163], v[48:51]
	v_mfma_f32_16x16x32_bf16 v[36:39], v[144:147], v[168:171], v[36:39]
	v_mfma_f32_16x16x32_bf16 v[32:35], v[152:155], v[168:171], v[32:35]
	v_mfma_f32_16x16x32_bf16 v[20:23], v[144:147], v[188:191], v[20:23]
	v_mfma_f32_16x16x32_bf16 v[16:19], v[152:155], v[188:191], v[16:19]
	v_mfma_f32_16x16x32_bf16 v[4:7], v[144:147], v[196:199], v[4:7]
	v_mfma_f32_16x16x32_bf16 v[0:3], v[152:155], v[196:199], v[0:3]
	v_mfma_f32_16x16x32_bf16 v[52:55], v[148:151], v[164:167], v[52:55]
	v_mfma_f32_16x16x32_bf16 v[48:51], v[156:159], v[164:167], v[48:51]
	v_mfma_f32_16x16x32_bf16 v[36:39], v[148:151], v[172:175], v[36:39]
	v_mfma_f32_16x16x32_bf16 v[32:35], v[156:159], v[172:175], v[32:35]
	v_mfma_f32_16x16x32_bf16 v[20:23], v[148:151], v[192:195], v[20:23]
	v_mfma_f32_16x16x32_bf16 v[16:19], v[156:159], v[192:195], v[16:19]
	v_mfma_f32_16x16x32_bf16 v[4:7], v[148:151], v[210:213], v[4:7]
	v_mfma_f32_16x16x32_bf16 v[0:3], v[156:159], v[210:213], v[0:3]
	s_setprio 1
	s_barrier
	s_add_i32 s46, 0, 0x18000
	s_add_i32 s47, 0, 0x1c000
	v_add_u32_e32 v140, s46, v204
	v_add_u32_e32 v156, s47, v204
	ds_read_b128 v[128:131], v140
	ds_read_b128 v[132:135], v140 offset:1024
	ds_read_b128 v[136:139], v140 offset:2048
	ds_read_b128 v[140:143], v140 offset:3072
	ds_read_b128 v[144:147], v156
	ds_read_b128 v[148:151], v156 offset:1024
	ds_read_b128 v[152:155], v156 offset:2048
	ds_read_b128 v[156:159], v156 offset:3072
	s_add_u32 s30, s30, 0x80000
	s_addc_u32 s31, s31, 0
	s_mov_b32 m0, s40
	v_lshl_add_u64 v[222:223], s[30:31], 0, v[176:177]
	ds_read_b128 v[160:163], v208 offset:32768
	ds_read_b128 v[164:167], v208 offset:33792
	ds_read_b128 v[168:171], v208 offset:34816
	ds_read_b128 v[172:175], v208 offset:35840
	ds_read_b128 v[188:191], v208 offset:36864
	ds_read_b128 v[192:195], v208 offset:37888
	ds_read_b128 v[196:199], v208 offset:38912
	ds_read_b128 v[210:213], v208 offset:39936
	global_load_lds_dwordx4 v[222:223], off
	v_lshl_add_u64 v[222:223], s[30:31], 0, v[180:181]
	s_mov_b32 m0, s41
	s_nop 0
	global_load_lds_dwordx4 v[222:223], off
	s_waitcnt vmcnt(8)
	s_waitcnt lgkmcnt(0)
	s_barrier
	s_setprio 0
	s_waitcnt lgkmcnt(0)
	v_mfma_f32_16x16x32_bf16 v[124:127], v[128:131], v[160:163], v[124:127]
	v_mfma_f32_16x16x32_bf16 v[120:123], v[136:139], v[160:163], v[120:123]
	v_mfma_f32_16x16x32_bf16 v[108:111], v[128:131], v[168:171], v[108:111]
	v_mfma_f32_16x16x32_bf16 v[104:107], v[136:139], v[168:171], v[104:107]
	v_mfma_f32_16x16x32_bf16 v[92:95], v[128:131], v[188:191], v[92:95]
	v_mfma_f32_16x16x32_bf16 v[88:91], v[136:139], v[188:191], v[88:91]
	v_mfma_f32_16x16x32_bf16 v[76:79], v[128:131], v[196:199], v[76:79]
	v_mfma_f32_16x16x32_bf16 v[72:75], v[136:139], v[196:199], v[72:75]
	v_mfma_f32_16x16x32_bf16 v[124:127], v[132:135], v[164:167], v[124:127]
	v_mfma_f32_16x16x32_bf16 v[120:123], v[140:143], v[164:167], v[120:123]
	v_mfma_f32_16x16x32_bf16 v[108:111], v[132:135], v[172:175], v[108:111]
	v_mfma_f32_16x16x32_bf16 v[104:107], v[140:143], v[172:175], v[104:107]
	v_mfma_f32_16x16x32_bf16 v[92:95], v[132:135], v[192:195], v[92:95]
	v_mfma_f32_16x16x32_bf16 v[88:91], v[140:143], v[192:195], v[88:91]
	v_mfma_f32_16x16x32_bf16 v[76:79], v[132:135], v[210:213], v[76:79]
	v_mfma_f32_16x16x32_bf16 v[72:75], v[140:143], v[210:213], v[72:75]
	v_mfma_f32_16x16x32_bf16 v[116:119], v[144:147], v[160:163], v[116:119]
	v_mfma_f32_16x16x32_bf16 v[112:115], v[152:155], v[160:163], v[112:115]
	v_mfma_f32_16x16x32_bf16 v[100:103], v[144:147], v[168:171], v[100:103]
	v_mfma_f32_16x16x32_bf16 v[96:99], v[152:155], v[168:171], v[96:99]
	v_mfma_f32_16x16x32_bf16 v[84:87], v[144:147], v[188:191], v[84:87]
	v_mfma_f32_16x16x32_bf16 v[80:83], v[152:155], v[188:191], v[80:83]
	v_mfma_f32_16x16x32_bf16 v[68:71], v[144:147], v[196:199], v[68:71]
	v_mfma_f32_16x16x32_bf16 v[64:67], v[152:155], v[196:199], v[64:67]
	v_mfma_f32_16x16x32_bf16 v[116:119], v[148:151], v[164:167], v[116:119]
	v_mfma_f32_16x16x32_bf16 v[112:115], v[156:159], v[164:167], v[112:115]
	v_mfma_f32_16x16x32_bf16 v[100:103], v[148:151], v[172:175], v[100:103]
	v_mfma_f32_16x16x32_bf16 v[96:99], v[156:159], v[172:175], v[96:99]
	v_mfma_f32_16x16x32_bf16 v[84:87], v[148:151], v[192:195], v[84:87]
	v_mfma_f32_16x16x32_bf16 v[80:83], v[156:159], v[192:195], v[80:83]
	v_mfma_f32_16x16x32_bf16 v[68:71], v[148:151], v[210:213], v[68:71]
	v_mfma_f32_16x16x32_bf16 v[64:67], v[156:159], v[210:213], v[64:67]
	s_setprio 1
	s_barrier
; #define PG8_STAGE(bufoff, gbase, voff) do { _Pragma("unroll") for (int _i = 0; _i < 2; ++_i) \
;         __builtin_amdgcn_global_load_lds((const unsigned*)((const char*)(gbase) + (voff)[_i]), (LAS unsigned*)(lds + (bufoff) + ldsw + _i * 8192), 16, 0, 0); } while (0)
; #define PG8_LDA(dst, b, h) do { _Pragma("unroll") for (int m = 0; m < 4; ++m) _Pragma("unroll") for (int k = 0; k < 2; ++k) dst[m][k] = *(const LAS bf16x8*)(lds + PG8_SA(b, h) + aoff + m * 2048 + k * 1024); } while (0)
; #define PG8_MMA(ai, bj, At, Bt) do { __builtin_amdgcn_s_setprio(1); _Pragma("unroll") for (int m = 0; m < 4; ++m) _Pragma("unroll") for (int n = 0; n < 2; ++n) _Pragma("unroll") for (int k = 0; k < 2; ++k) \
;         acc[ai][bj][m][n] = __builtin_amdgcn_mfma_f32_16x16x32_bf16(Bt[n][k], At[m][k], acc[ai][bj][m][n], 0, 0, 0); __builtin_amdgcn_s_setprio(0); } while (0)
; #define PG8_WAIT_V(n) asm volatile("s_waitcnt vmcnt(" #n ")" ::: "memory")
; #define PG8_WAIT_L(n) asm volatile("s_waitcnt lgkmcnt(" #n ")" ::: "memory")
; #define PG8_BAR __builtin_amdgcn_s_barrier()
; #define PG8_SCHED __builtin_amdgcn_sched_barrier(0)
; template <class Epi, class Sched, bool ALIGN_EPI = true>
; __device__ __forceinline__ void gemm_phase(LAS unsigned char* lds, const Gemm g, const Sched& S, const Epi& E) {
;     ...
;             PG8_LDA(At, 1, 1); PG8_STAGE(PG8_SB(1, 0), b3, voffB); PG8_STAGE(PG8_SB(1, 1), b3 + hstep, voffB); PG8_STAGE(PG8_SA(1, 0), a3, voffA);
;             PG8_WAIT_V(8); PG8_WAIT_L(0); PG8_BAR; PG8_MMA(1, 0, At, B0); PG8_MMA(1, 1, At, B1); PG8_BAR; PG8_SCHED;
;         }
;         if constexpr (ALIGN_EPI) { if (wr == 0) PG8_BAR; }
	s_add_i32 s30, s46, s37
	v_lshl_add_u64 v[214:215], v[214:215], 0, s[20:21]
	s_mov_b32 m0, s30
	ds_read_b128 v[160:163], v208 offset:49152
	ds_read_b128 v[164:167], v208 offset:50176
	ds_read_b128 v[168:171], v208 offset:51200
	ds_read_b128 v[172:175], v208 offset:52224
	ds_read_b128 v[188:191], v208 offset:53248
	ds_read_b128 v[192:195], v208 offset:54272
	ds_read_b128 v[196:199], v208 offset:55296
	ds_read_b128 v[210:213], v208 offset:56320
	global_load_lds_dwordx4 v[214:215], off
	s_add_i32 m0, s30, 0x2000
	s_add_u32 s28, s28, 0x80080
	v_lshl_add_u64 v[214:215], v[216:217], 0, s[20:21]
	s_addc_u32 s29, s29, 0
	s_add_i32 s30, s47, s37
	global_load_lds_dwordx4 v[214:215], off
	v_lshl_add_u64 v[214:215], s[28:29], 0, v[178:179]
	s_mov_b32 m0, s30
	s_nop 0
	global_load_lds_dwordx4 v[214:215], off
	v_lshl_add_u64 v[214:215], s[28:29], 0, v[182:183]
	s_add_i32 m0, s30, 0x2000
	s_nop 0
	global_load_lds_dwordx4 v[214:215], off
	v_lshl_add_u64 v[214:215], v[218:219], 0, s[20:21]
	s_mov_b32 m0, s42
	s_nop 0
	global_load_lds_dwordx4 v[214:215], off
	v_lshl_add_u64 v[214:215], v[220:221], 0, s[20:21]
	s_mov_b32 m0, s43
	s_nop 0
	global_load_lds_dwordx4 v[214:215], off
	s_waitcnt vmcnt(8)
	s_waitcnt lgkmcnt(0)
	s_barrier
	s_setprio 0
	s_waitcnt lgkmcnt(0)
	v_mfma_f32_16x16x32_bf16 v[60:63], v[128:131], v[160:163], v[60:63]
	v_mfma_f32_16x16x32_bf16 v[56:59], v[136:139], v[160:163], v[56:59]
	v_mfma_f32_16x16x32_bf16 v[44:47], v[128:131], v[168:171], v[44:47]
	v_mfma_f32_16x16x32_bf16 v[40:43], v[136:139], v[168:171], v[40:43]
	v_mfma_f32_16x16x32_bf16 v[28:31], v[128:131], v[188:191], v[28:31]
	v_mfma_f32_16x16x32_bf16 v[24:27], v[136:139], v[188:191], v[24:27]
	v_mfma_f32_16x16x32_bf16 v[12:15], v[128:131], v[196:199], v[12:15]
	v_mfma_f32_16x16x32_bf16 v[8:11], v[136:139], v[196:199], v[8:11]
	v_mfma_f32_16x16x32_bf16 v[60:63], v[132:135], v[164:167], v[60:63]
	v_mfma_f32_16x16x32_bf16 v[56:59], v[140:143], v[164:167], v[56:59]
	v_mfma_f32_16x16x32_bf16 v[44:47], v[132:135], v[172:175], v[44:47]
	v_mfma_f32_16x16x32_bf16 v[40:43], v[140:143], v[172:175], v[40:43]
	v_mfma_f32_16x16x32_bf16 v[28:31], v[132:135], v[192:195], v[28:31]
	v_mfma_f32_16x16x32_bf16 v[24:27], v[140:143], v[192:195], v[24:27]
	v_mfma_f32_16x16x32_bf16 v[12:15], v[132:135], v[210:213], v[12:15]
	v_mfma_f32_16x16x32_bf16 v[8:11], v[140:143], v[210:213], v[8:11]
	v_mfma_f32_16x16x32_bf16 v[52:55], v[144:147], v[160:163], v[52:55]
	v_mfma_f32_16x16x32_bf16 v[48:51], v[152:155], v[160:163], v[48:51]
	v_mfma_f32_16x16x32_bf16 v[36:39], v[144:147], v[168:171], v[36:39]
	v_mfma_f32_16x16x32_bf16 v[32:35], v[152:155], v[168:171], v[32:35]
	v_mfma_f32_16x16x32_bf16 v[20:23], v[144:147], v[188:191], v[20:23]
	v_mfma_f32_16x16x32_bf16 v[16:19], v[152:155], v[188:191], v[16:19]
	v_mfma_f32_16x16x32_bf16 v[4:7], v[144:147], v[196:199], v[4:7]
	v_mfma_f32_16x16x32_bf16 v[0:3], v[152:155], v[196:199], v[0:3]
	v_mfma_f32_16x16x32_bf16 v[52:55], v[148:151], v[164:167], v[52:55]
	v_mfma_f32_16x16x32_bf16 v[48:51], v[156:159], v[164:167], v[48:51]
	v_mfma_f32_16x16x32_bf16 v[36:39], v[148:151], v[172:175], v[36:39]
	v_mfma_f32_16x16x32_bf16 v[32:35], v[156:159], v[172:175], v[32:35]
	v_mfma_f32_16x16x32_bf16 v[20:23], v[148:151], v[192:195], v[20:23]
	v_mfma_f32_16x16x32_bf16 v[16:19], v[156:159], v[192:195], v[16:19]
	v_mfma_f32_16x16x32_bf16 v[4:7], v[148:151], v[210:213], v[4:7]
	v_mfma_f32_16x16x32_bf16 v[0:3], v[156:159], v[210:213], v[0:3]
	s_setprio 1
	s_barrier
	s_add_i32 s58, s58, 2
	s_add_u32 s26, s26, 0x100
	s_addc_u32 s27, s27, 0
	s_add_u32 s56, s56, 0x100
	s_addc_u32 s57, s57, 0
	s_cmp_gt_u32 s58, 29
	s_cbranch_scc0 .LBB0_560
	s_and_b64 vcc, exec, s[22:23]
	s_cbranch_vccz .LBB0_563
	s_barrier

; #define PG8_STAGE(bufoff, gbase, voff) do { _Pragma("unroll") for (int _i = 0; _i < 2; ++_i) \
;         __builtin_amdgcn_global_load_lds((const unsigned*)((const char*)(gbase) + (voff)[_i]), (LAS unsigned*)(lds + (bufoff) + ldsw + _i * 8192), 16, 0, 0); } while (0)
; #define PG8_LDA(dst, b, h) do { _Pragma("unroll") for (int m = 0; m < 4; ++m) _Pragma("unroll") for (int k = 0; k < 2; ++k) dst[m][k] = *(const LAS bf16x8*)(lds + PG8_SA(b, h) + aoff + m * 2048 + k * 1024); } while (0)
; #define PG8_LDB(dst, b, h) do { _Pragma("unroll") for (int n = 0; n < 2; ++n) _Pragma("unroll") for (int k = 0; k < 2; ++k) dst[n][k] = *(const LAS bf16x8*)(lds + PG8_SB(b, h) + boff + n * 2048 + k * 1024); } while (0)
; #define PG8_MMA(ai, bj, At, Bt) do { __builtin_amdgcn_s_setprio(1); _Pragma("unroll") for (int m = 0; m < 4; ++m) _Pragma("unroll") for (int n = 0; n < 2; ++n) _Pragma("unroll") for (int k = 0; k < 2; ++k) \
;         acc[ai][bj][m][n] = __builtin_amdgcn_mfma_f32_16x16x32_bf16(Bt[n][k], At[m][k], acc[ai][bj][m][n], 0, 0, 0); __builtin_amdgcn_s_setprio(0); } while (0)
; #define PG8_WAIT_V(n) asm volatile("s_waitcnt vmcnt(" #n ")" ::: "memory")
; #define PG8_WAIT_L(n) asm volatile("s_waitcnt lgkmcnt(" #n ")" ::: "memory")
; #define PG8_BAR __builtin_amdgcn_s_barrier()
; #define PG8_SCHED __builtin_amdgcn_sched_barrier(0)
; template <class Epi, class Sched, bool ALIGN_EPI = true>
; __device__ __forceinline__ void gemm_phase(LAS unsigned char* lds, const Gemm g, const Sched& S, const Epi& E) {
;     ...
;         for (int t = 0; t < nt; t += 2) {
;             const bool last = (t == nt - 2);
;             const char* a1 = cA + (size_t)(t + 1) * kstep;
;             const char* a2 = last ? nA : cA + (size_t)(t + 2) * kstep; const char* b2 = last ? nB : cB + (size_t)(t + 2) * kstep;
;             const char* a3 = a2 + kstep; const char* b3 = b2 + kstep;
;             PG8_LDB(B0, 0, 0); PG8_LDB(B1, 0, 1); PG8_SCHED; PG8_LDA(At, 0, 0); PG8_STAGE(PG8_SA(1, 1), a1 + hstep, voffA);
;             PG8_WAIT_V(8); PG8_WAIT_L(0); PG8_BAR; PG8_MMA(0, 0, At, B0); PG8_MMA(0, 1, At, B1); PG8_BAR; PG8_SCHED;
;             PG8_LDA(At, 0, 1); PG8_STAGE(PG8_SB(0, 0), b2, voffB); PG8_STAGE(PG8_SB(0, 1), b2 + hstep, voffB); PG8_STAGE(PG8_SA(0, 0), a2, voffA);
.LBB0_647:
	ds_read_b128 v[152:155], v147
	ds_read_b128 v[156:159], v147 offset:1024
	ds_read_b128 v[160:163], v147 offset:2048
	ds_read_b128 v[164:167], v147 offset:3072
	ds_read_b128 v[168:171], v148
	ds_read_b128 v[172:175], v148 offset:1024
	ds_read_b128 v[176:179], v148 offset:2048
	ds_read_b128 v[180:183], v148 offset:3072
	s_add_u32 s26, s24, 0xfff80080
	s_addc_u32 s27, s25, -1
	s_cmp_eq_u32 s56, 28
	s_cselect_b32 s29, s51, s27
	s_cselect_b32 s28, s52, s26
	s_cselect_b32 s27, s7, s55
	s_cselect_b32 s26, s53, s54
	v_lshl_add_u64 v[140:141], s[24:25], 0, v[136:137]
	s_add_i32 m0, s37, 0xc000
	ds_read_b128 v[184:187], v149
	ds_read_b128 v[188:191], v149 offset:1024
	ds_read_b128 v[192:195], v149 offset:2048
	ds_read_b128 v[196:199], v149 offset:3072
	ds_read_b128 v[204:207], v149 offset:4096
	ds_read_b128 v[208:211], v149 offset:5120
	ds_read_b128 v[212:215], v149 offset:6144
	ds_read_b128 v[216:219], v149 offset:7168
	global_load_lds_dwordx4 v[140:141], off
	v_lshl_add_u64 v[140:141], s[24:25], 0, v[138:139]
	s_add_i32 m0, s37, 0xe000
	s_nop 0
	global_load_lds_dwordx4 v[140:141], off
	s_waitcnt vmcnt(8)
	s_waitcnt lgkmcnt(0)
	s_barrier
	s_setprio 0
	s_waitcnt lgkmcnt(0)
	v_mfma_f32_16x16x32_bf16 v[112:115], v[152:155], v[184:187], v[112:115]
	v_mfma_f32_16x16x32_bf16 v[108:111], v[160:163], v[184:187], v[108:111]
	v_mfma_f32_16x16x32_bf16 v[100:103], v[152:155], v[192:195], v[100:103]
	v_mfma_f32_16x16x32_bf16 v[96:99], v[160:163], v[192:195], v[96:99]
	v_mfma_f32_16x16x32_bf16 v[92:95], v[152:155], v[204:207], v[92:95]
	v_mfma_f32_16x16x32_bf16 v[84:87], v[160:163], v[204:207], v[84:87]
	v_mfma_f32_16x16x32_bf16 v[76:79], v[152:155], v[212:215], v[76:79]
	v_mfma_f32_16x16x32_bf16 v[68:71], v[160:163], v[212:215], v[68:71]
	v_mfma_f32_16x16x32_bf16 v[112:115], v[156:159], v[188:191], v[112:115]
	v_mfma_f32_16x16x32_bf16 v[108:111], v[164:167], v[188:191], v[108:111]
	v_mfma_f32_16x16x32_bf16 v[100:103], v[156:159], v[196:199], v[100:103]
	v_mfma_f32_16x16x32_bf16 v[96:99], v[164:167], v[196:199], v[96:99]
	v_mfma_f32_16x16x32_bf16 v[92:95], v[156:159], v[208:211], v[92:95]
	v_mfma_f32_16x16x32_bf16 v[84:87], v[164:167], v[208:211], v[84:87]
	v_mfma_f32_16x16x32_bf16 v[76:79], v[156:159], v[216:219], v[76:79]
	v_mfma_f32_16x16x32_bf16 v[68:71], v[164:167], v[216:219], v[68:71]
	v_mfma_f32_16x16x32_bf16 v[124:127], v[168:171], v[184:187], v[124:127]
	v_mfma_f32_16x16x32_bf16 v[120:123], v[176:179], v[184:187], v[120:123]
	v_mfma_f32_16x16x32_bf16 v[116:119], v[168:171], v[192:195], v[116:119]
	v_mfma_f32_16x16x32_bf16 v[104:107], v[176:179], v[192:195], v[104:107]
	v_mfma_f32_16x16x32_bf16 v[88:91], v[168:171], v[204:207], v[88:91]
	v_mfma_f32_16x16x32_bf16 v[80:83], v[176:179], v[204:207], v[80:83]
	v_mfma_f32_16x16x32_bf16 v[72:75], v[168:171], v[212:215], v[72:75]
	v_mfma_f32_16x16x32_bf16 v[64:67], v[176:179], v[212:215], v[64:67]
	v_mfma_f32_16x16x32_bf16 v[124:127], v[172:175], v[188:191], v[124:127]
	v_mfma_f32_16x16x32_bf16 v[120:123], v[180:183], v[188:191], v[120:123]
	v_mfma_f32_16x16x32_bf16 v[116:119], v[172:175], v[196:199], v[116:119]
	v_mfma_f32_16x16x32_bf16 v[104:107], v[180:183], v[196:199], v[104:107]
	v_mfma_f32_16x16x32_bf16 v[88:91], v[172:175], v[208:211], v[88:91]
	v_mfma_f32_16x16x32_bf16 v[80:83], v[180:183], v[208:211], v[80:83]
	v_mfma_f32_16x16x32_bf16 v[72:75], v[172:175], v[216:219], v[72:75]
	v_mfma_f32_16x16x32_bf16 v[64:67], v[180:183], v[216:219], v[64:67]
	s_setprio 1
	s_barrier
	s_add_i32 s46, s43, s36
	v_lshl_add_u64 v[140:141], s[26:27], 0, v[130:131]
	s_mov_b32 m0, s46
	ds_read_b128 v[184:187], v149 offset:16384
	ds_read_b128 v[188:191], v149 offset:17408
	ds_read_b128 v[192:195], v149 offset:18432
	ds_read_b128 v[196:199], v149 offset:19456
	ds_read_b128 v[204:207], v149 offset:20480
	ds_read_b128 v[208:211], v149 offset:21504
	ds_read_b128 v[212:215], v149 offset:22528
	ds_read_b128 v[216:219], v149 offset:23552
	global_load_lds_dwordx4 v[140:141], off
	s_add_i32 m0, s46, 0x2000
	s_add_u32 s46, s26, 0x80000
	v_lshl_add_u64 v[200:201], s[26:27], 0, v[134:135]
	s_addc_u32 s47, s27, 0
	s_add_i32 s57, s44, s36
	global_load_lds_dwordx4 v[200:201], off
	v_lshl_add_u64 v[220:221], s[46:47], 0, v[130:131]
	s_mov_b32 m0, s57
	v_lshl_add_u64 v[222:223], s[28:29], 0, v[132:133]
	global_load_lds_dwordx4 v[220:221], off
	v_lshl_add_u64 v[220:221], s[46:47], 0, v[134:135]
	s_add_i32 m0, s57, 0x2000
	s_nop 0
	global_load_lds_dwordx4 v[220:221], off
	v_lshl_add_u64 v[220:221], s[28:29], 0, v[128:129]
	s_mov_b32 m0, s37
	s_nop 0
	global_load_lds_dwordx4 v[220:221], off
	s_mov_b32 m0, s38
	s_nop 0
	global_load_lds_dwordx4 v[222:223], off
	s_waitcnt vmcnt(8)
	s_waitcnt lgkmcnt(0)
	s_barrier
; #define PG8_STAGE(bufoff, gbase, voff) do { _Pragma("unroll") for (int _i = 0; _i < 2; ++_i) \
;         __builtin_amdgcn_global_load_lds((const unsigned*)((const char*)(gbase) + (voff)[_i]), (LAS unsigned*)(lds + (bufoff) + ldsw + _i * 8192), 16, 0, 0); } while (0)
; #define PG8_LDA(dst, b, h) do { _Pragma("unroll") for (int m = 0; m < 4; ++m) _Pragma("unroll") for (int k = 0; k < 2; ++k) dst[m][k] = *(const LAS bf16x8*)(lds + PG8_SA(b, h) + aoff + m * 2048 + k * 1024); } while (0)
; #define PG8_LDB(dst, b, h) do { _Pragma("unroll") for (int n = 0; n < 2; ++n) _Pragma("unroll") for (int k = 0; k < 2; ++k) dst[n][k] = *(const LAS bf16x8*)(lds + PG8_SB(b, h) + boff + n * 2048 + k * 1024); } while (0)
; #define PG8_MMA(ai, bj, At, Bt) do { __builtin_amdgcn_s_setprio(1); _Pragma("unroll") for (int m = 0; m < 4; ++m) _Pragma("unroll") for (int n = 0; n < 2; ++n) _Pragma("unroll") for (int k = 0; k < 2; ++k) \
;         acc[ai][bj][m][n] = __builtin_amdgcn_mfma_f32_16x16x32_bf16(Bt[n][k], At[m][k], acc[ai][bj][m][n], 0, 0, 0); __builtin_amdgcn_s_setprio(0); } while (0)
; #define PG8_WAIT_V(n) asm volatile("s_waitcnt vmcnt(" #n ")" ::: "memory")
; #define PG8_WAIT_L(n) asm volatile("s_waitcnt lgkmcnt(" #n ")" ::: "memory")
; #define PG8_BAR __builtin_amdgcn_s_barrier()
; #define PG8_SCHED __builtin_amdgcn_sched_barrier(0)
; template <class Epi, class Sched, bool ALIGN_EPI = true>
; __device__ __forceinline__ void gemm_phase(LAS unsigned char* lds, const Gemm g, const Sched& S, const Epi& E) {
;     ...
;             PG8_WAIT_V(8); PG8_WAIT_L(0); PG8_BAR; PG8_MMA(1, 0, At, B0); PG8_MMA(1, 1, At, B1); PG8_BAR; PG8_SCHED;
;             PG8_LDB(B0, 1, 0); PG8_LDB(B1, 1, 1); PG8_SCHED; PG8_LDA(At, 1, 0); PG8_STAGE(PG8_SA(0, 1), a2 + hstep, voffA);
;             PG8_WAIT_V(8); PG8_WAIT_L(0); PG8_BAR; PG8_MMA(0, 0, At, B0); PG8_MMA(0, 1, At, B1); PG8_BAR; PG8_SCHED;
	s_setprio 0
	s_waitcnt lgkmcnt(0)
	v_mfma_f32_16x16x32_bf16 v[60:63], v[152:155], v[184:187], v[60:63]
	v_mfma_f32_16x16x32_bf16 v[52:55], v[160:163], v[184:187], v[52:55]
	v_mfma_f32_16x16x32_bf16 v[44:47], v[152:155], v[192:195], v[44:47]
	v_mfma_f32_16x16x32_bf16 v[36:39], v[160:163], v[192:195], v[36:39]
	v_mfma_f32_16x16x32_bf16 v[28:31], v[152:155], v[204:207], v[28:31]
	v_mfma_f32_16x16x32_bf16 v[20:23], v[160:163], v[204:207], v[20:23]
	v_mfma_f32_16x16x32_bf16 v[12:15], v[152:155], v[212:215], v[12:15]
	v_mfma_f32_16x16x32_bf16 v[4:7], v[160:163], v[212:215], v[4:7]
	v_mfma_f32_16x16x32_bf16 v[60:63], v[156:159], v[188:191], v[60:63]
	v_mfma_f32_16x16x32_bf16 v[52:55], v[164:167], v[188:191], v[52:55]
	v_mfma_f32_16x16x32_bf16 v[44:47], v[156:159], v[196:199], v[44:47]
	v_mfma_f32_16x16x32_bf16 v[36:39], v[164:167], v[196:199], v[36:39]
	v_mfma_f32_16x16x32_bf16 v[28:31], v[156:159], v[208:211], v[28:31]
	v_mfma_f32_16x16x32_bf16 v[20:23], v[164:167], v[208:211], v[20:23]
	v_mfma_f32_16x16x32_bf16 v[12:15], v[156:159], v[216:219], v[12:15]
	v_mfma_f32_16x16x32_bf16 v[4:7], v[164:167], v[216:219], v[4:7]
	v_mfma_f32_16x16x32_bf16 v[56:59], v[168:171], v[184:187], v[56:59]
	v_mfma_f32_16x16x32_bf16 v[48:51], v[176:179], v[184:187], v[48:51]
	v_mfma_f32_16x16x32_bf16 v[40:43], v[168:171], v[192:195], v[40:43]
	v_mfma_f32_16x16x32_bf16 v[32:35], v[176:179], v[192:195], v[32:35]
	v_mfma_f32_16x16x32_bf16 v[24:27], v[168:171], v[204:207], v[24:27]
	v_mfma_f32_16x16x32_bf16 v[16:19], v[176:179], v[204:207], v[16:19]
	v_mfma_f32_16x16x32_bf16 v[8:11], v[168:171], v[212:215], v[8:11]
	v_mfma_f32_16x16x32_bf16 v[0:3], v[176:179], v[212:215], v[0:3]
	v_mfma_f32_16x16x32_bf16 v[56:59], v[172:175], v[188:191], v[56:59]
	v_mfma_f32_16x16x32_bf16 v[48:51], v[180:183], v[188:191], v[48:51]
	v_mfma_f32_16x16x32_bf16 v[40:43], v[172:175], v[196:199], v[40:43]
	v_mfma_f32_16x16x32_bf16 v[32:35], v[180:183], v[196:199], v[32:35]
	v_mfma_f32_16x16x32_bf16 v[24:27], v[172:175], v[208:211], v[24:27]
	v_mfma_f32_16x16x32_bf16 v[16:19], v[180:183], v[208:211], v[16:19]
	v_mfma_f32_16x16x32_bf16 v[8:11], v[172:175], v[216:219], v[8:11]
	v_mfma_f32_16x16x32_bf16 v[0:3], v[180:183], v[216:219], v[0:3]
	s_setprio 1
	s_barrier
	s_add_i32 s46, 0, 0x18000
	v_add_u32_e32 v151, s46, v145
	s_add_i32 s47, 0, 0x1c000
	ds_read_b128 v[152:155], v151
	ds_read_b128 v[156:159], v151 offset:1024
	ds_read_b128 v[160:163], v151 offset:2048
	ds_read_b128 v[164:167], v151 offset:3072
	v_add_u32_e32 v151, s47, v145
	ds_read_b128 v[168:171], v151
	ds_read_b128 v[172:175], v151 offset:1024
	ds_read_b128 v[176:179], v151 offset:2048
	ds_read_b128 v[180:183], v151 offset:3072
	s_add_u32 s28, s28, 0x80000
	s_addc_u32 s29, s29, 0
	s_mov_b32 m0, s39
	v_lshl_add_u64 v[224:225], s[28:29], 0, v[128:129]
	ds_read_b128 v[184:187], v149 offset:32768
	ds_read_b128 v[188:191], v149 offset:33792
	ds_read_b128 v[192:195], v149 offset:34816
	ds_read_b128 v[196:199], v149 offset:35840
	ds_read_b128 v[204:207], v149 offset:36864
	ds_read_b128 v[208:211], v149 offset:37888
	ds_read_b128 v[212:215], v149 offset:38912
	ds_read_b128 v[216:219], v149 offset:39936
	global_load_lds_dwordx4 v[224:225], off
	v_lshl_add_u64 v[224:225], s[28:29], 0, v[132:133]
	s_mov_b32 m0, s40
	s_nop 0
	global_load_lds_dwordx4 v[224:225], off
	s_waitcnt vmcnt(8)
	s_waitcnt lgkmcnt(0)
	s_barrier
	s_setprio 0
	s_waitcnt lgkmcnt(0)
	v_mfma_f32_16x16x32_bf16 v[112:115], v[152:155], v[184:187], v[112:115]
	v_mfma_f32_16x16x32_bf16 v[108:111], v[160:163], v[184:187], v[108:111]
	v_mfma_f32_16x16x32_bf16 v[100:103], v[152:155], v[192:195], v[100:103]
	v_mfma_f32_16x16x32_bf16 v[96:99], v[160:163], v[192:195], v[96:99]
	v_mfma_f32_16x16x32_bf16 v[92:95], v[152:155], v[204:207], v[92:95]
	v_mfma_f32_16x16x32_bf16 v[84:87], v[160:163], v[204:207], v[84:87]
	v_mfma_f32_16x16x32_bf16 v[76:79], v[152:155], v[212:215], v[76:79]
	v_mfma_f32_16x16x32_bf16 v[68:71], v[160:163], v[212:215], v[68:71]
	v_mfma_f32_16x16x32_bf16 v[112:115], v[156:159], v[188:191], v[112:115]
	v_mfma_f32_16x16x32_bf16 v[108:111], v[164:167], v[188:191], v[108:111]
	v_mfma_f32_16x16x32_bf16 v[100:103], v[156:159], v[196:199], v[100:103]
	v_mfma_f32_16x16x32_bf16 v[96:99], v[164:167], v[196:199], v[96:99]
	v_mfma_f32_16x16x32_bf16 v[92:95], v[156:159], v[208:211], v[92:95]
	v_mfma_f32_16x16x32_bf16 v[84:87], v[164:167], v[208:211], v[84:87]
	v_mfma_f32_16x16x32_bf16 v[76:79], v[156:159], v[216:219], v[76:79]
	v_mfma_f32_16x16x32_bf16 v[68:71], v[164:167], v[216:219], v[68:71]
	v_mfma_f32_16x16x32_bf16 v[124:127], v[168:171], v[184:187], v[124:127]
	v_mfma_f32_16x16x32_bf16 v[120:123], v[176:179], v[184:187], v[120:123]
	v_mfma_f32_16x16x32_bf16 v[116:119], v[168:171], v[192:195], v[116:119]
	v_mfma_f32_16x16x32_bf16 v[104:107], v[176:179], v[192:195], v[104:107]
	v_mfma_f32_16x16x32_bf16 v[88:91], v[168:171], v[204:207], v[88:91]
	v_mfma_f32_16x16x32_bf16 v[80:83], v[176:179], v[204:207], v[80:83]
	v_mfma_f32_16x16x32_bf16 v[72:75], v[168:171], v[212:215], v[72:75]
	v_mfma_f32_16x16x32_bf16 v[64:67], v[176:179], v[212:215], v[64:67]
	v_mfma_f32_16x16x32_bf16 v[124:127], v[172:175], v[188:191], v[124:127]
	v_mfma_f32_16x16x32_bf16 v[120:123], v[180:183], v[188:191], v[120:123]
	v_mfma_f32_16x16x32_bf16 v[116:119], v[172:175], v[196:199], v[116:119]
	v_mfma_f32_16x16x32_bf16 v[104:107], v[180:183], v[196:199], v[104:107]
	v_mfma_f32_16x16x32_bf16 v[88:91], v[172:175], v[208:211], v[88:91]
	v_mfma_f32_16x16x32_bf16 v[80:83], v[180:183], v[208:211], v[80:83]
	v_mfma_f32_16x16x32_bf16 v[72:75], v[172:175], v[216:219], v[72:75]
	v_mfma_f32_16x16x32_bf16 v[64:67], v[180:183], v[216:219], v[64:67]
	s_setprio 1
	s_barrier
; #define PG8_STAGE(bufoff, gbase, voff) do { _Pragma("unroll") for (int _i = 0; _i < 2; ++_i) \
;         __builtin_amdgcn_global_load_lds((const unsigned*)((const char*)(gbase) + (voff)[_i]), (LAS unsigned*)(lds + (bufoff) + ldsw + _i * 8192), 16, 0, 0); } while (0)
; #define PG8_LDA(dst, b, h) do { _Pragma("unroll") for (int m = 0; m < 4; ++m) _Pragma("unroll") for (int k = 0; k < 2; ++k) dst[m][k] = *(const LAS bf16x8*)(lds + PG8_SA(b, h) + aoff + m * 2048 + k * 1024); } while (0)
; #define PG8_MMA(ai, bj, At, Bt) do { __builtin_amdgcn_s_setprio(1); _Pragma("unroll") for (int m = 0; m < 4; ++m) _Pragma("unroll") for (int n = 0; n < 2; ++n) _Pragma("unroll") for (int k = 0; k < 2; ++k) \
;         acc[ai][bj][m][n] = __builtin_amdgcn_mfma_f32_16x16x32_bf16(Bt[n][k], At[m][k], acc[ai][bj][m][n], 0, 0, 0); __builtin_amdgcn_s_setprio(0); } while (0)
; #define PG8_WAIT_V(n) asm volatile("s_waitcnt vmcnt(" #n ")" ::: "memory")
; #define PG8_WAIT_L(n) asm volatile("s_waitcnt lgkmcnt(" #n ")" ::: "memory")
; #define PG8_BAR __builtin_amdgcn_s_barrier()
; #define PG8_SCHED __builtin_amdgcn_sched_barrier(0)
; template <class Epi, class Sched, bool ALIGN_EPI = true>
; __device__ __forceinline__ void gemm_phase(LAS unsigned char* lds, const Gemm g, const Sched& S, const Epi& E) {
;     ...
;             PG8_LDA(At, 1, 1); PG8_STAGE(PG8_SB(1, 0), b3, voffB); PG8_STAGE(PG8_SB(1, 1), b3 + hstep, voffB); PG8_STAGE(PG8_SA(1, 0), a3, voffA);
;             PG8_WAIT_V(8); PG8_WAIT_L(0); PG8_BAR; PG8_MMA(1, 0, At, B0); PG8_MMA(1, 1, At, B1); PG8_BAR; PG8_SCHED;
;         }
;         if constexpr (ALIGN_EPI) { if (wr == 0) PG8_BAR; }
	s_add_i32 s28, s46, s36
	v_lshl_add_u64 v[140:141], v[140:141], 0, s[18:19]
	s_mov_b32 m0, s28
	ds_read_b128 v[184:187], v149 offset:49152
	ds_read_b128 v[188:191], v149 offset:50176
	ds_read_b128 v[192:195], v149 offset:51200
	ds_read_b128 v[196:199], v149 offset:52224
	ds_read_b128 v[204:207], v149 offset:53248
	ds_read_b128 v[208:211], v149 offset:54272
	ds_read_b128 v[212:215], v149 offset:55296
	ds_read_b128 v[216:219], v149 offset:56320
	global_load_lds_dwordx4 v[140:141], off
	s_add_i32 m0, s28, 0x2000
	s_add_u32 s26, s26, 0x80080
	v_lshl_add_u64 v[140:141], v[200:201], 0, s[18:19]
	s_addc_u32 s27, s27, 0
	s_add_i32 s28, s47, s36
	global_load_lds_dwordx4 v[140:141], off
	v_lshl_add_u64 v[140:141], s[26:27], 0, v[130:131]
	s_mov_b32 m0, s28
	s_nop 0
	global_load_lds_dwordx4 v[140:141], off
	v_lshl_add_u64 v[140:141], s[26:27], 0, v[134:135]
	s_add_i32 m0, s28, 0x2000
	s_nop 0
	global_load_lds_dwordx4 v[140:141], off
	v_lshl_add_u64 v[140:141], v[220:221], 0, s[18:19]
	s_mov_b32 m0, s41
	s_nop 0
	global_load_lds_dwordx4 v[140:141], off
	v_lshl_add_u64 v[140:141], v[222:223], 0, s[18:19]
	s_mov_b32 m0, s42
	s_nop 0
	global_load_lds_dwordx4 v[140:141], off
	s_waitcnt vmcnt(8)
	s_waitcnt lgkmcnt(0)
	s_barrier
	s_setprio 0
	s_waitcnt lgkmcnt(0)
	v_mfma_f32_16x16x32_bf16 v[60:63], v[152:155], v[184:187], v[60:63]
	v_mfma_f32_16x16x32_bf16 v[52:55], v[160:163], v[184:187], v[52:55]
	v_mfma_f32_16x16x32_bf16 v[44:47], v[152:155], v[192:195], v[44:47]
	v_mfma_f32_16x16x32_bf16 v[36:39], v[160:163], v[192:195], v[36:39]
	v_mfma_f32_16x16x32_bf16 v[28:31], v[152:155], v[204:207], v[28:31]
	v_mfma_f32_16x16x32_bf16 v[20:23], v[160:163], v[204:207], v[20:23]
	v_mfma_f32_16x16x32_bf16 v[12:15], v[152:155], v[212:215], v[12:15]
	v_mfma_f32_16x16x32_bf16 v[4:7], v[160:163], v[212:215], v[4:7]
	v_mfma_f32_16x16x32_bf16 v[60:63], v[156:159], v[188:191], v[60:63]
	v_mfma_f32_16x16x32_bf16 v[52:55], v[164:167], v[188:191], v[52:55]
	v_mfma_f32_16x16x32_bf16 v[44:47], v[156:159], v[196:199], v[44:47]
	v_mfma_f32_16x16x32_bf16 v[36:39], v[164:167], v[196:199], v[36:39]
	v_mfma_f32_16x16x32_bf16 v[28:31], v[156:159], v[208:211], v[28:31]
	v_mfma_f32_16x16x32_bf16 v[20:23], v[164:167], v[208:211], v[20:23]
	v_mfma_f32_16x16x32_bf16 v[12:15], v[156:159], v[216:219], v[12:15]
	v_mfma_f32_16x16x32_bf16 v[4:7], v[164:167], v[216:219], v[4:7]
	v_mfma_f32_16x16x32_bf16 v[56:59], v[168:171], v[184:187], v[56:59]
	v_mfma_f32_16x16x32_bf16 v[48:51], v[176:179], v[184:187], v[48:51]
	v_mfma_f32_16x16x32_bf16 v[40:43], v[168:171], v[192:195], v[40:43]
	v_mfma_f32_16x16x32_bf16 v[32:35], v[176:179], v[192:195], v[32:35]
	v_mfma_f32_16x16x32_bf16 v[24:27], v[168:171], v[204:207], v[24:27]
	v_mfma_f32_16x16x32_bf16 v[16:19], v[176:179], v[204:207], v[16:19]
	v_mfma_f32_16x16x32_bf16 v[8:11], v[168:171], v[212:215], v[8:11]
	v_mfma_f32_16x16x32_bf16 v[0:3], v[176:179], v[212:215], v[0:3]
	v_mfma_f32_16x16x32_bf16 v[56:59], v[172:175], v[188:191], v[56:59]
	v_mfma_f32_16x16x32_bf16 v[48:51], v[180:183], v[188:191], v[48:51]
	v_mfma_f32_16x16x32_bf16 v[40:43], v[172:175], v[196:199], v[40:43]
	v_mfma_f32_16x16x32_bf16 v[32:35], v[180:183], v[196:199], v[32:35]
	v_mfma_f32_16x16x32_bf16 v[24:27], v[172:175], v[208:211], v[24:27]
	v_mfma_f32_16x16x32_bf16 v[16:19], v[180:183], v[208:211], v[16:19]
	v_mfma_f32_16x16x32_bf16 v[8:11], v[172:175], v[216:219], v[8:11]
	v_mfma_f32_16x16x32_bf16 v[0:3], v[180:183], v[216:219], v[0:3]
	s_setprio 1
	s_barrier
	s_add_i32 s56, s56, 2
	s_add_u32 s24, s24, 0x100
	s_addc_u32 s25, s25, 0
	s_add_u32 s54, s54, 0x100
	s_addc_u32 s55, s55, 0
	s_cmp_gt_u32 s56, 29
	s_cbranch_scc0 .LBB0_647
	s_and_b64 vcc, exec, s[20:21]
	s_cbranch_vccz .LBB0_650
	s_barrier

; #define PG8_STAGE(bufoff, gbase, voff) do { _Pragma("unroll") for (int _i = 0; _i < 2; ++_i) \
;         __builtin_amdgcn_global_load_lds((const unsigned*)((const char*)(gbase) + (voff)[_i]), (LAS unsigned*)(lds + (bufoff) + ldsw + _i * 8192), 16, 0, 0); } while (0)
; #define PG8_LDA(dst, b, h) do { _Pragma("unroll") for (int m = 0; m < 4; ++m) _Pragma("unroll") for (int k = 0; k < 2; ++k) dst[m][k] = *(const LAS bf16x8*)(lds + PG8_SA(b, h) + aoff + m * 2048 + k * 1024); } while (0)
; #define PG8_LDB(dst, b, h) do { _Pragma("unroll") for (int n = 0; n < 2; ++n) _Pragma("unroll") for (int k = 0; k < 2; ++k) dst[n][k] = *(const LAS bf16x8*)(lds + PG8_SB(b, h) + boff + n * 2048 + k * 1024); } while (0)
; #define PG8_MMA(ai, bj, At, Bt) do { __builtin_amdgcn_s_setprio(1); _Pragma("unroll") for (int m = 0; m < 4; ++m) _Pragma("unroll") for (int n = 0; n < 2; ++n) _Pragma("unroll") for (int k = 0; k < 2; ++k) \
;         acc[ai][bj][m][n] = __builtin_amdgcn_mfma_f32_16x16x32_bf16(Bt[n][k], At[m][k], acc[ai][bj][m][n], 0, 0, 0); __builtin_amdgcn_s_setprio(0); } while (0)
; #define PG8_WAIT_V(n) asm volatile("s_waitcnt vmcnt(" #n ")" ::: "memory")
; #define PG8_WAIT_L(n) asm volatile("s_waitcnt lgkmcnt(" #n ")" ::: "memory")
; template <class Epi, class Sched, bool ALIGN_EPI = true>
; __device__ __forceinline__ void gemm_phase(LAS unsigned char* lds, const Gemm g, const Sched& S, const Epi& E) {
;     ...
;         const bool has_next = PG8_NEXT(ui + 1, nxt);
;         const char* nA = has_next ? (const char*)g.A + (size_t)nxt.pm * tstep : cA; const char* nB = has_next ? (const char*)g.Bt + (size_t)nxt.pn * tstep : cB;
;         for (int t = 0; t < nt; t += 2) {
;             const bool last = (t == nt - 2);
;             const char* a1 = cA + (size_t)(t + 1) * kstep;
;             const char* a2 = last ? nA : cA + (size_t)(t + 2) * kstep; const char* b2 = last ? nB : cB + (size_t)(t + 2) * kstep;
;             const char* a3 = a2 + kstep; const char* b3 = b2 + kstep;
;             PG8_LDB(B0, 0, 0); PG8_LDB(B1, 0, 1); PG8_SCHED; PG8_LDA(At, 0, 0); PG8_STAGE(PG8_SA(1, 1), a1 + hstep, voffA);
;             PG8_WAIT_V(8); PG8_WAIT_L(0); PG8_BAR; PG8_MMA(0, 0, At, B0); PG8_MMA(0, 1, At, B1); PG8_BAR; PG8_SCHED;
;             PG8_LDA(At, 0, 1); PG8_STAGE(PG8_SB(0, 0), b2, voffB); PG8_STAGE(PG8_SB(0, 1), b2 + hstep, voffB); PG8_STAGE(PG8_SA(0, 0), a2, voffA);
.LBB0_667:
	v_readlane_b32 s14, v137, s56
	ds_read_b128 v[0:3], v140
	ds_read_b128 v[4:7], v140 offset:1024
	ds_read_b128 v[8:11], v140 offset:2048
	ds_read_b128 v[12:15], v140 offset:3072
	ds_read_b128 v[16:19], v141
	ds_read_b128 v[20:23], v141 offset:1024
	ds_read_b128 v[24:27], v141 offset:2048
	ds_read_b128 v[28:31], v141 offset:3072
	s_cmp_gt_i32 s14, -1
	s_mov_b64 s[48:49], s[6:7]
	s_cselect_b64 s[38:39], -1, 0
	s_lshl_b64 s[6:7], s[14:15], 17
	s_add_u32 s36, s3, s6
	s_addc_u32 s37, s50, s7
	v_readlane_b32 s34, v136, s56
	s_and_b64 s[6:7], s[38:39], exec
	s_cselect_b32 s45, s37, s43
	s_cselect_b32 s44, s36, s42
	s_ashr_i32 s35, s34, 31
	s_lshl_b64 s[6:7], s[34:35], 17
	s_add_u32 s6, s51, s6
	s_addc_u32 s7, s52, s7
	s_and_b64 s[40:41], s[38:39], exec
	s_cselect_b32 s41, s7, s49
	s_cselect_b32 s40, s6, s48
	s_add_u32 s46, s42, 0x10080
	s_addc_u32 s47, s43, 0
	s_mov_b32 m0, s59
	v_lshl_add_u64 v[64:65], s[46:47], 0, v[128:129]
	ds_read_b128 v[32:35], v142
	ds_read_b128 v[36:39], v142 offset:1024
	ds_read_b128 v[40:43], v142 offset:2048
	ds_read_b128 v[44:47], v142 offset:3072
	ds_read_b128 v[48:51], v142 offset:4096
	ds_read_b128 v[52:55], v142 offset:5120
	ds_read_b128 v[56:59], v142 offset:6144
	ds_read_b128 v[60:63], v142 offset:7168
	global_load_lds_dwordx4 v[64:65], off
	v_lshl_add_u64 v[64:65], s[46:47], 0, v[132:133]
	s_mov_b32 m0, s60
	s_nop 0
	global_load_lds_dwordx4 v[64:65], off
	s_waitcnt vmcnt(8)
	s_waitcnt lgkmcnt(0)
	s_barrier
	s_setprio 0
	s_waitcnt lgkmcnt(0)
	v_mfma_f32_16x16x32_bf16 v[64:67], v[0:3], v[32:35], 0
	v_mfma_f32_16x16x32_bf16 v[68:71], v[8:11], v[32:35], 0
	v_mfma_f32_16x16x32_bf16 v[72:75], v[0:3], v[40:43], 0
	v_mfma_f32_16x16x32_bf16 v[76:79], v[8:11], v[40:43], 0
	v_mfma_f32_16x16x32_bf16 v[80:83], v[0:3], v[48:51], 0
	v_mfma_f32_16x16x32_bf16 v[84:87], v[8:11], v[48:51], 0
	v_mfma_f32_16x16x32_bf16 v[88:91], v[0:3], v[56:59], 0
	v_mfma_f32_16x16x32_bf16 v[92:95], v[8:11], v[56:59], 0
	v_mfma_f32_16x16x32_bf16 v[64:67], v[4:7], v[36:39], v[64:67]
	v_mfma_f32_16x16x32_bf16 v[68:71], v[12:15], v[36:39], v[68:71]
	v_mfma_f32_16x16x32_bf16 v[72:75], v[4:7], v[44:47], v[72:75]
	v_mfma_f32_16x16x32_bf16 v[76:79], v[12:15], v[44:47], v[76:79]
	v_mfma_f32_16x16x32_bf16 v[80:83], v[4:7], v[52:55], v[80:83]
	v_mfma_f32_16x16x32_bf16 v[84:87], v[12:15], v[52:55], v[84:87]
	v_mfma_f32_16x16x32_bf16 v[88:91], v[4:7], v[60:63], v[88:91]
	v_mfma_f32_16x16x32_bf16 v[92:95], v[12:15], v[60:63], v[92:95]
	v_mfma_f32_16x16x32_bf16 v[96:99], v[16:19], v[32:35], 0
	v_mfma_f32_16x16x32_bf16 v[32:35], v[24:27], v[32:35], 0
	v_mfma_f32_16x16x32_bf16 v[96:99], v[20:23], v[36:39], v[96:99]
	v_mfma_f32_16x16x32_bf16 v[32:35], v[28:31], v[36:39], v[32:35]
	v_mfma_f32_16x16x32_bf16 v[36:39], v[16:19], v[40:43], 0
	v_mfma_f32_16x16x32_bf16 v[40:43], v[24:27], v[40:43], 0
	v_mfma_f32_16x16x32_bf16 v[36:39], v[20:23], v[44:47], v[36:39]
	v_mfma_f32_16x16x32_bf16 v[40:43], v[28:31], v[44:47], v[40:43]
	v_mfma_f32_16x16x32_bf16 v[44:47], v[16:19], v[48:51], 0
	v_mfma_f32_16x16x32_bf16 v[48:51], v[24:27], v[48:51], 0
	v_mfma_f32_16x16x32_bf16 v[44:47], v[20:23], v[52:55], v[44:47]
	v_mfma_f32_16x16x32_bf16 v[48:51], v[28:31], v[52:55], v[48:51]
	v_mfma_f32_16x16x32_bf16 v[52:55], v[16:19], v[56:59], 0
	v_mfma_f32_16x16x32_bf16 v[56:59], v[24:27], v[56:59], 0
	v_mfma_f32_16x16x32_bf16 v[52:55], v[20:23], v[60:63], v[52:55]
	v_mfma_f32_16x16x32_bf16 v[56:59], v[28:31], v[60:63], v[56:59]
	s_setprio 1
	s_barrier
	v_lshl_add_u64 v[212:213], s[48:49], 0, v[130:131]
	s_mov_b32 m0, s61
	v_lshl_add_u64 v[146:147], v[212:213], 0, s[16:17]
	v_lshl_add_u64 v[214:215], s[48:49], 0, v[134:135]
	s_add_u32 s46, s48, 0x10100
	ds_read_b128 v[60:63], v142 offset:16384
	ds_read_b128 v[100:103], v142 offset:17408
	ds_read_b128 v[104:107], v142 offset:18432
	ds_read_b128 v[108:111], v142 offset:19456
	ds_read_b128 v[112:115], v142 offset:20480
	ds_read_b128 v[116:119], v142 offset:21504
	ds_read_b128 v[120:123], v142 offset:22528
	ds_read_b128 v[124:127], v142 offset:23552
	global_load_lds_dwordx4 v[146:147], off
	v_lshl_add_u64 v[146:147], v[214:215], 0, s[16:17]
	s_mov_b32 m0, s62
	s_addc_u32 s47, s49, 0
	global_load_lds_dwordx4 v[146:147], off
	v_lshl_add_u64 v[146:147], s[46:47], 0, v[130:131]
	s_mov_b32 m0, s63
	v_lshl_add_u64 v[216:217], s[42:43], 0, v[128:129]
	global_load_lds_dwordx4 v[146:147], off
	v_lshl_add_u64 v[146:147], s[46:47], 0, v[134:135]
	s_mov_b32 m0, s76
	v_lshl_add_u64 v[218:219], s[42:43], 0, v[132:133]
	global_load_lds_dwordx4 v[146:147], off
	v_lshl_add_u64 v[146:147], v[216:217], 0, s[16:17]
	s_mov_b32 m0, s23
	s_nop 0
	global_load_lds_dwordx4 v[146:147], off
	v_lshl_add_u64 v[146:147], v[218:219], 0, s[16:17]
	s_mov_b32 m0, s53
	s_nop 0
	global_load_lds_dwordx4 v[146:147], off
	s_waitcnt vmcnt(8)
	s_waitcnt lgkmcnt(0)
	s_barrier
; #define PG8_STAGE(bufoff, gbase, voff) do { _Pragma("unroll") for (int _i = 0; _i < 2; ++_i) \
;         __builtin_amdgcn_global_load_lds((const unsigned*)((const char*)(gbase) + (voff)[_i]), (LAS unsigned*)(lds + (bufoff) + ldsw + _i * 8192), 16, 0, 0); } while (0)
; #define PG8_LDA(dst, b, h) do { _Pragma("unroll") for (int m = 0; m < 4; ++m) _Pragma("unroll") for (int k = 0; k < 2; ++k) dst[m][k] = *(const LAS bf16x8*)(lds + PG8_SA(b, h) + aoff + m * 2048 + k * 1024); } while (0)
; #define PG8_LDB(dst, b, h) do { _Pragma("unroll") for (int n = 0; n < 2; ++n) _Pragma("unroll") for (int k = 0; k < 2; ++k) dst[n][k] = *(const LAS bf16x8*)(lds + PG8_SB(b, h) + boff + n * 2048 + k * 1024); } while (0)
; #define PG8_MMA(ai, bj, At, Bt) do { __builtin_amdgcn_s_setprio(1); _Pragma("unroll") for (int m = 0; m < 4; ++m) _Pragma("unroll") for (int n = 0; n < 2; ++n) _Pragma("unroll") for (int k = 0; k < 2; ++k) \
;         acc[ai][bj][m][n] = __builtin_amdgcn_mfma_f32_16x16x32_bf16(Bt[n][k], At[m][k], acc[ai][bj][m][n], 0, 0, 0); __builtin_amdgcn_s_setprio(0); } while (0)
; #define PG8_WAIT_V(n) asm volatile("s_waitcnt vmcnt(" #n ")" ::: "memory")
; #define PG8_WAIT_L(n) asm volatile("s_waitcnt lgkmcnt(" #n ")" ::: "memory")
; #define PG8_BAR __builtin_amdgcn_s_barrier()
; #define PG8_SCHED __builtin_amdgcn_sched_barrier(0)
; template <class Epi, class Sched, bool ALIGN_EPI = true>
; __device__ __forceinline__ void gemm_phase(LAS unsigned char* lds, const Gemm g, const Sched& S, const Epi& E) {
;     ...
;             PG8_WAIT_V(8); PG8_WAIT_L(0); PG8_BAR; PG8_MMA(1, 0, At, B0); PG8_MMA(1, 1, At, B1); PG8_BAR; PG8_SCHED;
;             PG8_LDB(B0, 1, 0); PG8_LDB(B1, 1, 1); PG8_SCHED; PG8_LDA(At, 1, 0); PG8_STAGE(PG8_SA(0, 1), a2 + hstep, voffA);
;             PG8_WAIT_V(8); PG8_WAIT_L(0); PG8_BAR; PG8_MMA(0, 0, At, B0); PG8_MMA(0, 1, At, B1); PG8_BAR; PG8_SCHED;
	s_setprio 0
	s_waitcnt lgkmcnt(0)
	v_mfma_f32_16x16x32_bf16 v[146:149], v[0:3], v[60:63], 0
	v_mfma_f32_16x16x32_bf16 v[154:157], v[0:3], v[104:107], 0
	v_mfma_f32_16x16x32_bf16 v[162:165], v[0:3], v[112:115], 0
	v_mfma_f32_16x16x32_bf16 v[0:3], v[0:3], v[120:123], 0
	v_mfma_f32_16x16x32_bf16 v[146:149], v[4:7], v[100:103], v[146:149]
	v_mfma_f32_16x16x32_bf16 v[154:157], v[4:7], v[108:111], v[154:157]
	v_mfma_f32_16x16x32_bf16 v[162:165], v[4:7], v[116:119], v[162:165]
	v_mfma_f32_16x16x32_bf16 v[0:3], v[4:7], v[124:127], v[0:3]
	v_mfma_f32_16x16x32_bf16 v[4:7], v[8:11], v[120:123], 0
	v_mfma_f32_16x16x32_bf16 v[150:153], v[8:11], v[60:63], 0
	v_mfma_f32_16x16x32_bf16 v[158:161], v[8:11], v[104:107], 0
	v_mfma_f32_16x16x32_bf16 v[166:169], v[8:11], v[112:115], 0
	v_mfma_f32_16x16x32_bf16 v[4:7], v[12:15], v[124:127], v[4:7]
	v_mfma_f32_16x16x32_bf16 v[150:153], v[12:15], v[100:103], v[150:153]
	v_mfma_f32_16x16x32_bf16 v[158:161], v[12:15], v[108:111], v[158:161]
	v_mfma_f32_16x16x32_bf16 v[166:169], v[12:15], v[116:119], v[166:169]
	v_mfma_f32_16x16x32_bf16 v[8:11], v[16:19], v[60:63], 0
	v_mfma_f32_16x16x32_bf16 v[12:15], v[24:27], v[60:63], 0
	v_mfma_f32_16x16x32_bf16 v[8:11], v[20:23], v[100:103], v[8:11]
	v_mfma_f32_16x16x32_bf16 v[12:15], v[28:31], v[100:103], v[12:15]
	v_mfma_f32_16x16x32_bf16 v[60:63], v[16:19], v[104:107], 0
	v_mfma_f32_16x16x32_bf16 v[100:103], v[24:27], v[104:107], 0
	v_mfma_f32_16x16x32_bf16 v[104:107], v[16:19], v[112:115], 0
	v_mfma_f32_16x16x32_bf16 v[16:19], v[16:19], v[120:123], 0
	v_mfma_f32_16x16x32_bf16 v[60:63], v[20:23], v[108:111], v[60:63]
	v_mfma_f32_16x16x32_bf16 v[100:103], v[28:31], v[108:111], v[100:103]
	v_mfma_f32_16x16x32_bf16 v[104:107], v[20:23], v[116:119], v[104:107]
	v_mfma_f32_16x16x32_bf16 v[108:111], v[24:27], v[112:115], 0
	v_mfma_f32_16x16x32_bf16 v[16:19], v[20:23], v[124:127], v[16:19]
	v_mfma_f32_16x16x32_bf16 v[20:23], v[24:27], v[120:123], 0
	v_mfma_f32_16x16x32_bf16 v[108:111], v[28:31], v[116:119], v[108:111]
	v_mfma_f32_16x16x32_bf16 v[20:23], v[28:31], v[124:127], v[20:23]
	s_setprio 1
	s_barrier
	ds_read_b128 v[24:27], v143
	ds_read_b128 v[28:31], v143 offset:1024
	ds_read_b128 v[112:115], v143 offset:2048
	ds_read_b128 v[116:119], v143 offset:3072
	ds_read_b128 v[120:123], v144
	ds_read_b128 v[124:127], v144 offset:1024
	ds_read_b128 v[170:173], v144 offset:2048
	ds_read_b128 v[174:177], v144 offset:3072
	s_add_u32 s46, s42, 0x10100
	s_addc_u32 s47, s43, 0
	s_mov_b32 m0, s54
	v_lshl_add_u64 v[220:221], s[46:47], 0, v[128:129]
	ds_read_b128 v[178:181], v142 offset:32768
	ds_read_b128 v[182:185], v142 offset:33792
	ds_read_b128 v[186:189], v142 offset:34816
	ds_read_b128 v[190:193], v142 offset:35840
	ds_read_b128 v[194:197], v142 offset:36864
	ds_read_b128 v[198:201], v142 offset:37888
	ds_read_b128 v[204:207], v142 offset:38912
	ds_read_b128 v[208:211], v142 offset:39936
	global_load_lds_dwordx4 v[220:221], off
	v_lshl_add_u64 v[220:221], s[46:47], 0, v[132:133]
	s_mov_b32 m0, s55
	s_nop 0
	global_load_lds_dwordx4 v[220:221], off
	s_waitcnt vmcnt(8)
	s_waitcnt lgkmcnt(0)
	s_barrier
	s_setprio 0
	s_waitcnt lgkmcnt(0)
	v_mfma_f32_16x16x32_bf16 v[64:67], v[24:27], v[178:181], v[64:67]
	v_mfma_f32_16x16x32_bf16 v[68:71], v[112:115], v[178:181], v[68:71]
	v_mfma_f32_16x16x32_bf16 v[72:75], v[24:27], v[186:189], v[72:75]
	v_mfma_f32_16x16x32_bf16 v[76:79], v[112:115], v[186:189], v[76:79]
	v_mfma_f32_16x16x32_bf16 v[80:83], v[24:27], v[194:197], v[80:83]
	v_mfma_f32_16x16x32_bf16 v[84:87], v[112:115], v[194:197], v[84:87]
	v_mfma_f32_16x16x32_bf16 v[88:91], v[24:27], v[204:207], v[88:91]
	v_mfma_f32_16x16x32_bf16 v[92:95], v[112:115], v[204:207], v[92:95]
	v_mfma_f32_16x16x32_bf16 v[64:67], v[28:31], v[182:185], v[64:67]
	v_mfma_f32_16x16x32_bf16 v[68:71], v[116:119], v[182:185], v[68:71]
	v_mfma_f32_16x16x32_bf16 v[72:75], v[28:31], v[190:193], v[72:75]
	v_mfma_f32_16x16x32_bf16 v[76:79], v[116:119], v[190:193], v[76:79]
	v_mfma_f32_16x16x32_bf16 v[80:83], v[28:31], v[198:201], v[80:83]
	v_mfma_f32_16x16x32_bf16 v[84:87], v[116:119], v[198:201], v[84:87]
	v_mfma_f32_16x16x32_bf16 v[88:91], v[28:31], v[208:211], v[88:91]
	v_mfma_f32_16x16x32_bf16 v[92:95], v[116:119], v[208:211], v[92:95]
	v_mfma_f32_16x16x32_bf16 v[96:99], v[120:123], v[178:181], v[96:99]
	v_mfma_f32_16x16x32_bf16 v[32:35], v[170:173], v[178:181], v[32:35]
	v_mfma_f32_16x16x32_bf16 v[36:39], v[120:123], v[186:189], v[36:39]
	v_mfma_f32_16x16x32_bf16 v[40:43], v[170:173], v[186:189], v[40:43]
	v_mfma_f32_16x16x32_bf16 v[44:47], v[120:123], v[194:197], v[44:47]
	v_mfma_f32_16x16x32_bf16 v[48:51], v[170:173], v[194:197], v[48:51]
	v_mfma_f32_16x16x32_bf16 v[52:55], v[120:123], v[204:207], v[52:55]
	v_mfma_f32_16x16x32_bf16 v[56:59], v[170:173], v[204:207], v[56:59]
	v_mfma_f32_16x16x32_bf16 v[96:99], v[124:127], v[182:185], v[96:99]
	v_mfma_f32_16x16x32_bf16 v[32:35], v[174:177], v[182:185], v[32:35]
	v_mfma_f32_16x16x32_bf16 v[36:39], v[124:127], v[190:193], v[36:39]
	v_mfma_f32_16x16x32_bf16 v[40:43], v[174:177], v[190:193], v[40:43]
	v_mfma_f32_16x16x32_bf16 v[44:47], v[124:127], v[198:201], v[44:47]
	v_mfma_f32_16x16x32_bf16 v[48:51], v[174:177], v[198:201], v[48:51]
	v_mfma_f32_16x16x32_bf16 v[52:55], v[124:127], v[208:211], v[52:55]
	v_mfma_f32_16x16x32_bf16 v[56:59], v[174:177], v[208:211], v[56:59]
	s_setprio 1
	s_barrier
; #define PG8_STAGE(bufoff, gbase, voff) do { _Pragma("unroll") for (int _i = 0; _i < 2; ++_i) \
;         __builtin_amdgcn_global_load_lds((const unsigned*)((const char*)(gbase) + (voff)[_i]), (LAS unsigned*)(lds + (bufoff) + ldsw + _i * 8192), 16, 0, 0); } while (0)
; #define PG8_LDA(dst, b, h) do { _Pragma("unroll") for (int m = 0; m < 4; ++m) _Pragma("unroll") for (int k = 0; k < 2; ++k) dst[m][k] = *(const LAS bf16x8*)(lds + PG8_SA(b, h) + aoff + m * 2048 + k * 1024); } while (0)
; #define PG8_LDB(dst, b, h) do { _Pragma("unroll") for (int n = 0; n < 2; ++n) _Pragma("unroll") for (int k = 0; k < 2; ++k) dst[n][k] = *(const LAS bf16x8*)(lds + PG8_SB(b, h) + boff + n * 2048 + k * 1024); } while (0)
; #define PG8_MMA(ai, bj, At, Bt) do { __builtin_amdgcn_s_setprio(1); _Pragma("unroll") for (int m = 0; m < 4; ++m) _Pragma("unroll") for (int n = 0; n < 2; ++n) _Pragma("unroll") for (int k = 0; k < 2; ++k) \
;         acc[ai][bj][m][n] = __builtin_amdgcn_mfma_f32_16x16x32_bf16(Bt[n][k], At[m][k], acc[ai][bj][m][n], 0, 0, 0); __builtin_amdgcn_s_setprio(0); } while (0)
; #define PG8_WAIT_V(n) asm volatile("s_waitcnt vmcnt(" #n ")" ::: "memory")
; template <class Epi, class Sched, bool ALIGN_EPI = true>
; __device__ __forceinline__ void gemm_phase(LAS unsigned char* lds, const Gemm g, const Sched& S, const Epi& E) {
;     ...
;             PG8_LDB(B0, 0, 0); PG8_LDB(B1, 0, 1); PG8_SCHED; PG8_LDA(At, 0, 0); PG8_STAGE(PG8_SA(1, 1), a1 + hstep, voffA);
;             PG8_WAIT_V(8); PG8_WAIT_L(0); PG8_BAR; PG8_MMA(0, 0, At, B0); PG8_MMA(0, 1, At, B1); PG8_BAR; PG8_SCHED;
;             PG8_LDA(At, 0, 1); PG8_STAGE(PG8_SB(0, 0), b2, voffB); PG8_STAGE(PG8_SB(0, 1), b2 + hstep, voffB); PG8_STAGE(PG8_SA(0, 0), a2, voffA);
;             PG8_WAIT_V(8); PG8_WAIT_L(0); PG8_BAR; PG8_MMA(1, 0, At, B0); PG8_MMA(1, 1, At, B1); PG8_BAR; PG8_SCHED;
;             PG8_LDB(B0, 1, 0); PG8_LDB(B1, 1, 1); PG8_SCHED; PG8_LDA(At, 1, 0); PG8_STAGE(PG8_SA(0, 1), a2 + hstep, voffA);
;             PG8_WAIT_V(8); PG8_WAIT_L(0); PG8_BAR; PG8_MMA(0, 0, At, B0); PG8_MMA(0, 1, At, B1); PG8_BAR; PG8_SCHED;
;             PG8_LDA(At, 1, 1); PG8_STAGE(PG8_SB(1, 0), b3, voffB); PG8_STAGE(PG8_SB(1, 1), b3 + hstep, voffB); PG8_STAGE(PG8_SA(1, 0), a3, voffA);
;             PG8_WAIT_V(8); PG8_WAIT_L(0); PG8_BAR; PG8_MMA(1, 0, At, B0); PG8_MMA(1, 1, At, B1); PG8_BAR; PG8_SCHED;
	s_mov_b32 m0, s77
	v_lshl_add_u64 v[212:213], v[212:213], 0, s[18:19]
	s_add_u32 s46, s48, 0x10180
	ds_read_b128 v[178:181], v142 offset:49152
	ds_read_b128 v[182:185], v142 offset:50176
	ds_read_b128 v[186:189], v142 offset:51200
	ds_read_b128 v[190:193], v142 offset:52224
	ds_read_b128 v[194:197], v142 offset:53248
	ds_read_b128 v[198:201], v142 offset:54272
	ds_read_b128 v[204:207], v142 offset:55296
	ds_read_b128 v[208:211], v142 offset:56320
	global_load_lds_dwordx4 v[212:213], off
	v_lshl_add_u64 v[212:213], v[214:215], 0, s[18:19]
	s_mov_b32 m0, s78
	s_addc_u32 s47, s49, 0
	global_load_lds_dwordx4 v[212:213], off
	v_lshl_add_u64 v[212:213], s[46:47], 0, v[130:131]
	s_mov_b32 m0, s79
	s_nop 0
	global_load_lds_dwordx4 v[212:213], off
	v_lshl_add_u64 v[212:213], s[46:47], 0, v[134:135]
	s_mov_b32 m0, s80
	s_nop 0
	global_load_lds_dwordx4 v[212:213], off
	v_lshl_add_u64 v[212:213], v[216:217], 0, s[18:19]
	s_mov_b32 m0, s57
	s_nop 0
	global_load_lds_dwordx4 v[212:213], off
	v_lshl_add_u64 v[212:213], v[218:219], 0, s[18:19]
	s_mov_b32 m0, s58
	s_nop 0
	global_load_lds_dwordx4 v[212:213], off
	s_waitcnt vmcnt(8)
	s_waitcnt lgkmcnt(0)
	s_barrier
	s_setprio 0
	s_waitcnt lgkmcnt(0)
	v_mfma_f32_16x16x32_bf16 v[0:3], v[24:27], v[204:207], v[0:3]
	v_mfma_f32_16x16x32_bf16 v[4:7], v[112:115], v[204:207], v[4:7]
	v_mfma_f32_16x16x32_bf16 v[146:149], v[24:27], v[178:181], v[146:149]
	v_mfma_f32_16x16x32_bf16 v[150:153], v[112:115], v[178:181], v[150:153]
	v_mfma_f32_16x16x32_bf16 v[154:157], v[24:27], v[186:189], v[154:157]
	v_mfma_f32_16x16x32_bf16 v[158:161], v[112:115], v[186:189], v[158:161]
	v_mfma_f32_16x16x32_bf16 v[162:165], v[24:27], v[194:197], v[162:165]
	v_mfma_f32_16x16x32_bf16 v[166:169], v[112:115], v[194:197], v[166:169]
	v_mfma_f32_16x16x32_bf16 v[0:3], v[28:31], v[208:211], v[0:3]
	v_mfma_f32_16x16x32_bf16 v[4:7], v[116:119], v[208:211], v[4:7]
	v_mfma_f32_16x16x32_bf16 v[146:149], v[28:31], v[182:185], v[146:149]
	v_mfma_f32_16x16x32_bf16 v[150:153], v[116:119], v[182:185], v[150:153]
	v_mfma_f32_16x16x32_bf16 v[154:157], v[28:31], v[190:193], v[154:157]
	v_mfma_f32_16x16x32_bf16 v[158:161], v[116:119], v[190:193], v[158:161]
	v_mfma_f32_16x16x32_bf16 v[162:165], v[28:31], v[198:201], v[162:165]
	v_mfma_f32_16x16x32_bf16 v[166:169], v[116:119], v[198:201], v[166:169]
	v_mfma_f32_16x16x32_bf16 v[8:11], v[120:123], v[178:181], v[8:11]
	v_mfma_f32_16x16x32_bf16 v[12:15], v[170:173], v[178:181], v[12:15]
	v_mfma_f32_16x16x32_bf16 v[24:27], v[120:123], v[186:189], v[60:63]
	v_mfma_f32_16x16x32_bf16 v[28:31], v[170:173], v[186:189], v[100:103]
	v_mfma_f32_16x16x32_bf16 v[60:63], v[120:123], v[194:197], v[104:107]
	v_mfma_f32_16x16x32_bf16 v[100:103], v[170:173], v[194:197], v[108:111]
	v_mfma_f32_16x16x32_bf16 v[16:19], v[120:123], v[204:207], v[16:19]
	v_mfma_f32_16x16x32_bf16 v[20:23], v[170:173], v[204:207], v[20:23]
	v_mfma_f32_16x16x32_bf16 v[8:11], v[124:127], v[182:185], v[8:11]
	v_mfma_f32_16x16x32_bf16 v[12:15], v[174:177], v[182:185], v[12:15]
	v_mfma_f32_16x16x32_bf16 v[24:27], v[124:127], v[190:193], v[24:27]
	v_mfma_f32_16x16x32_bf16 v[28:31], v[174:177], v[190:193], v[28:31]
	v_mfma_f32_16x16x32_bf16 v[60:63], v[124:127], v[198:201], v[60:63]
	v_mfma_f32_16x16x32_bf16 v[100:103], v[174:177], v[198:201], v[100:103]
	v_mfma_f32_16x16x32_bf16 v[16:19], v[124:127], v[208:211], v[16:19]
	v_mfma_f32_16x16x32_bf16 v[20:23], v[174:177], v[208:211], v[20:23]
	s_setprio 1
	s_barrier
	ds_read_b128 v[104:107], v140
	ds_read_b128 v[108:111], v140 offset:1024
	ds_read_b128 v[112:115], v140 offset:2048
	ds_read_b128 v[116:119], v140 offset:3072
	ds_read_b128 v[120:123], v141
	ds_read_b128 v[124:127], v141 offset:1024
	ds_read_b128 v[170:173], v141 offset:2048
	ds_read_b128 v[174:177], v141 offset:3072
	s_add_u32 s42, s42, 0x10180
	s_addc_u32 s43, s43, 0
	s_mov_b32 m0, s59
	v_lshl_add_u64 v[212:213], s[42:43], 0, v[128:129]
	ds_read_b128 v[178:181], v142
	ds_read_b128 v[182:185], v142 offset:1024
	ds_read_b128 v[186:189], v142 offset:2048
	ds_read_b128 v[190:193], v142 offset:3072
	ds_read_b128 v[194:197], v142 offset:4096
	ds_read_b128 v[198:201], v142 offset:5120
	ds_read_b128 v[204:207], v142 offset:6144
	ds_read_b128 v[208:211], v142 offset:7168
	global_load_lds_dwordx4 v[212:213], off
	v_lshl_add_u64 v[212:213], s[42:43], 0, v[132:133]
	s_mov_b32 m0, s60
	s_nop 0
	global_load_lds_dwordx4 v[212:213], off
	s_waitcnt vmcnt(8)
	s_waitcnt lgkmcnt(0)
	s_barrier
	s_setprio 0
	s_waitcnt lgkmcnt(0)
	v_mfma_f32_16x16x32_bf16 v[64:67], v[104:107], v[178:181], v[64:67]
	v_mfma_f32_16x16x32_bf16 v[68:71], v[112:115], v[178:181], v[68:71]
	v_mfma_f32_16x16x32_bf16 v[72:75], v[104:107], v[186:189], v[72:75]
	v_mfma_f32_16x16x32_bf16 v[76:79], v[112:115], v[186:189], v[76:79]
	v_mfma_f32_16x16x32_bf16 v[80:83], v[104:107], v[194:197], v[80:83]
	v_mfma_f32_16x16x32_bf16 v[84:87], v[112:115], v[194:197], v[84:87]
	v_mfma_f32_16x16x32_bf16 v[88:91], v[104:107], v[204:207], v[88:91]
	v_mfma_f32_16x16x32_bf16 v[92:95], v[112:115], v[204:207], v[92:95]
	v_mfma_f32_16x16x32_bf16 v[64:67], v[108:111], v[182:185], v[64:67]
	v_mfma_f32_16x16x32_bf16 v[68:71], v[116:119], v[182:185], v[68:71]
	v_mfma_f32_16x16x32_bf16 v[72:75], v[108:111], v[190:193], v[72:75]
	v_mfma_f32_16x16x32_bf16 v[76:79], v[116:119], v[190:193], v[76:79]
	v_mfma_f32_16x16x32_bf16 v[80:83], v[108:111], v[198:201], v[80:83]
	v_mfma_f32_16x16x32_bf16 v[84:87], v[116:119], v[198:201], v[84:87]
	v_mfma_f32_16x16x32_bf16 v[88:91], v[108:111], v[208:211], v[88:91]
	v_mfma_f32_16x16x32_bf16 v[92:95], v[116:119], v[208:211], v[92:95]
	v_mfma_f32_16x16x32_bf16 v[32:35], v[170:173], v[178:181], v[32:35]
	v_mfma_f32_16x16x32_bf16 v[36:39], v[120:123], v[186:189], v[36:39]
	v_mfma_f32_16x16x32_bf16 v[40:43], v[170:173], v[186:189], v[40:43]
	v_mfma_f32_16x16x32_bf16 v[44:47], v[120:123], v[194:197], v[44:47]
	v_mfma_f32_16x16x32_bf16 v[48:51], v[170:173], v[194:197], v[48:51]
	v_mfma_f32_16x16x32_bf16 v[52:55], v[120:123], v[204:207], v[52:55]
	v_mfma_f32_16x16x32_bf16 v[56:59], v[170:173], v[204:207], v[56:59]
	v_mfma_f32_16x16x32_bf16 v[96:99], v[120:123], v[178:181], v[96:99]
	v_mfma_f32_16x16x32_bf16 v[32:35], v[174:177], v[182:185], v[32:35]
	v_mfma_f32_16x16x32_bf16 v[36:39], v[124:127], v[190:193], v[36:39]
	v_mfma_f32_16x16x32_bf16 v[40:43], v[174:177], v[190:193], v[40:43]
	v_mfma_f32_16x16x32_bf16 v[44:47], v[124:127], v[198:201], v[44:47]
	v_mfma_f32_16x16x32_bf16 v[48:51], v[174:177], v[198:201], v[48:51]
	v_mfma_f32_16x16x32_bf16 v[52:55], v[124:127], v[208:211], v[52:55]
	v_mfma_f32_16x16x32_bf16 v[56:59], v[174:177], v[208:211], v[56:59]
	v_mfma_f32_16x16x32_bf16 v[212:215], v[124:127], v[182:185], v[96:99]
	s_setprio 1
	s_barrier
; #define PG8_STAGE(bufoff, gbase, voff) do { _Pragma("unroll") for (int _i = 0; _i < 2; ++_i) \
;         __builtin_amdgcn_global_load_lds((const unsigned*)((const char*)(gbase) + (voff)[_i]), (LAS unsigned*)(lds + (bufoff) + ldsw + _i * 8192), 16, 0, 0); } while (0)
; #define PG8_LDA(dst, b, h) do { _Pragma("unroll") for (int m = 0; m < 4; ++m) _Pragma("unroll") for (int k = 0; k < 2; ++k) dst[m][k] = *(const LAS bf16x8*)(lds + PG8_SA(b, h) + aoff + m * 2048 + k * 1024); } while (0)
; #define PG8_LDB(dst, b, h) do { _Pragma("unroll") for (int n = 0; n < 2; ++n) _Pragma("unroll") for (int k = 0; k < 2; ++k) dst[n][k] = *(const LAS bf16x8*)(lds + PG8_SB(b, h) + boff + n * 2048 + k * 1024); } while (0)
; #define PG8_MMA(ai, bj, At, Bt) do { __builtin_amdgcn_s_setprio(1); _Pragma("unroll") for (int m = 0; m < 4; ++m) _Pragma("unroll") for (int n = 0; n < 2; ++n) _Pragma("unroll") for (int k = 0; k < 2; ++k) \
;         acc[ai][bj][m][n] = __builtin_amdgcn_mfma_f32_16x16x32_bf16(Bt[n][k], At[m][k], acc[ai][bj][m][n], 0, 0, 0); __builtin_amdgcn_s_setprio(0); } while (0)
; #define PG8_WAIT_V(n) asm volatile("s_waitcnt vmcnt(" #n ")" ::: "memory")
; #define PG8_WAIT_L(n) asm volatile("s_waitcnt lgkmcnt(" #n ")" ::: "memory")
; #define PG8_BAR __builtin_amdgcn_s_barrier()
; #define PG8_SCHED __builtin_amdgcn_sched_barrier(0)
; template <class Epi, class Sched, bool ALIGN_EPI = true>
; __device__ __forceinline__ void gemm_phase(LAS unsigned char* lds, const Gemm g, const Sched& S, const Epi& E) {
;     ...
;             PG8_LDA(At, 0, 1); PG8_STAGE(PG8_SB(0, 0), b2, voffB); PG8_STAGE(PG8_SB(0, 1), b2 + hstep, voffB); PG8_STAGE(PG8_SA(0, 0), a2, voffA);
;             PG8_WAIT_V(8); PG8_WAIT_L(0); PG8_BAR; PG8_MMA(1, 0, At, B0); PG8_MMA(1, 1, At, B1); PG8_BAR; PG8_SCHED;
;             PG8_LDB(B0, 1, 0); PG8_LDB(B1, 1, 1); PG8_SCHED; PG8_LDA(At, 1, 0); PG8_STAGE(PG8_SA(0, 1), a2 + hstep, voffA);
;             PG8_WAIT_V(8); PG8_WAIT_L(0); PG8_BAR; PG8_MMA(0, 0, At, B0); PG8_MMA(0, 1, At, B1); PG8_BAR; PG8_SCHED;
	s_mov_b32 m0, s61
	v_lshl_add_u64 v[248:249], s[40:41], 0, v[130:131]
	s_add_u32 s42, s40, 0x10000
	ds_read_b128 v[96:99], v142 offset:16384
	ds_read_b128 v[178:181], v142 offset:17408
	ds_read_b128 v[182:185], v142 offset:18432
	ds_read_b128 v[186:189], v142 offset:19456
	ds_read_b128 v[190:193], v142 offset:20480
	ds_read_b128 v[194:197], v142 offset:21504
	ds_read_b128 v[198:201], v142 offset:22528
	ds_read_b128 v[204:207], v142 offset:23552
	global_load_lds_dwordx4 v[248:249], off
	v_lshl_add_u64 v[250:251], s[40:41], 0, v[134:135]
	s_mov_b32 m0, s62
	s_addc_u32 s43, s41, 0
	global_load_lds_dwordx4 v[250:251], off
	v_lshl_add_u64 v[208:209], s[42:43], 0, v[130:131]
	s_mov_b32 m0, s63
	v_lshl_add_u64 v[252:253], s[44:45], 0, v[128:129]
	global_load_lds_dwordx4 v[208:209], off
	v_lshl_add_u64 v[208:209], s[42:43], 0, v[134:135]
	s_mov_b32 m0, s76
	v_lshl_add_u64 v[202:203], s[44:45], 0, v[132:133]
	global_load_lds_dwordx4 v[208:209], off
	s_mov_b32 m0, s23
	s_nop 0
	global_load_lds_dwordx4 v[252:253], off
	s_mov_b32 m0, s53
	s_nop 0
	global_load_lds_dwordx4 v[202:203], off
	s_waitcnt vmcnt(8)
	s_waitcnt lgkmcnt(0)
	s_barrier
	s_setprio 0
	s_waitcnt lgkmcnt(0)
	v_mfma_f32_16x16x32_bf16 v[0:3], v[104:107], v[198:201], v[0:3]
	v_mfma_f32_16x16x32_bf16 v[4:7], v[112:115], v[198:201], v[4:7]
	v_mfma_f32_16x16x32_bf16 v[146:149], v[104:107], v[96:99], v[146:149]
	v_mfma_f32_16x16x32_bf16 v[150:153], v[112:115], v[96:99], v[150:153]
	v_mfma_f32_16x16x32_bf16 v[154:157], v[104:107], v[182:185], v[154:157]
	v_mfma_f32_16x16x32_bf16 v[158:161], v[112:115], v[182:185], v[158:161]
	v_mfma_f32_16x16x32_bf16 v[162:165], v[104:107], v[190:193], v[162:165]
	v_mfma_f32_16x16x32_bf16 v[166:169], v[112:115], v[190:193], v[166:169]
	v_mfma_f32_16x16x32_bf16 v[0:3], v[108:111], v[204:207], v[0:3]
	v_mfma_f32_16x16x32_bf16 v[4:7], v[116:119], v[204:207], v[4:7]
	v_mfma_f32_16x16x32_bf16 v[146:149], v[108:111], v[178:181], v[146:149]
	v_mfma_f32_16x16x32_bf16 v[150:153], v[116:119], v[178:181], v[150:153]
	v_mfma_f32_16x16x32_bf16 v[154:157], v[108:111], v[186:189], v[154:157]
	v_mfma_f32_16x16x32_bf16 v[158:161], v[116:119], v[186:189], v[158:161]
	v_mfma_f32_16x16x32_bf16 v[162:165], v[108:111], v[194:197], v[162:165]
	v_mfma_f32_16x16x32_bf16 v[166:169], v[116:119], v[194:197], v[166:169]
	v_mfma_f32_16x16x32_bf16 v[8:11], v[120:123], v[96:99], v[8:11]
	v_mfma_f32_16x16x32_bf16 v[12:15], v[170:173], v[96:99], v[12:15]
	v_mfma_f32_16x16x32_bf16 v[24:27], v[120:123], v[182:185], v[24:27]
	v_mfma_f32_16x16x32_bf16 v[8:11], v[124:127], v[178:181], v[8:11]
	v_mfma_f32_16x16x32_bf16 v[12:15], v[174:177], v[178:181], v[12:15]
	v_mfma_f32_16x16x32_bf16 v[178:181], v[124:127], v[186:189], v[24:27]
	v_mfma_f32_16x16x32_bf16 v[24:27], v[170:173], v[182:185], v[28:31]
	v_mfma_f32_16x16x32_bf16 v[182:185], v[174:177], v[186:189], v[24:27]
	v_mfma_f32_16x16x32_bf16 v[24:27], v[120:123], v[190:193], v[60:63]
	v_mfma_f32_16x16x32_bf16 v[186:189], v[124:127], v[194:197], v[24:27]
	v_mfma_f32_16x16x32_bf16 v[24:27], v[170:173], v[190:193], v[100:103]
	v_mfma_f32_16x16x32_bf16 v[16:19], v[120:123], v[198:201], v[16:19]
	v_mfma_f32_16x16x32_bf16 v[190:193], v[174:177], v[194:197], v[24:27]
	v_mfma_f32_16x16x32_bf16 v[194:197], v[124:127], v[204:207], v[16:19]
	v_mfma_f32_16x16x32_bf16 v[16:19], v[170:173], v[198:201], v[20:23]
	v_mfma_f32_16x16x32_bf16 v[170:173], v[174:177], v[204:207], v[16:19]
	s_setprio 1
	s_barrier
	ds_read_b128 v[60:63], v143
	ds_read_b128 v[174:177], v143 offset:1024
	ds_read_b128 v[198:201], v143 offset:2048
	ds_read_b128 v[204:207], v143 offset:3072
	ds_read_b128 v[208:211], v144
	ds_read_b128 v[216:219], v144 offset:1024
	ds_read_b128 v[220:223], v144 offset:2048
	ds_read_b128 v[224:227], v144 offset:3072
	s_add_u32 s42, s44, 0x10000
	s_addc_u32 s43, s45, 0
	s_mov_b32 m0, s54
	v_lshl_add_u64 v[24:25], s[42:43], 0, v[128:129]
	ds_read_b128 v[16:19], v142 offset:32768
	ds_read_b128 v[20:23], v142 offset:33792
	ds_read_b128 v[108:111], v142 offset:34816
	ds_read_b128 v[228:231], v142 offset:35840
	ds_read_b128 v[232:235], v142 offset:36864
	ds_read_b128 v[236:239], v142 offset:37888
	ds_read_b128 v[240:243], v142 offset:38912
	ds_read_b128 v[244:247], v142 offset:39936
	global_load_lds_dwordx4 v[24:25], off
	v_lshl_add_u64 v[24:25], s[42:43], 0, v[132:133]
	s_mov_b32 m0, s55
	s_nop 0
	global_load_lds_dwordx4 v[24:25], off
	s_waitcnt vmcnt(8)
	s_waitcnt lgkmcnt(0)
	s_barrier
; #define PG8_STAGE(bufoff, gbase, voff) do { _Pragma("unroll") for (int _i = 0; _i < 2; ++_i) \
;         __builtin_amdgcn_global_load_lds((const unsigned*)((const char*)(gbase) + (voff)[_i]), (LAS unsigned*)(lds + (bufoff) + ldsw + _i * 8192), 16, 0, 0); } while (0)
; #define PG8_LDA(dst, b, h) do { _Pragma("unroll") for (int m = 0; m < 4; ++m) _Pragma("unroll") for (int k = 0; k < 2; ++k) dst[m][k] = *(const LAS bf16x8*)(lds + PG8_SA(b, h) + aoff + m * 2048 + k * 1024); } while (0)
; #define PG8_MMA(ai, bj, At, Bt) do { __builtin_amdgcn_s_setprio(1); _Pragma("unroll") for (int m = 0; m < 4; ++m) _Pragma("unroll") for (int n = 0; n < 2; ++n) _Pragma("unroll") for (int k = 0; k < 2; ++k) \
;         acc[ai][bj][m][n] = __builtin_amdgcn_mfma_f32_16x16x32_bf16(Bt[n][k], At[m][k], acc[ai][bj][m][n], 0, 0, 0); __builtin_amdgcn_s_setprio(0); } while (0)
; #define PG8_WAIT_V(n) asm volatile("s_waitcnt vmcnt(" #n ")" ::: "memory")
; #define PG8_WAIT_L(n) asm volatile("s_waitcnt lgkmcnt(" #n ")" ::: "memory")
; #define PG8_BAR __builtin_amdgcn_s_barrier()
; #define PG8_SCHED __builtin_amdgcn_sched_barrier(0)
; template <class Epi, class Sched, bool ALIGN_EPI = true>
; __device__ __forceinline__ void gemm_phase(LAS unsigned char* lds, const Gemm g, const Sched& S, const Epi& E) {
;     ...
;             PG8_WAIT_V(8); PG8_WAIT_L(0); PG8_BAR; PG8_MMA(0, 0, At, B0); PG8_MMA(0, 1, At, B1); PG8_BAR; PG8_SCHED;
;             PG8_LDA(At, 1, 1); PG8_STAGE(PG8_SB(1, 0), b3, voffB); PG8_STAGE(PG8_SB(1, 1), b3 + hstep, voffB); PG8_STAGE(PG8_SA(1, 0), a3, voffA);
;             PG8_WAIT_V(8); PG8_WAIT_L(0); PG8_BAR; PG8_MMA(1, 0, At, B0); PG8_MMA(1, 1, At, B1); PG8_BAR; PG8_SCHED;
;         }
;         if constexpr (ALIGN_EPI) { if (wr == 0) PG8_BAR; }
	s_setprio 0
	s_waitcnt lgkmcnt(0)
	v_mfma_f32_16x16x32_bf16 v[24:27], v[60:63], v[16:19], v[64:67]
	v_mfma_f32_16x16x32_bf16 v[112:115], v[174:177], v[20:23], v[24:27]
	v_mfma_f32_16x16x32_bf16 v[24:27], v[198:201], v[16:19], v[68:71]
	v_mfma_f32_16x16x32_bf16 v[116:119], v[204:207], v[20:23], v[24:27]
	v_mfma_f32_16x16x32_bf16 v[24:27], v[60:63], v[108:111], v[72:75]
	v_mfma_f32_16x16x32_bf16 v[96:99], v[174:177], v[228:231], v[24:27]
	v_mfma_f32_16x16x32_bf16 v[24:27], v[198:201], v[108:111], v[76:79]
	v_mfma_f32_16x16x32_bf16 v[100:103], v[204:207], v[228:231], v[24:27]
	v_mfma_f32_16x16x32_bf16 v[24:27], v[60:63], v[232:235], v[80:83]
	v_mfma_f32_16x16x32_bf16 v[64:67], v[174:177], v[236:239], v[24:27]
	v_mfma_f32_16x16x32_bf16 v[24:27], v[198:201], v[232:235], v[84:87]
	v_mfma_f32_16x16x32_bf16 v[68:71], v[204:207], v[236:239], v[24:27]
	v_mfma_f32_16x16x32_bf16 v[24:27], v[60:63], v[240:243], v[88:91]
	v_mfma_f32_16x16x32_bf16 v[28:31], v[198:201], v[240:243], v[92:95]
	v_mfma_f32_16x16x32_bf16 v[24:27], v[174:177], v[244:247], v[24:27]
	v_mfma_f32_16x16x32_bf16 v[28:31], v[204:207], v[244:247], v[28:31]
	v_mfma_f32_16x16x32_bf16 v[72:75], v[208:211], v[16:19], v[212:215]
	v_mfma_f32_16x16x32_bf16 v[16:19], v[220:223], v[16:19], v[32:35]
	v_mfma_f32_16x16x32_bf16 v[124:127], v[224:227], v[20:23], v[16:19]
	v_mfma_f32_16x16x32_bf16 v[16:19], v[208:211], v[108:111], v[36:39]
	v_mfma_f32_16x16x32_bf16 v[104:107], v[216:219], v[228:231], v[16:19]
	v_mfma_f32_16x16x32_bf16 v[16:19], v[220:223], v[108:111], v[40:43]
	v_mfma_f32_16x16x32_bf16 v[108:111], v[224:227], v[228:231], v[16:19]
	v_mfma_f32_16x16x32_bf16 v[16:19], v[208:211], v[232:235], v[44:47]
	v_mfma_f32_16x16x32_bf16 v[120:123], v[216:219], v[20:23], v[72:75]
	v_mfma_f32_16x16x32_bf16 v[72:75], v[216:219], v[236:239], v[16:19]
	v_mfma_f32_16x16x32_bf16 v[16:19], v[220:223], v[232:235], v[48:51]
	v_mfma_f32_16x16x32_bf16 v[76:79], v[224:227], v[236:239], v[16:19]
	v_mfma_f32_16x16x32_bf16 v[16:19], v[208:211], v[240:243], v[52:55]
	v_mfma_f32_16x16x32_bf16 v[40:43], v[216:219], v[244:247], v[16:19]
	v_mfma_f32_16x16x32_bf16 v[16:19], v[220:223], v[240:243], v[56:59]
	v_mfma_f32_16x16x32_bf16 v[44:47], v[224:227], v[244:247], v[16:19]
	s_setprio 1
	s_barrier
	s_mov_b32 m0, s77
	s_nop 3
	v_lshl_add_u64 v[16:17], v[248:249], 0, s[12:13]
	s_add_u32 s40, s40, 0x10080
	ds_read_b128 v[32:35], v142 offset:49152
	ds_read_b128 v[36:39], v142 offset:50176
	ds_read_b128 v[212:215], v142 offset:51200
	ds_read_b128 v[228:231], v142 offset:52224
	ds_read_b128 v[232:235], v142 offset:53248
	ds_read_b128 v[236:239], v142 offset:54272
	ds_read_b128 v[240:243], v142 offset:55296
	ds_read_b128 v[244:247], v142 offset:56320
	global_load_lds_dwordx4 v[16:17], off
	v_lshl_add_u64 v[16:17], v[250:251], 0, s[12:13]
	s_mov_b32 m0, s78
	s_addc_u32 s41, s41, 0
	global_load_lds_dwordx4 v[16:17], off
	v_lshl_add_u64 v[16:17], s[40:41], 0, v[130:131]
	s_mov_b32 m0, s79
	s_nop 0
	global_load_lds_dwordx4 v[16:17], off
	v_lshl_add_u64 v[16:17], s[40:41], 0, v[134:135]
	s_mov_b32 m0, s80
	s_nop 0
	global_load_lds_dwordx4 v[16:17], off
	v_lshl_add_u64 v[16:17], v[252:253], 0, s[12:13]
	s_mov_b32 m0, s57
	s_nop 0
	global_load_lds_dwordx4 v[16:17], off
	v_lshl_add_u64 v[16:17], v[202:203], 0, s[12:13]
	s_mov_b32 m0, s58
	s_nop 0
	global_load_lds_dwordx4 v[16:17], off
	s_waitcnt vmcnt(8)
	s_waitcnt lgkmcnt(0)
	s_barrier
	s_setprio 0
	s_waitcnt lgkmcnt(0)
	v_mfma_f32_16x16x32_bf16 v[16:19], v[60:63], v[32:35], v[146:149]
	v_mfma_f32_16x16x32_bf16 v[80:83], v[174:177], v[36:39], v[16:19]
	v_mfma_f32_16x16x32_bf16 v[16:19], v[198:201], v[32:35], v[150:153]
	v_mfma_f32_16x16x32_bf16 v[84:87], v[204:207], v[36:39], v[16:19]
	v_mfma_f32_16x16x32_bf16 v[16:19], v[60:63], v[212:215], v[154:157]
	v_mfma_f32_16x16x32_bf16 v[48:51], v[174:177], v[228:231], v[16:19]
	v_mfma_f32_16x16x32_bf16 v[16:19], v[198:201], v[212:215], v[158:161]
	v_mfma_f32_16x16x32_bf16 v[52:55], v[204:207], v[228:231], v[16:19]
	v_mfma_f32_16x16x32_bf16 v[16:19], v[60:63], v[232:235], v[162:165]
	v_mfma_f32_16x16x32_bf16 v[20:23], v[198:201], v[232:235], v[166:169]
	v_mfma_f32_16x16x32_bf16 v[0:3], v[60:63], v[240:243], v[0:3]
	v_mfma_f32_16x16x32_bf16 v[4:7], v[198:201], v[240:243], v[4:7]
	v_mfma_f32_16x16x32_bf16 v[16:19], v[174:177], v[236:239], v[16:19]
	v_mfma_f32_16x16x32_bf16 v[20:23], v[204:207], v[236:239], v[20:23]
	v_mfma_f32_16x16x32_bf16 v[0:3], v[174:177], v[244:247], v[0:3]
	v_mfma_f32_16x16x32_bf16 v[4:7], v[204:207], v[244:247], v[4:7]
	v_mfma_f32_16x16x32_bf16 v[8:11], v[208:211], v[32:35], v[8:11]
	v_mfma_f32_16x16x32_bf16 v[88:91], v[216:219], v[36:39], v[8:11]
	v_mfma_f32_16x16x32_bf16 v[8:11], v[220:223], v[32:35], v[12:15]
	v_mfma_f32_16x16x32_bf16 v[92:95], v[224:227], v[36:39], v[8:11]
	v_mfma_f32_16x16x32_bf16 v[8:11], v[208:211], v[212:215], v[178:181]
	v_mfma_f32_16x16x32_bf16 v[56:59], v[216:219], v[228:231], v[8:11]
	v_mfma_f32_16x16x32_bf16 v[8:11], v[220:223], v[212:215], v[182:185]
	v_mfma_f32_16x16x32_bf16 v[60:63], v[224:227], v[228:231], v[8:11]
	v_mfma_f32_16x16x32_bf16 v[8:11], v[208:211], v[232:235], v[186:189]
	v_mfma_f32_16x16x32_bf16 v[32:35], v[216:219], v[236:239], v[8:11]
	v_mfma_f32_16x16x32_bf16 v[8:11], v[220:223], v[232:235], v[190:193]
	v_mfma_f32_16x16x32_bf16 v[36:39], v[224:227], v[236:239], v[8:11]
	v_mfma_f32_16x16x32_bf16 v[8:11], v[208:211], v[240:243], v[194:197]
	v_mfma_f32_16x16x32_bf16 v[12:15], v[220:223], v[240:243], v[170:173]
	v_mfma_f32_16x16x32_bf16 v[8:11], v[216:219], v[244:247], v[8:11]
	v_mfma_f32_16x16x32_bf16 v[12:15], v[224:227], v[244:247], v[12:15]
	s_setprio 1
	s_barrier
	s_and_b64 vcc, exec, s[4:5]
	s_cbranch_vccnz .LBB0_669
	s_barrier

; #define PG8_STAGE(bufoff, gbase, voff) do { _Pragma("unroll") for (int _i = 0; _i < 2; ++_i) \
;         __builtin_amdgcn_global_load_lds((const unsigned*)((const char*)(gbase) + (voff)[_i]), (LAS unsigned*)(lds + (bufoff) + ldsw + _i * 8192), 16, 0, 0); } while (0)
; #define PG8_LDA(dst, b, h) do { _Pragma("unroll") for (int m = 0; m < 4; ++m) _Pragma("unroll") for (int k = 0; k < 2; ++k) dst[m][k] = *(const LAS bf16x8*)(lds + PG8_SA(b, h) + aoff + m * 2048 + k * 1024); } while (0)
; #define PG8_LDB(dst, b, h) do { _Pragma("unroll") for (int n = 0; n < 2; ++n) _Pragma("unroll") for (int k = 0; k < 2; ++k) dst[n][k] = *(const LAS bf16x8*)(lds + PG8_SB(b, h) + boff + n * 2048 + k * 1024); } while (0)
; #define PG8_MMA(ai, bj, At, Bt) do { __builtin_amdgcn_s_setprio(1); _Pragma("unroll") for (int m = 0; m < 4; ++m) _Pragma("unroll") for (int n = 0; n < 2; ++n) _Pragma("unroll") for (int k = 0; k < 2; ++k) \
;         acc[ai][bj][m][n] = __builtin_amdgcn_mfma_f32_16x16x32_bf16(Bt[n][k], At[m][k], acc[ai][bj][m][n], 0, 0, 0); __builtin_amdgcn_s_setprio(0); } while (0)
; #define PG8_WAIT_V(n) asm volatile("s_waitcnt vmcnt(" #n ")" ::: "memory")
; #define PG8_WAIT_L(n) asm volatile("s_waitcnt lgkmcnt(" #n ")" ::: "memory")
; #define PG8_BAR __builtin_amdgcn_s_barrier()
; #define PG8_SCHED __builtin_amdgcn_sched_barrier(0)
; template <class Epi, class Sched, bool ALIGN_EPI = true>
; __device__ __forceinline__ void gemm_phase(LAS unsigned char* lds, const Gemm g, const Sched& S, const Epi& E) {
;     ...
;         for (int t = 0; t < nt; t += 2) {
;             const bool last = (t == nt - 2);
;             const char* a1 = cA + (size_t)(t + 1) * kstep;
;             const char* a2 = last ? nA : cA + (size_t)(t + 2) * kstep; const char* b2 = last ? nB : cB + (size_t)(t + 2) * kstep;
;             const char* a3 = a2 + kstep; const char* b3 = b2 + kstep;
;             PG8_LDB(B0, 0, 0); PG8_LDB(B1, 0, 1); PG8_SCHED; PG8_LDA(At, 0, 0); PG8_STAGE(PG8_SA(1, 1), a1 + hstep, voffA);
;             PG8_WAIT_V(8); PG8_WAIT_L(0); PG8_BAR; PG8_MMA(0, 0, At, B0); PG8_MMA(0, 1, At, B1); PG8_BAR; PG8_SCHED;
;             PG8_LDA(At, 0, 1); PG8_STAGE(PG8_SB(0, 0), b2, voffB); PG8_STAGE(PG8_SB(0, 1), b2 + hstep, voffB); PG8_STAGE(PG8_SA(0, 0), a2, voffA);
.LBB0_746:
	ds_read_b128 v[128:131], v187
	ds_read_b128 v[132:135], v187 offset:1024
	ds_read_b128 v[136:139], v187 offset:2048
	ds_read_b128 v[140:143], v187 offset:3072
	ds_read_b128 v[144:147], v188
	ds_read_b128 v[148:151], v188 offset:1024
	ds_read_b128 v[164:167], v188 offset:2048
	ds_read_b128 v[168:171], v188 offset:3072
	s_add_u32 s24, s22, 0x100
	s_addc_u32 s25, s23, 0
	s_cmpk_eq_i32 s56, 0x54
	s_cselect_b32 s29, s19, s25
	s_cselect_b32 s28, s18, s24
	s_cselect_b32 s27, s21, s55
	s_cselect_b32 s26, s20, s54
	s_mov_b32 m0, s43
	v_lshl_add_u64 v[180:181], s[22:23], 0, v[160:161]
	ds_read_b128 v[172:175], v189
	ds_read_b128 v[176:179], v189 offset:1024
	ds_read_b128 v[192:195], v189 offset:2048
	ds_read_b128 v[196:199], v189 offset:3072
	ds_read_b128 v[204:207], v189 offset:4096
	ds_read_b128 v[208:211], v189 offset:5120
	ds_read_b128 v[212:215], v189 offset:6144
	ds_read_b128 v[216:219], v189 offset:7168
	global_load_lds_dwordx4 v[180:181], off
	v_lshl_add_u64 v[180:181], s[22:23], 0, v[162:163]
	s_mov_b32 m0, s44
	s_nop 0
	global_load_lds_dwordx4 v[180:181], off
	s_waitcnt vmcnt(8)
	s_waitcnt lgkmcnt(0)
	s_barrier
	s_setprio 0
	s_waitcnt lgkmcnt(0)
	v_mfma_f32_16x16x32_bf16 v[124:127], v[128:131], v[172:175], v[124:127]
	v_mfma_f32_16x16x32_bf16 v[120:123], v[136:139], v[172:175], v[120:123]
	v_mfma_f32_16x16x32_bf16 v[108:111], v[128:131], v[192:195], v[108:111]
	v_mfma_f32_16x16x32_bf16 v[104:107], v[136:139], v[192:195], v[104:107]
	v_mfma_f32_16x16x32_bf16 v[92:95], v[128:131], v[204:207], v[92:95]
	v_mfma_f32_16x16x32_bf16 v[88:91], v[136:139], v[204:207], v[88:91]
	v_mfma_f32_16x16x32_bf16 v[76:79], v[128:131], v[212:215], v[76:79]
	v_mfma_f32_16x16x32_bf16 v[72:75], v[136:139], v[212:215], v[72:75]
	v_mfma_f32_16x16x32_bf16 v[124:127], v[132:135], v[176:179], v[124:127]
	v_mfma_f32_16x16x32_bf16 v[120:123], v[140:143], v[176:179], v[120:123]
	v_mfma_f32_16x16x32_bf16 v[108:111], v[132:135], v[196:199], v[108:111]
	v_mfma_f32_16x16x32_bf16 v[104:107], v[140:143], v[196:199], v[104:107]
	v_mfma_f32_16x16x32_bf16 v[92:95], v[132:135], v[208:211], v[92:95]
	v_mfma_f32_16x16x32_bf16 v[88:91], v[140:143], v[208:211], v[88:91]
	v_mfma_f32_16x16x32_bf16 v[76:79], v[132:135], v[216:219], v[76:79]
	v_mfma_f32_16x16x32_bf16 v[72:75], v[140:143], v[216:219], v[72:75]
	v_mfma_f32_16x16x32_bf16 v[116:119], v[144:147], v[172:175], v[116:119]
	v_mfma_f32_16x16x32_bf16 v[112:115], v[164:167], v[172:175], v[112:115]
	v_mfma_f32_16x16x32_bf16 v[100:103], v[144:147], v[192:195], v[100:103]
	v_mfma_f32_16x16x32_bf16 v[96:99], v[164:167], v[192:195], v[96:99]
	v_mfma_f32_16x16x32_bf16 v[84:87], v[144:147], v[204:207], v[84:87]
	v_mfma_f32_16x16x32_bf16 v[80:83], v[164:167], v[204:207], v[80:83]
	v_mfma_f32_16x16x32_bf16 v[68:71], v[144:147], v[212:215], v[68:71]
	v_mfma_f32_16x16x32_bf16 v[64:67], v[164:167], v[212:215], v[64:67]
	v_mfma_f32_16x16x32_bf16 v[116:119], v[148:151], v[176:179], v[116:119]
	v_mfma_f32_16x16x32_bf16 v[112:115], v[168:171], v[176:179], v[112:115]
	v_mfma_f32_16x16x32_bf16 v[100:103], v[148:151], v[196:199], v[100:103]
	v_mfma_f32_16x16x32_bf16 v[96:99], v[168:171], v[196:199], v[96:99]
	v_mfma_f32_16x16x32_bf16 v[84:87], v[148:151], v[208:211], v[84:87]
	v_mfma_f32_16x16x32_bf16 v[80:83], v[168:171], v[208:211], v[80:83]
	v_mfma_f32_16x16x32_bf16 v[68:71], v[148:151], v[216:219], v[68:71]
	v_mfma_f32_16x16x32_bf16 v[64:67], v[168:171], v[216:219], v[64:67]
	s_setprio 1
	s_barrier
	s_mov_b32 m0, s45
	v_lshl_add_u64 v[180:181], s[26:27], 0, v[154:155]
	s_add_u32 s22, s26, 0x160000
	ds_read_b128 v[172:175], v189 offset:16384
	ds_read_b128 v[176:179], v189 offset:17408
	ds_read_b128 v[192:195], v189 offset:18432
	ds_read_b128 v[196:199], v189 offset:19456
	ds_read_b128 v[204:207], v189 offset:20480
	ds_read_b128 v[208:211], v189 offset:21504
	ds_read_b128 v[212:215], v189 offset:22528
	ds_read_b128 v[216:219], v189 offset:23552
	global_load_lds_dwordx4 v[180:181], off
	v_lshl_add_u64 v[200:201], s[26:27], 0, v[158:159]
	s_mov_b32 m0, s48
	s_addc_u32 s23, s27, 0
	global_load_lds_dwordx4 v[200:201], off
	v_lshl_add_u64 v[202:203], s[22:23], 0, v[154:155]
	s_mov_b32 m0, s49
	v_lshl_add_u64 v[220:221], s[28:29], 0, v[156:157]
	global_load_lds_dwordx4 v[202:203], off
	v_lshl_add_u64 v[202:203], s[22:23], 0, v[158:159]
	s_add_i32 m0, s49, 0x2000
	s_nop 0
	global_load_lds_dwordx4 v[202:203], off
	v_lshl_add_u64 v[202:203], s[28:29], 0, v[152:153]
	s_mov_b32 m0, s36
	s_nop 0
	global_load_lds_dwordx4 v[202:203], off
	s_mov_b32 m0, s37
	s_nop 0
	global_load_lds_dwordx4 v[220:221], off
	s_waitcnt vmcnt(8)
	s_waitcnt lgkmcnt(0)
	s_barrier
; #define PG8_STAGE(bufoff, gbase, voff) do { _Pragma("unroll") for (int _i = 0; _i < 2; ++_i) \
;         __builtin_amdgcn_global_load_lds((const unsigned*)((const char*)(gbase) + (voff)[_i]), (LAS unsigned*)(lds + (bufoff) + ldsw + _i * 8192), 16, 0, 0); } while (0)
; #define PG8_LDA(dst, b, h) do { _Pragma("unroll") for (int m = 0; m < 4; ++m) _Pragma("unroll") for (int k = 0; k < 2; ++k) dst[m][k] = *(const LAS bf16x8*)(lds + PG8_SA(b, h) + aoff + m * 2048 + k * 1024); } while (0)
; #define PG8_LDB(dst, b, h) do { _Pragma("unroll") for (int n = 0; n < 2; ++n) _Pragma("unroll") for (int k = 0; k < 2; ++k) dst[n][k] = *(const LAS bf16x8*)(lds + PG8_SB(b, h) + boff + n * 2048 + k * 1024); } while (0)
; #define PG8_MMA(ai, bj, At, Bt) do { __builtin_amdgcn_s_setprio(1); _Pragma("unroll") for (int m = 0; m < 4; ++m) _Pragma("unroll") for (int n = 0; n < 2; ++n) _Pragma("unroll") for (int k = 0; k < 2; ++k) \
;         acc[ai][bj][m][n] = __builtin_amdgcn_mfma_f32_16x16x32_bf16(Bt[n][k], At[m][k], acc[ai][bj][m][n], 0, 0, 0); __builtin_amdgcn_s_setprio(0); } while (0)
; #define PG8_WAIT_V(n) asm volatile("s_waitcnt vmcnt(" #n ")" ::: "memory")
; #define PG8_WAIT_L(n) asm volatile("s_waitcnt lgkmcnt(" #n ")" ::: "memory")
; #define PG8_BAR __builtin_amdgcn_s_barrier()
; #define PG8_SCHED __builtin_amdgcn_sched_barrier(0)
; template <class Epi, class Sched, bool ALIGN_EPI = true>
; __device__ __forceinline__ void gemm_phase(LAS unsigned char* lds, const Gemm g, const Sched& S, const Epi& E) {
;     ...
;             PG8_WAIT_V(8); PG8_WAIT_L(0); PG8_BAR; PG8_MMA(1, 0, At, B0); PG8_MMA(1, 1, At, B1); PG8_BAR; PG8_SCHED;
;             PG8_LDB(B0, 1, 0); PG8_LDB(B1, 1, 1); PG8_SCHED; PG8_LDA(At, 1, 0); PG8_STAGE(PG8_SA(0, 1), a2 + hstep, voffA);
;             PG8_WAIT_V(8); PG8_WAIT_L(0); PG8_BAR; PG8_MMA(0, 0, At, B0); PG8_MMA(0, 1, At, B1); PG8_BAR; PG8_SCHED;
	s_setprio 0
	s_waitcnt lgkmcnt(0)
	v_mfma_f32_16x16x32_bf16 v[60:63], v[128:131], v[172:175], v[60:63]
	v_mfma_f32_16x16x32_bf16 v[56:59], v[136:139], v[172:175], v[56:59]
	v_mfma_f32_16x16x32_bf16 v[44:47], v[128:131], v[192:195], v[44:47]
	v_mfma_f32_16x16x32_bf16 v[40:43], v[136:139], v[192:195], v[40:43]
	v_mfma_f32_16x16x32_bf16 v[28:31], v[128:131], v[204:207], v[28:31]
	v_mfma_f32_16x16x32_bf16 v[24:27], v[136:139], v[204:207], v[24:27]
	v_mfma_f32_16x16x32_bf16 v[12:15], v[128:131], v[212:215], v[12:15]
	v_mfma_f32_16x16x32_bf16 v[8:11], v[136:139], v[212:215], v[8:11]
	v_mfma_f32_16x16x32_bf16 v[60:63], v[132:135], v[176:179], v[60:63]
	v_mfma_f32_16x16x32_bf16 v[56:59], v[140:143], v[176:179], v[56:59]
	v_mfma_f32_16x16x32_bf16 v[44:47], v[132:135], v[196:199], v[44:47]
	v_mfma_f32_16x16x32_bf16 v[40:43], v[140:143], v[196:199], v[40:43]
	v_mfma_f32_16x16x32_bf16 v[28:31], v[132:135], v[208:211], v[28:31]
	v_mfma_f32_16x16x32_bf16 v[24:27], v[140:143], v[208:211], v[24:27]
	v_mfma_f32_16x16x32_bf16 v[12:15], v[132:135], v[216:219], v[12:15]
	v_mfma_f32_16x16x32_bf16 v[8:11], v[140:143], v[216:219], v[8:11]
	v_mfma_f32_16x16x32_bf16 v[52:55], v[144:147], v[172:175], v[52:55]
	v_mfma_f32_16x16x32_bf16 v[48:51], v[164:167], v[172:175], v[48:51]
	v_mfma_f32_16x16x32_bf16 v[36:39], v[144:147], v[192:195], v[36:39]
	v_mfma_f32_16x16x32_bf16 v[32:35], v[164:167], v[192:195], v[32:35]
	v_mfma_f32_16x16x32_bf16 v[20:23], v[144:147], v[204:207], v[20:23]
	v_mfma_f32_16x16x32_bf16 v[16:19], v[164:167], v[204:207], v[16:19]
	v_mfma_f32_16x16x32_bf16 v[4:7], v[144:147], v[212:215], v[4:7]
	v_mfma_f32_16x16x32_bf16 v[0:3], v[164:167], v[212:215], v[0:3]
	v_mfma_f32_16x16x32_bf16 v[52:55], v[148:151], v[176:179], v[52:55]
	v_mfma_f32_16x16x32_bf16 v[48:51], v[168:171], v[176:179], v[48:51]
	v_mfma_f32_16x16x32_bf16 v[36:39], v[148:151], v[196:199], v[36:39]
	v_mfma_f32_16x16x32_bf16 v[32:35], v[168:171], v[196:199], v[32:35]
	v_mfma_f32_16x16x32_bf16 v[20:23], v[148:151], v[208:211], v[20:23]
	v_mfma_f32_16x16x32_bf16 v[16:19], v[168:171], v[208:211], v[16:19]
	v_mfma_f32_16x16x32_bf16 v[4:7], v[148:151], v[216:219], v[4:7]
	v_mfma_f32_16x16x32_bf16 v[0:3], v[168:171], v[216:219], v[0:3]
	s_setprio 1
	s_barrier
	s_add_i32 s46, 0, 0x18000
	s_add_i32 s47, 0, 0x1c000
	v_add_u32_e32 v140, s46, v185
	v_add_u32_e32 v168, s47, v185
	ds_read_b128 v[128:131], v140
	ds_read_b128 v[132:135], v140 offset:1024
	ds_read_b128 v[136:139], v140 offset:2048
	ds_read_b128 v[140:143], v140 offset:3072
	ds_read_b128 v[144:147], v168
	ds_read_b128 v[148:151], v168 offset:1024
	ds_read_b128 v[164:167], v168 offset:2048
	ds_read_b128 v[168:171], v168 offset:3072
	s_add_u32 s22, s28, 0x160000
	s_addc_u32 s23, s29, 0
	s_mov_b32 m0, s38
	v_lshl_add_u64 v[222:223], s[22:23], 0, v[152:153]
	ds_read_b128 v[172:175], v189 offset:32768
	ds_read_b128 v[176:179], v189 offset:33792
	ds_read_b128 v[192:195], v189 offset:34816
	ds_read_b128 v[196:199], v189 offset:35840
	ds_read_b128 v[204:207], v189 offset:36864
	ds_read_b128 v[208:211], v189 offset:37888
	ds_read_b128 v[212:215], v189 offset:38912
	ds_read_b128 v[216:219], v189 offset:39936
	global_load_lds_dwordx4 v[222:223], off
	v_lshl_add_u64 v[222:223], s[22:23], 0, v[156:157]
	s_mov_b32 m0, s39
	s_nop 0
	global_load_lds_dwordx4 v[222:223], off
	s_waitcnt vmcnt(8)
	s_waitcnt lgkmcnt(0)
	s_barrier
	s_setprio 0
	s_waitcnt lgkmcnt(0)
	v_mfma_f32_16x16x32_bf16 v[124:127], v[128:131], v[172:175], v[124:127]
	v_mfma_f32_16x16x32_bf16 v[120:123], v[136:139], v[172:175], v[120:123]
	v_mfma_f32_16x16x32_bf16 v[108:111], v[128:131], v[192:195], v[108:111]
	v_mfma_f32_16x16x32_bf16 v[104:107], v[136:139], v[192:195], v[104:107]
	v_mfma_f32_16x16x32_bf16 v[92:95], v[128:131], v[204:207], v[92:95]
	v_mfma_f32_16x16x32_bf16 v[88:91], v[136:139], v[204:207], v[88:91]
	v_mfma_f32_16x16x32_bf16 v[76:79], v[128:131], v[212:215], v[76:79]
	v_mfma_f32_16x16x32_bf16 v[72:75], v[136:139], v[212:215], v[72:75]
	v_mfma_f32_16x16x32_bf16 v[124:127], v[132:135], v[176:179], v[124:127]
	v_mfma_f32_16x16x32_bf16 v[120:123], v[140:143], v[176:179], v[120:123]
	v_mfma_f32_16x16x32_bf16 v[108:111], v[132:135], v[196:199], v[108:111]
	v_mfma_f32_16x16x32_bf16 v[104:107], v[140:143], v[196:199], v[104:107]
	v_mfma_f32_16x16x32_bf16 v[92:95], v[132:135], v[208:211], v[92:95]
	v_mfma_f32_16x16x32_bf16 v[88:91], v[140:143], v[208:211], v[88:91]
	v_mfma_f32_16x16x32_bf16 v[76:79], v[132:135], v[216:219], v[76:79]
	v_mfma_f32_16x16x32_bf16 v[72:75], v[140:143], v[216:219], v[72:75]
	v_mfma_f32_16x16x32_bf16 v[116:119], v[144:147], v[172:175], v[116:119]
	v_mfma_f32_16x16x32_bf16 v[112:115], v[164:167], v[172:175], v[112:115]
	v_mfma_f32_16x16x32_bf16 v[100:103], v[144:147], v[192:195], v[100:103]
	v_mfma_f32_16x16x32_bf16 v[96:99], v[164:167], v[192:195], v[96:99]
	v_mfma_f32_16x16x32_bf16 v[84:87], v[144:147], v[204:207], v[84:87]
	v_mfma_f32_16x16x32_bf16 v[80:83], v[164:167], v[204:207], v[80:83]
	v_mfma_f32_16x16x32_bf16 v[68:71], v[144:147], v[212:215], v[68:71]
	v_mfma_f32_16x16x32_bf16 v[64:67], v[164:167], v[212:215], v[64:67]
	v_mfma_f32_16x16x32_bf16 v[116:119], v[148:151], v[176:179], v[116:119]
	v_mfma_f32_16x16x32_bf16 v[112:115], v[168:171], v[176:179], v[112:115]
	v_mfma_f32_16x16x32_bf16 v[100:103], v[148:151], v[196:199], v[100:103]
	v_mfma_f32_16x16x32_bf16 v[96:99], v[168:171], v[196:199], v[96:99]
	v_mfma_f32_16x16x32_bf16 v[84:87], v[148:151], v[208:211], v[84:87]
	v_mfma_f32_16x16x32_bf16 v[80:83], v[168:171], v[208:211], v[80:83]
	v_mfma_f32_16x16x32_bf16 v[68:71], v[148:151], v[216:219], v[68:71]
	v_mfma_f32_16x16x32_bf16 v[64:67], v[168:171], v[216:219], v[64:67]
	s_setprio 1
	s_barrier
; #define PG8_STAGE(bufoff, gbase, voff) do { _Pragma("unroll") for (int _i = 0; _i < 2; ++_i) \
;         __builtin_amdgcn_global_load_lds((const unsigned*)((const char*)(gbase) + (voff)[_i]), (LAS unsigned*)(lds + (bufoff) + ldsw + _i * 8192), 16, 0, 0); } while (0)
; #define PG8_LDA(dst, b, h) do { _Pragma("unroll") for (int m = 0; m < 4; ++m) _Pragma("unroll") for (int k = 0; k < 2; ++k) dst[m][k] = *(const LAS bf16x8*)(lds + PG8_SA(b, h) + aoff + m * 2048 + k * 1024); } while (0)
; #define PG8_MMA(ai, bj, At, Bt) do { __builtin_amdgcn_s_setprio(1); _Pragma("unroll") for (int m = 0; m < 4; ++m) _Pragma("unroll") for (int n = 0; n < 2; ++n) _Pragma("unroll") for (int k = 0; k < 2; ++k) \
;         acc[ai][bj][m][n] = __builtin_amdgcn_mfma_f32_16x16x32_bf16(Bt[n][k], At[m][k], acc[ai][bj][m][n], 0, 0, 0); __builtin_amdgcn_s_setprio(0); } while (0)
; #define PG8_WAIT_V(n) asm volatile("s_waitcnt vmcnt(" #n ")" ::: "memory")
; #define PG8_WAIT_L(n) asm volatile("s_waitcnt lgkmcnt(" #n ")" ::: "memory")
; #define PG8_BAR __builtin_amdgcn_s_barrier()
; #define PG8_SCHED __builtin_amdgcn_sched_barrier(0)
; template <class Epi, class Sched, bool ALIGN_EPI = true>
; __device__ __forceinline__ void gemm_phase(LAS unsigned char* lds, const Gemm g, const Sched& S, const Epi& E) {
;     ...
;             PG8_LDA(At, 1, 1); PG8_STAGE(PG8_SB(1, 0), b3, voffB); PG8_STAGE(PG8_SB(1, 1), b3 + hstep, voffB); PG8_STAGE(PG8_SA(1, 0), a3, voffA);
;             PG8_WAIT_V(8); PG8_WAIT_L(0); PG8_BAR; PG8_MMA(1, 0, At, B0); PG8_MMA(1, 1, At, B1); PG8_BAR; PG8_SCHED;
;         }
;         if constexpr (ALIGN_EPI) { if (wr == 0) PG8_BAR; }
	s_add_i32 s22, s46, s35
	v_lshl_add_u64 v[180:181], v[180:181], 0, s[14:15]
	s_mov_b32 m0, s22
	ds_read_b128 v[172:175], v189 offset:49152
	ds_read_b128 v[176:179], v189 offset:50176
	ds_read_b128 v[192:195], v189 offset:51200
	ds_read_b128 v[196:199], v189 offset:52224
	ds_read_b128 v[204:207], v189 offset:53248
	ds_read_b128 v[208:211], v189 offset:54272
	ds_read_b128 v[212:215], v189 offset:55296
	ds_read_b128 v[216:219], v189 offset:56320
	global_load_lds_dwordx4 v[180:181], off
	s_add_i32 m0, s22, 0x2000
	s_add_u32 s22, s26, 0x160080
	v_lshl_add_u64 v[180:181], v[200:201], 0, s[14:15]
	s_addc_u32 s23, s27, 0
	s_add_i32 s26, s47, s35
	global_load_lds_dwordx4 v[180:181], off
	v_lshl_add_u64 v[180:181], s[22:23], 0, v[154:155]
	s_mov_b32 m0, s26
	s_nop 0
	global_load_lds_dwordx4 v[180:181], off
	v_lshl_add_u64 v[180:181], s[22:23], 0, v[158:159]
	s_add_i32 m0, s26, 0x2000
	s_nop 0
	global_load_lds_dwordx4 v[180:181], off
	v_lshl_add_u64 v[180:181], v[202:203], 0, s[14:15]
	s_mov_b32 m0, s40
	s_nop 0
	global_load_lds_dwordx4 v[180:181], off
	v_lshl_add_u64 v[180:181], v[220:221], 0, s[14:15]
	s_mov_b32 m0, s41
	s_nop 0
	global_load_lds_dwordx4 v[180:181], off
	s_waitcnt vmcnt(8)
	s_waitcnt lgkmcnt(0)
	s_barrier
	s_setprio 0
	s_waitcnt lgkmcnt(0)
	v_mfma_f32_16x16x32_bf16 v[60:63], v[128:131], v[172:175], v[60:63]
	v_mfma_f32_16x16x32_bf16 v[56:59], v[136:139], v[172:175], v[56:59]
	v_mfma_f32_16x16x32_bf16 v[44:47], v[128:131], v[192:195], v[44:47]
	v_mfma_f32_16x16x32_bf16 v[40:43], v[136:139], v[192:195], v[40:43]
	v_mfma_f32_16x16x32_bf16 v[28:31], v[128:131], v[204:207], v[28:31]
	v_mfma_f32_16x16x32_bf16 v[24:27], v[136:139], v[204:207], v[24:27]
	v_mfma_f32_16x16x32_bf16 v[12:15], v[128:131], v[212:215], v[12:15]
	v_mfma_f32_16x16x32_bf16 v[8:11], v[136:139], v[212:215], v[8:11]
	v_mfma_f32_16x16x32_bf16 v[60:63], v[132:135], v[176:179], v[60:63]
	v_mfma_f32_16x16x32_bf16 v[56:59], v[140:143], v[176:179], v[56:59]
	v_mfma_f32_16x16x32_bf16 v[44:47], v[132:135], v[196:199], v[44:47]
	v_mfma_f32_16x16x32_bf16 v[40:43], v[140:143], v[196:199], v[40:43]
	v_mfma_f32_16x16x32_bf16 v[28:31], v[132:135], v[208:211], v[28:31]
	v_mfma_f32_16x16x32_bf16 v[24:27], v[140:143], v[208:211], v[24:27]
	v_mfma_f32_16x16x32_bf16 v[12:15], v[132:135], v[216:219], v[12:15]
	v_mfma_f32_16x16x32_bf16 v[8:11], v[140:143], v[216:219], v[8:11]
	v_mfma_f32_16x16x32_bf16 v[52:55], v[144:147], v[172:175], v[52:55]
	v_mfma_f32_16x16x32_bf16 v[48:51], v[164:167], v[172:175], v[48:51]
	v_mfma_f32_16x16x32_bf16 v[36:39], v[144:147], v[192:195], v[36:39]
	v_mfma_f32_16x16x32_bf16 v[32:35], v[164:167], v[192:195], v[32:35]
	v_mfma_f32_16x16x32_bf16 v[20:23], v[144:147], v[204:207], v[20:23]
	v_mfma_f32_16x16x32_bf16 v[16:19], v[164:167], v[204:207], v[16:19]
	v_mfma_f32_16x16x32_bf16 v[4:7], v[144:147], v[212:215], v[4:7]
	v_mfma_f32_16x16x32_bf16 v[0:3], v[164:167], v[212:215], v[0:3]
	v_mfma_f32_16x16x32_bf16 v[52:55], v[148:151], v[176:179], v[52:55]
	v_mfma_f32_16x16x32_bf16 v[48:51], v[168:171], v[176:179], v[48:51]
	v_mfma_f32_16x16x32_bf16 v[36:39], v[148:151], v[196:199], v[36:39]
	v_mfma_f32_16x16x32_bf16 v[32:35], v[168:171], v[196:199], v[32:35]
	v_mfma_f32_16x16x32_bf16 v[20:23], v[148:151], v[208:211], v[20:23]
	v_mfma_f32_16x16x32_bf16 v[16:19], v[168:171], v[208:211], v[16:19]
	v_mfma_f32_16x16x32_bf16 v[4:7], v[148:151], v[216:219], v[4:7]
	v_mfma_f32_16x16x32_bf16 v[0:3], v[168:171], v[216:219], v[0:3]
	s_setprio 1
	s_barrier
	s_add_i32 s56, s56, 2
	s_add_u32 s54, s54, 0x100
	s_addc_u32 s55, s55, 0
	s_cmpk_gt_u32 s56, 0x55
	s_mov_b64 s[22:23], s[24:25]
	s_cbranch_scc0 .LBB0_746
	s_and_b64 vcc, exec, s[16:17]
	s_cbranch_vccz .LBB0_749
	s_barrier

; #define PG8_STAGE(bufoff, gbase, voff) do { _Pragma("unroll") for (int _i = 0; _i < 2; ++_i) \
;         __builtin_amdgcn_global_load_lds((const unsigned*)((const char*)(gbase) + (voff)[_i]), (LAS unsigned*)(lds + (bufoff) + ldsw + _i * 8192), 16, 0, 0); } while (0)
; #define PG8_LDA(dst, b, h) do { _Pragma("unroll") for (int m = 0; m < 4; ++m) _Pragma("unroll") for (int k = 0; k < 2; ++k) dst[m][k] = *(const LAS bf16x8*)(lds + PG8_SA(b, h) + aoff + m * 2048 + k * 1024); } while (0)
; #define PG8_LDB(dst, b, h) do { _Pragma("unroll") for (int n = 0; n < 2; ++n) _Pragma("unroll") for (int k = 0; k < 2; ++k) dst[n][k] = *(const LAS bf16x8*)(lds + PG8_SB(b, h) + boff + n * 2048 + k * 1024); } while (0)
; #define PG8_MMA(ai, bj, At, Bt) do { __builtin_amdgcn_s_setprio(1); _Pragma("unroll") for (int m = 0; m < 4; ++m) _Pragma("unroll") for (int n = 0; n < 2; ++n) _Pragma("unroll") for (int k = 0; k < 2; ++k) \
;         acc[ai][bj][m][n] = __builtin_amdgcn_mfma_f32_16x16x32_bf16(Bt[n][k], At[m][k], acc[ai][bj][m][n], 0, 0, 0); __builtin_amdgcn_s_setprio(0); } while (0)
; #define PG8_WAIT_V(n) asm volatile("s_waitcnt vmcnt(" #n ")" ::: "memory")
; #define PG8_WAIT_L(n) asm volatile("s_waitcnt lgkmcnt(" #n ")" ::: "memory")
; #define PG8_BAR __builtin_amdgcn_s_barrier()
; #define PG8_SCHED __builtin_amdgcn_sched_barrier(0)
; template <class Epi, class Sched, bool ALIGN_EPI = true>
; __device__ __forceinline__ void gemm_phase(LAS unsigned char* lds, const Gemm g, const Sched& S, const Epi& E) {
;     ...
;         for (int t = 0; t < nt; t += 2) {
;             const bool last = (t == nt - 2);
;             const char* a1 = cA + (size_t)(t + 1) * kstep;
;             const char* a2 = last ? nA : cA + (size_t)(t + 2) * kstep; const char* b2 = last ? nB : cB + (size_t)(t + 2) * kstep;
;             const char* a3 = a2 + kstep; const char* b3 = b2 + kstep;
;             PG8_LDB(B0, 0, 0); PG8_LDB(B1, 0, 1); PG8_SCHED; PG8_LDA(At, 0, 0); PG8_STAGE(PG8_SA(1, 1), a1 + hstep, voffA);
;             PG8_WAIT_V(8); PG8_WAIT_L(0); PG8_BAR; PG8_MMA(0, 0, At, B0); PG8_MMA(0, 1, At, B1); PG8_BAR; PG8_SCHED;
;             PG8_LDA(At, 0, 1); PG8_STAGE(PG8_SB(0, 0), b2, voffB); PG8_STAGE(PG8_SB(0, 1), b2 + hstep, voffB); PG8_STAGE(PG8_SA(0, 0), a2, voffA);
;             PG8_WAIT_V(8); PG8_WAIT_L(0); PG8_BAR; PG8_MMA(1, 0, At, B0); PG8_MMA(1, 1, At, B1); PG8_BAR; PG8_SCHED;
.LBB0_837:
	ds_read_b128 v[120:123], v208
	ds_read_b128 v[124:127], v208 offset:1024
	ds_read_b128 v[132:135], v208 offset:2048
	ds_read_b128 v[136:139], v208 offset:3072
	ds_read_b128 v[144:147], v209
	ds_read_b128 v[148:151], v209 offset:1024
	ds_read_b128 v[152:155], v209 offset:2048
	ds_read_b128 v[156:159], v209 offset:3072
	s_add_u32 s36, s34, 0xfff80080
	s_addc_u32 s37, s35, -1
	s_cmp_eq_u32 s60, 28
	s_cselect_b32 s39, s55, s37
	s_cselect_b32 s38, s56, s36
	s_cselect_b32 s37, s11, s59
	s_cselect_b32 s36, s57, s58
	v_lshl_add_u64 v[200:201], s[34:35], 0, v[184:185]
	s_add_i32 m0, s42, 0xc000
	ds_read_b128 v[160:163], v210
	ds_read_b128 v[164:167], v210 offset:1024
	ds_read_b128 v[168:171], v210 offset:2048
	ds_read_b128 v[172:175], v210 offset:3072
	ds_read_b128 v[188:191], v210 offset:4096
	ds_read_b128 v[192:195], v210 offset:5120
	ds_read_b128 v[196:199], v210 offset:6144
	ds_read_b128 v[214:217], v210 offset:7168
	global_load_lds_dwordx4 v[200:201], off
	v_lshl_add_u64 v[200:201], s[34:35], 0, v[186:187]
	s_add_i32 m0, s42, 0xe000
	s_nop 0
	global_load_lds_dwordx4 v[200:201], off
	s_waitcnt vmcnt(8)
	s_waitcnt lgkmcnt(0)
	s_barrier
	s_setprio 0
	s_waitcnt lgkmcnt(0)
	v_mfma_f32_16x16x32_bf16 v[140:143], v[120:123], v[160:163], v[140:143]
	v_mfma_f32_16x16x32_bf16 v[128:131], v[132:135], v[160:163], v[128:131]
	v_mfma_f32_16x16x32_bf16 v[108:111], v[120:123], v[168:171], v[108:111]
	v_mfma_f32_16x16x32_bf16 v[104:107], v[132:135], v[168:171], v[104:107]
	v_mfma_f32_16x16x32_bf16 v[92:95], v[120:123], v[188:191], v[92:95]
	v_mfma_f32_16x16x32_bf16 v[88:91], v[132:135], v[188:191], v[88:91]
	v_mfma_f32_16x16x32_bf16 v[76:79], v[120:123], v[196:199], v[76:79]
	v_mfma_f32_16x16x32_bf16 v[72:75], v[132:135], v[196:199], v[72:75]
	v_mfma_f32_16x16x32_bf16 v[140:143], v[124:127], v[164:167], v[140:143]
	v_mfma_f32_16x16x32_bf16 v[128:131], v[136:139], v[164:167], v[128:131]
	v_mfma_f32_16x16x32_bf16 v[108:111], v[124:127], v[172:175], v[108:111]
	v_mfma_f32_16x16x32_bf16 v[104:107], v[136:139], v[172:175], v[104:107]
	v_mfma_f32_16x16x32_bf16 v[92:95], v[124:127], v[192:195], v[92:95]
	v_mfma_f32_16x16x32_bf16 v[88:91], v[136:139], v[192:195], v[88:91]
	v_mfma_f32_16x16x32_bf16 v[76:79], v[124:127], v[214:217], v[76:79]
	v_mfma_f32_16x16x32_bf16 v[72:75], v[136:139], v[214:217], v[72:75]
	v_mfma_f32_16x16x32_bf16 v[116:119], v[144:147], v[160:163], v[116:119]
	v_mfma_f32_16x16x32_bf16 v[112:115], v[152:155], v[160:163], v[112:115]
	v_mfma_f32_16x16x32_bf16 v[100:103], v[144:147], v[168:171], v[100:103]
	v_mfma_f32_16x16x32_bf16 v[96:99], v[152:155], v[168:171], v[96:99]
	v_mfma_f32_16x16x32_bf16 v[84:87], v[144:147], v[188:191], v[84:87]
	v_mfma_f32_16x16x32_bf16 v[80:83], v[152:155], v[188:191], v[80:83]
	v_mfma_f32_16x16x32_bf16 v[68:71], v[144:147], v[196:199], v[68:71]
	v_mfma_f32_16x16x32_bf16 v[64:67], v[152:155], v[196:199], v[64:67]
	v_mfma_f32_16x16x32_bf16 v[116:119], v[148:151], v[164:167], v[116:119]
	v_mfma_f32_16x16x32_bf16 v[112:115], v[156:159], v[164:167], v[112:115]
	v_mfma_f32_16x16x32_bf16 v[100:103], v[148:151], v[172:175], v[100:103]
	v_mfma_f32_16x16x32_bf16 v[96:99], v[156:159], v[172:175], v[96:99]
	v_mfma_f32_16x16x32_bf16 v[84:87], v[148:151], v[192:195], v[84:87]
	v_mfma_f32_16x16x32_bf16 v[80:83], v[156:159], v[192:195], v[80:83]
	v_mfma_f32_16x16x32_bf16 v[68:71], v[148:151], v[214:217], v[68:71]
	v_mfma_f32_16x16x32_bf16 v[64:67], v[156:159], v[214:217], v[64:67]
	s_setprio 1
	s_barrier
	s_add_i32 s46, s50, s41
	v_lshl_add_u64 v[200:201], s[36:37], 0, v[178:179]
	s_mov_b32 m0, s46
	ds_read_b128 v[160:163], v210 offset:16384
	ds_read_b128 v[164:167], v210 offset:17408
	ds_read_b128 v[168:171], v210 offset:18432
	ds_read_b128 v[172:175], v210 offset:19456
	ds_read_b128 v[188:191], v210 offset:20480
	ds_read_b128 v[192:195], v210 offset:21504
	ds_read_b128 v[196:199], v210 offset:22528
	ds_read_b128 v[214:217], v210 offset:23552
	global_load_lds_dwordx4 v[200:201], off
	s_add_i32 m0, s46, 0x2000
	s_add_u32 s46, s36, 0x80000
	v_lshl_add_u64 v[218:219], s[36:37], 0, v[182:183]
	s_addc_u32 s47, s37, 0
	s_add_i32 s61, s51, s41
	global_load_lds_dwordx4 v[218:219], off
	v_lshl_add_u64 v[220:221], s[46:47], 0, v[178:179]
	s_mov_b32 m0, s61
	v_lshl_add_u64 v[222:223], s[38:39], 0, v[180:181]
	global_load_lds_dwordx4 v[220:221], off
	v_lshl_add_u64 v[220:221], s[46:47], 0, v[182:183]
	s_add_i32 m0, s61, 0x2000
	s_nop 0
	global_load_lds_dwordx4 v[220:221], off
	v_lshl_add_u64 v[220:221], s[38:39], 0, v[176:177]
	s_mov_b32 m0, s42
	s_nop 0
	global_load_lds_dwordx4 v[220:221], off
	s_mov_b32 m0, s43
	s_nop 0
	global_load_lds_dwordx4 v[222:223], off
	s_waitcnt vmcnt(8)
	s_waitcnt lgkmcnt(0)
	s_barrier
; #define PG8_STAGE(bufoff, gbase, voff) do { _Pragma("unroll") for (int _i = 0; _i < 2; ++_i) \
;         __builtin_amdgcn_global_load_lds((const unsigned*)((const char*)(gbase) + (voff)[_i]), (LAS unsigned*)(lds + (bufoff) + ldsw + _i * 8192), 16, 0, 0); } while (0)
; #define PG8_LDA(dst, b, h) do { _Pragma("unroll") for (int m = 0; m < 4; ++m) _Pragma("unroll") for (int k = 0; k < 2; ++k) dst[m][k] = *(const LAS bf16x8*)(lds + PG8_SA(b, h) + aoff + m * 2048 + k * 1024); } while (0)
; #define PG8_LDB(dst, b, h) do { _Pragma("unroll") for (int n = 0; n < 2; ++n) _Pragma("unroll") for (int k = 0; k < 2; ++k) dst[n][k] = *(const LAS bf16x8*)(lds + PG8_SB(b, h) + boff + n * 2048 + k * 1024); } while (0)
; #define PG8_MMA(ai, bj, At, Bt) do { __builtin_amdgcn_s_setprio(1); _Pragma("unroll") for (int m = 0; m < 4; ++m) _Pragma("unroll") for (int n = 0; n < 2; ++n) _Pragma("unroll") for (int k = 0; k < 2; ++k) \
;         acc[ai][bj][m][n] = __builtin_amdgcn_mfma_f32_16x16x32_bf16(Bt[n][k], At[m][k], acc[ai][bj][m][n], 0, 0, 0); __builtin_amdgcn_s_setprio(0); } while (0)
; #define PG8_WAIT_V(n) asm volatile("s_waitcnt vmcnt(" #n ")" ::: "memory")
; #define PG8_WAIT_L(n) asm volatile("s_waitcnt lgkmcnt(" #n ")" ::: "memory")
; #define PG8_BAR __builtin_amdgcn_s_barrier()
; #define PG8_SCHED __builtin_amdgcn_sched_barrier(0)
; template <class Epi, class Sched, bool ALIGN_EPI = true>
; __device__ __forceinline__ void gemm_phase(LAS unsigned char* lds, const Gemm g, const Sched& S, const Epi& E) {
;     ...
;             PG8_WAIT_V(8); PG8_WAIT_L(0); PG8_BAR; PG8_MMA(1, 0, At, B0); PG8_MMA(1, 1, At, B1); PG8_BAR; PG8_SCHED;
;             PG8_LDB(B0, 1, 0); PG8_LDB(B1, 1, 1); PG8_SCHED; PG8_LDA(At, 1, 0); PG8_STAGE(PG8_SA(0, 1), a2 + hstep, voffA);
;             PG8_WAIT_V(8); PG8_WAIT_L(0); PG8_BAR; PG8_MMA(0, 0, At, B0); PG8_MMA(0, 1, At, B1); PG8_BAR; PG8_SCHED;
	s_setprio 0
	s_waitcnt lgkmcnt(0)
	v_mfma_f32_16x16x32_bf16 v[60:63], v[120:123], v[160:163], v[60:63]
	v_mfma_f32_16x16x32_bf16 v[56:59], v[132:135], v[160:163], v[56:59]
	v_mfma_f32_16x16x32_bf16 v[44:47], v[120:123], v[168:171], v[44:47]
	v_mfma_f32_16x16x32_bf16 v[40:43], v[132:135], v[168:171], v[40:43]
	v_mfma_f32_16x16x32_bf16 v[28:31], v[120:123], v[188:191], v[28:31]
	v_mfma_f32_16x16x32_bf16 v[24:27], v[132:135], v[188:191], v[24:27]
	v_mfma_f32_16x16x32_bf16 v[12:15], v[120:123], v[196:199], v[12:15]
	v_mfma_f32_16x16x32_bf16 v[8:11], v[132:135], v[196:199], v[8:11]
	v_mfma_f32_16x16x32_bf16 v[60:63], v[124:127], v[164:167], v[60:63]
	v_mfma_f32_16x16x32_bf16 v[56:59], v[136:139], v[164:167], v[56:59]
	v_mfma_f32_16x16x32_bf16 v[44:47], v[124:127], v[172:175], v[44:47]
	v_mfma_f32_16x16x32_bf16 v[40:43], v[136:139], v[172:175], v[40:43]
	v_mfma_f32_16x16x32_bf16 v[28:31], v[124:127], v[192:195], v[28:31]
	v_mfma_f32_16x16x32_bf16 v[24:27], v[136:139], v[192:195], v[24:27]
	v_mfma_f32_16x16x32_bf16 v[12:15], v[124:127], v[214:217], v[12:15]
	v_mfma_f32_16x16x32_bf16 v[8:11], v[136:139], v[214:217], v[8:11]
	v_mfma_f32_16x16x32_bf16 v[52:55], v[144:147], v[160:163], v[52:55]
	v_mfma_f32_16x16x32_bf16 v[48:51], v[152:155], v[160:163], v[48:51]
	v_mfma_f32_16x16x32_bf16 v[36:39], v[144:147], v[168:171], v[36:39]
	v_mfma_f32_16x16x32_bf16 v[32:35], v[152:155], v[168:171], v[32:35]
	v_mfma_f32_16x16x32_bf16 v[20:23], v[144:147], v[188:191], v[20:23]
	v_mfma_f32_16x16x32_bf16 v[16:19], v[152:155], v[188:191], v[16:19]
	v_mfma_f32_16x16x32_bf16 v[4:7], v[144:147], v[196:199], v[4:7]
	v_mfma_f32_16x16x32_bf16 v[0:3], v[152:155], v[196:199], v[0:3]
	v_mfma_f32_16x16x32_bf16 v[52:55], v[148:151], v[164:167], v[52:55]
	v_mfma_f32_16x16x32_bf16 v[48:51], v[156:159], v[164:167], v[48:51]
	v_mfma_f32_16x16x32_bf16 v[36:39], v[148:151], v[172:175], v[36:39]
	v_mfma_f32_16x16x32_bf16 v[32:35], v[156:159], v[172:175], v[32:35]
	v_mfma_f32_16x16x32_bf16 v[20:23], v[148:151], v[192:195], v[20:23]
	v_mfma_f32_16x16x32_bf16 v[16:19], v[156:159], v[192:195], v[16:19]
	v_mfma_f32_16x16x32_bf16 v[4:7], v[148:151], v[214:217], v[4:7]
	v_mfma_f32_16x16x32_bf16 v[0:3], v[156:159], v[214:217], v[0:3]
	s_setprio 1
	s_barrier
	s_add_i32 s46, 0, 0x18000
	s_add_i32 s47, 0, 0x1c000
	v_add_u32_e32 v136, s46, v206
	v_add_u32_e32 v156, s47, v206
	ds_read_b128 v[120:123], v136
	ds_read_b128 v[124:127], v136 offset:1024
	ds_read_b128 v[132:135], v136 offset:2048
	ds_read_b128 v[136:139], v136 offset:3072
	ds_read_b128 v[144:147], v156
	ds_read_b128 v[148:151], v156 offset:1024
	ds_read_b128 v[152:155], v156 offset:2048
	ds_read_b128 v[156:159], v156 offset:3072
	s_add_u32 s38, s38, 0x80000
	s_addc_u32 s39, s39, 0
	s_mov_b32 m0, s44
	v_lshl_add_u64 v[224:225], s[38:39], 0, v[176:177]
	ds_read_b128 v[160:163], v210 offset:32768
	ds_read_b128 v[164:167], v210 offset:33792
	ds_read_b128 v[168:171], v210 offset:34816
	ds_read_b128 v[172:175], v210 offset:35840
	ds_read_b128 v[188:191], v210 offset:36864
	ds_read_b128 v[192:195], v210 offset:37888
	ds_read_b128 v[196:199], v210 offset:38912
	ds_read_b128 v[214:217], v210 offset:39936
	global_load_lds_dwordx4 v[224:225], off
	v_lshl_add_u64 v[224:225], s[38:39], 0, v[180:181]
	s_mov_b32 m0, s45
	s_nop 0
	global_load_lds_dwordx4 v[224:225], off
	s_waitcnt vmcnt(8)
	s_waitcnt lgkmcnt(0)
	s_barrier
	s_setprio 0
	s_waitcnt lgkmcnt(0)
	v_mfma_f32_16x16x32_bf16 v[140:143], v[120:123], v[160:163], v[140:143]
	v_mfma_f32_16x16x32_bf16 v[128:131], v[132:135], v[160:163], v[128:131]
	v_mfma_f32_16x16x32_bf16 v[108:111], v[120:123], v[168:171], v[108:111]
	v_mfma_f32_16x16x32_bf16 v[104:107], v[132:135], v[168:171], v[104:107]
	v_mfma_f32_16x16x32_bf16 v[92:95], v[120:123], v[188:191], v[92:95]
	v_mfma_f32_16x16x32_bf16 v[88:91], v[132:135], v[188:191], v[88:91]
	v_mfma_f32_16x16x32_bf16 v[76:79], v[120:123], v[196:199], v[76:79]
	v_mfma_f32_16x16x32_bf16 v[72:75], v[132:135], v[196:199], v[72:75]
	v_mfma_f32_16x16x32_bf16 v[140:143], v[124:127], v[164:167], v[140:143]
	v_mfma_f32_16x16x32_bf16 v[128:131], v[136:139], v[164:167], v[128:131]
	v_mfma_f32_16x16x32_bf16 v[108:111], v[124:127], v[172:175], v[108:111]
	v_mfma_f32_16x16x32_bf16 v[104:107], v[136:139], v[172:175], v[104:107]
	v_mfma_f32_16x16x32_bf16 v[92:95], v[124:127], v[192:195], v[92:95]
	v_mfma_f32_16x16x32_bf16 v[88:91], v[136:139], v[192:195], v[88:91]
	v_mfma_f32_16x16x32_bf16 v[76:79], v[124:127], v[214:217], v[76:79]
	v_mfma_f32_16x16x32_bf16 v[72:75], v[136:139], v[214:217], v[72:75]
	v_mfma_f32_16x16x32_bf16 v[116:119], v[144:147], v[160:163], v[116:119]
	v_mfma_f32_16x16x32_bf16 v[112:115], v[152:155], v[160:163], v[112:115]
	v_mfma_f32_16x16x32_bf16 v[100:103], v[144:147], v[168:171], v[100:103]
	v_mfma_f32_16x16x32_bf16 v[96:99], v[152:155], v[168:171], v[96:99]
	v_mfma_f32_16x16x32_bf16 v[84:87], v[144:147], v[188:191], v[84:87]
	v_mfma_f32_16x16x32_bf16 v[80:83], v[152:155], v[188:191], v[80:83]
	v_mfma_f32_16x16x32_bf16 v[68:71], v[144:147], v[196:199], v[68:71]
	v_mfma_f32_16x16x32_bf16 v[64:67], v[152:155], v[196:199], v[64:67]
	v_mfma_f32_16x16x32_bf16 v[116:119], v[148:151], v[164:167], v[116:119]
	v_mfma_f32_16x16x32_bf16 v[112:115], v[156:159], v[164:167], v[112:115]
	v_mfma_f32_16x16x32_bf16 v[100:103], v[148:151], v[172:175], v[100:103]
	v_mfma_f32_16x16x32_bf16 v[96:99], v[156:159], v[172:175], v[96:99]
	v_mfma_f32_16x16x32_bf16 v[84:87], v[148:151], v[192:195], v[84:87]
	v_mfma_f32_16x16x32_bf16 v[80:83], v[156:159], v[192:195], v[80:83]
	v_mfma_f32_16x16x32_bf16 v[68:71], v[148:151], v[214:217], v[68:71]
	v_mfma_f32_16x16x32_bf16 v[64:67], v[156:159], v[214:217], v[64:67]
	s_setprio 1
	s_barrier
; #define PG8_STAGE(bufoff, gbase, voff) do { _Pragma("unroll") for (int _i = 0; _i < 2; ++_i) \
;         __builtin_amdgcn_global_load_lds((const unsigned*)((const char*)(gbase) + (voff)[_i]), (LAS unsigned*)(lds + (bufoff) + ldsw + _i * 8192), 16, 0, 0); } while (0)
; #define PG8_LDA(dst, b, h) do { _Pragma("unroll") for (int m = 0; m < 4; ++m) _Pragma("unroll") for (int k = 0; k < 2; ++k) dst[m][k] = *(const LAS bf16x8*)(lds + PG8_SA(b, h) + aoff + m * 2048 + k * 1024); } while (0)
; #define PG8_MMA(ai, bj, At, Bt) do { __builtin_amdgcn_s_setprio(1); _Pragma("unroll") for (int m = 0; m < 4; ++m) _Pragma("unroll") for (int n = 0; n < 2; ++n) _Pragma("unroll") for (int k = 0; k < 2; ++k) \
;         acc[ai][bj][m][n] = __builtin_amdgcn_mfma_f32_16x16x32_bf16(Bt[n][k], At[m][k], acc[ai][bj][m][n], 0, 0, 0); __builtin_amdgcn_s_setprio(0); } while (0)
; #define PG8_WAIT_V(n) asm volatile("s_waitcnt vmcnt(" #n ")" ::: "memory")
; #define PG8_WAIT_L(n) asm volatile("s_waitcnt lgkmcnt(" #n ")" ::: "memory")
; #define PG8_BAR __builtin_amdgcn_s_barrier()
; #define PG8_SCHED __builtin_amdgcn_sched_barrier(0)
; template <class Epi, class Sched, bool ALIGN_EPI = true>
; __device__ __forceinline__ void gemm_phase(LAS unsigned char* lds, const Gemm g, const Sched& S, const Epi& E) {
;     ...
;             PG8_LDA(At, 1, 1); PG8_STAGE(PG8_SB(1, 0), b3, voffB); PG8_STAGE(PG8_SB(1, 1), b3 + hstep, voffB); PG8_STAGE(PG8_SA(1, 0), a3, voffA);
;             PG8_WAIT_V(8); PG8_WAIT_L(0); PG8_BAR; PG8_MMA(1, 0, At, B0); PG8_MMA(1, 1, At, B1); PG8_BAR; PG8_SCHED;
;         }
	s_add_i32 s38, s46, s41
	v_lshl_add_u64 v[200:201], v[200:201], 0, s[26:27]
	s_mov_b32 m0, s38
	ds_read_b128 v[160:163], v210 offset:49152
	ds_read_b128 v[164:167], v210 offset:50176
	ds_read_b128 v[168:171], v210 offset:51200
	ds_read_b128 v[172:175], v210 offset:52224
	ds_read_b128 v[188:191], v210 offset:53248
	ds_read_b128 v[192:195], v210 offset:54272
	ds_read_b128 v[196:199], v210 offset:55296
	ds_read_b128 v[214:217], v210 offset:56320
	global_load_lds_dwordx4 v[200:201], off
	s_add_i32 m0, s38, 0x2000
	s_add_u32 s36, s36, 0x80080
	v_lshl_add_u64 v[200:201], v[218:219], 0, s[26:27]
	s_addc_u32 s37, s37, 0
	s_add_i32 s38, s47, s41
	global_load_lds_dwordx4 v[200:201], off
	v_lshl_add_u64 v[200:201], s[36:37], 0, v[178:179]
	s_mov_b32 m0, s38
	s_nop 0
	global_load_lds_dwordx4 v[200:201], off
	v_lshl_add_u64 v[200:201], s[36:37], 0, v[182:183]
	s_add_i32 m0, s38, 0x2000
	s_nop 0
	global_load_lds_dwordx4 v[200:201], off
	v_lshl_add_u64 v[200:201], v[220:221], 0, s[26:27]
	s_mov_b32 m0, s48
	s_nop 0
	global_load_lds_dwordx4 v[200:201], off
	v_lshl_add_u64 v[200:201], v[222:223], 0, s[26:27]
	s_mov_b32 m0, s49
	s_nop 0
	global_load_lds_dwordx4 v[200:201], off
	s_waitcnt vmcnt(8)
	s_waitcnt lgkmcnt(0)
	s_barrier
	s_setprio 0
	s_waitcnt lgkmcnt(0)
	v_mfma_f32_16x16x32_bf16 v[60:63], v[120:123], v[160:163], v[60:63]
	v_mfma_f32_16x16x32_bf16 v[56:59], v[132:135], v[160:163], v[56:59]
	v_mfma_f32_16x16x32_bf16 v[44:47], v[120:123], v[168:171], v[44:47]
	v_mfma_f32_16x16x32_bf16 v[40:43], v[132:135], v[168:171], v[40:43]
	v_mfma_f32_16x16x32_bf16 v[28:31], v[120:123], v[188:191], v[28:31]
	v_mfma_f32_16x16x32_bf16 v[24:27], v[132:135], v[188:191], v[24:27]
	v_mfma_f32_16x16x32_bf16 v[12:15], v[120:123], v[196:199], v[12:15]
	v_mfma_f32_16x16x32_bf16 v[8:11], v[132:135], v[196:199], v[8:11]
	v_mfma_f32_16x16x32_bf16 v[60:63], v[124:127], v[164:167], v[60:63]
	v_mfma_f32_16x16x32_bf16 v[56:59], v[136:139], v[164:167], v[56:59]
	v_mfma_f32_16x16x32_bf16 v[44:47], v[124:127], v[172:175], v[44:47]
	v_mfma_f32_16x16x32_bf16 v[40:43], v[136:139], v[172:175], v[40:43]
	v_mfma_f32_16x16x32_bf16 v[28:31], v[124:127], v[192:195], v[28:31]
	v_mfma_f32_16x16x32_bf16 v[24:27], v[136:139], v[192:195], v[24:27]
	v_mfma_f32_16x16x32_bf16 v[12:15], v[124:127], v[214:217], v[12:15]
	v_mfma_f32_16x16x32_bf16 v[8:11], v[136:139], v[214:217], v[8:11]
	v_mfma_f32_16x16x32_bf16 v[52:55], v[144:147], v[160:163], v[52:55]
	v_mfma_f32_16x16x32_bf16 v[48:51], v[152:155], v[160:163], v[48:51]
	v_mfma_f32_16x16x32_bf16 v[36:39], v[144:147], v[168:171], v[36:39]
	v_mfma_f32_16x16x32_bf16 v[32:35], v[152:155], v[168:171], v[32:35]
	v_mfma_f32_16x16x32_bf16 v[20:23], v[144:147], v[188:191], v[20:23]
	v_mfma_f32_16x16x32_bf16 v[16:19], v[152:155], v[188:191], v[16:19]
	v_mfma_f32_16x16x32_bf16 v[4:7], v[144:147], v[196:199], v[4:7]
	v_mfma_f32_16x16x32_bf16 v[0:3], v[152:155], v[196:199], v[0:3]
	v_mfma_f32_16x16x32_bf16 v[52:55], v[148:151], v[164:167], v[52:55]
	v_mfma_f32_16x16x32_bf16 v[48:51], v[156:159], v[164:167], v[48:51]
	v_mfma_f32_16x16x32_bf16 v[36:39], v[148:151], v[172:175], v[36:39]
	v_mfma_f32_16x16x32_bf16 v[32:35], v[156:159], v[172:175], v[32:35]
	v_mfma_f32_16x16x32_bf16 v[20:23], v[148:151], v[192:195], v[20:23]
	v_mfma_f32_16x16x32_bf16 v[16:19], v[156:159], v[192:195], v[16:19]
	v_mfma_f32_16x16x32_bf16 v[4:7], v[148:151], v[214:217], v[4:7]
	v_mfma_f32_16x16x32_bf16 v[0:3], v[156:159], v[214:217], v[0:3]
	s_setprio 1
	s_barrier
	s_add_i32 s60, s60, 2
	s_add_u32 s34, s34, 0x100
	s_addc_u32 s35, s35, 0
	s_add_u32 s58, s58, 0x100
	s_addc_u32 s59, s59, 0
	s_cmp_gt_u32 s60, 29
	s_cbranch_scc0 .LBB0_837
	s_and_b64 vcc, exec, s[28:29]
	s_cbranch_vccz .LBB0_840
	s_barrier
